# dead spill reloads removed (275 v_readlane from the spill VGPR whose SGPR is overwritten before use; 12 of 16-18 in every GEMM unit header), on v21
# speedup vs baseline: 1.0096x; 1.0007x over previous
.LBB0_21:
	s_lshr_b32 s55, s48, 6
	s_lshl_b32 s0, s74, 3
	s_add_i32 s84, s55, s0
	s_lshl_b32 s86, s52, 3
	s_add_u32 s0, s76, 0x300000
	s_addc_u32 s1, s77, 0
	v_writelane_b32 v246, s0, 36
	v_and_b32_e32 v170, 63, v171
	s_nop 0
	v_writelane_b32 v246, s1, 37
	s_add_u32 s0, s76, 0x1a00000
	s_addc_u32 s1, s77, 0
	v_writelane_b32 v246, s0, 38
	s_nop 1
	v_writelane_b32 v246, s1, 39
	s_add_u32 s0, s76, 0x1b00000
	s_addc_u32 s1, s77, 0
	v_writelane_b32 v246, s0, 40
	s_nop 1
	v_writelane_b32 v246, s1, 41
	s_add_u32 s0, s76, 0x1d00000
	s_addc_u32 s1, s77, 0
	v_writelane_b32 v246, s0, 42
	s_nop 1
	v_writelane_b32 v246, s1, 43
	s_add_u32 s0, s76, 0x1f00000
	s_addc_u32 s1, s77, 0
	v_writelane_b32 v246, s0, 44
	s_nop 1
	v_writelane_b32 v246, s1, 45
	s_add_u32 s0, s76, 0x2a00000
	s_addc_u32 s1, s77, 0
	v_writelane_b32 v246, s0, 46
	s_cmpk_eq_i32 s52, 0x100
	s_nop 0
	v_writelane_b32 v246, s1, 47
	s_cselect_b64 s[0:1], -1, 0
	s_cmp_eq_u32 s10, 13
	s_cselect_b64 s[2:3], -1, 0
	s_and_b64 s[92:93], s[2:3], s[0:1]
	s_cmp_lt_i32 s78, 1
	s_cselect_b64 s[0:1], -1, 0
	s_cmp_gt_i32 s79, 0
	s_cselect_b64 s[2:3], -1, 0
	s_and_b64 s[2:3], s[0:1], s[2:3]
	s_andn2_b64 vcc, exec, s[2:3]
	s_cbranch_vccnz .LBB0_62
	s_movk_i32 s4, 0x1700
	s_and_b64 s[0:1], s[92:93], exec
	s_cselect_b32 s10, s4, 0x2c80
	s_cmp_ge_i32 s84, s10
	v_mov_b32_e32 v1, 0
	s_cbranch_scc1 .LBB0_57
	v_lshlrev_b32_e32 v0, 3, v171
	s_lshl_b32 s0, s55, 14
	v_lshrrev_b32_e32 v3, 3, v170
	v_and_b32_e32 v0, 56, v0
	s_add_i32 s4, s0, 0
	v_mul_u32_u24_e32 v6, 0x84, v0
	v_lshlrev_b32_e32 v7, 2, v3
	v_add3_u32 v46, s4, v6, v7
	v_readlane_b32 s4, v246, 44
	v_lshlrev_b32_e32 v0, 1, v0
	v_readlane_b32 s5, v246, 45
	v_readlane_b32 s6, v246, 46
	v_lshrrev_b32_e32 v2, 5, v170
	v_lshl_add_u64 v[6:7], s[4:5], 0, v[0:1]
	v_readlane_b32 s4, v246, 42
	v_readlane_b32 s5, v246, 43
	v_readlane_b32 s7, v246, 47
	v_and_b32_e32 v16, 31, v171
	v_lshl_add_u64 v[8:9], s[4:5], 0, v[0:1]
	v_readlane_b32 s4, v246, 40
	v_readlane_b32 s5, v246, 41
	v_lshl_add_u64 v[4:5], s[6:7], 0, v[0:1]
	v_readlane_b32 s16, v246, 20
	v_lshl_add_u64 v[10:11], s[4:5], 0, v[0:1]
	v_readlane_b32 s4, v246, 38
	v_readlane_b32 s5, v246, 39
	v_mul_u32_u24_e32 v20, 0x5800, v2
	v_readlane_b32 s17, v246, 21
	v_lshl_add_u64 v[12:13], s[4:5], 0, v[0:1]
	v_readlane_b32 s4, v246, 36
	v_readlane_b32 s5, v246, 37
	s_nop 1
	v_lshl_add_u64 v[14:15], s[4:5], 0, v[0:1]
	v_mul_u32_u24_e32 v0, 0x84, v2
	v_or_b32_e32 v17, s0, v0
	v_lshlrev_b32_e32 v0, 2, v16
	v_readlane_b32 s22, v246, 26
	v_readlane_b32 s23, v246, 27
	v_readlane_b32 s24, v246, 28
	v_readlane_b32 s25, v246, 29
	v_mul_hi_u32_u24_e32 v21, 0x5800, v2
	v_or_b32_e32 v20, v20, v0
	v_add3_u32 v50, v17, v0, 0
	v_lshl_add_u64 v[16:17], s[24:25], 0, v[0:1]
	s_lshl_b32 s0, s74, 4
	s_lshl_b32 s4, s55, 1
	v_lshl_add_u64 v[18:19], s[22:23], 0, v[0:1]
	v_lshl_add_u64 v[20:21], s[22:23], 0, v[20:21]
	v_lshl_add_u64 v[22:23], s[16:17], 0, v[0:1]
	s_add_i32 s0, s0, s4
	s_lshl_b32 s4, s74, 8
	s_lshl_b32 s5, s55, 5
	v_readlane_b32 s22, v246, 10
	v_readlane_b32 s23, v246, 11
	v_readlane_b32 s28, v246, 16
	v_readlane_b32 s29, v246, 17
	v_readlane_b32 s30, v246, 18
	v_readlane_b32 s31, v246, 19
	s_mov_b32 s1, 0
	v_or_b32_e32 v47, 8, v3
	v_or_b32_e32 v48, 16, v3
	v_or_b32_e32 v49, 24, v3
	v_or_b32_e32 v51, 14, v2
	s_add_i32 s11, s0, 0x7fffb200
	s_lshl_b32 s12, s52, 4
	s_add_i32 s13, s4, s5
	s_lshl_b32 s14, s52, 8
	v_or_b32_e32 v52, 12, v2
	v_or_b32_e32 v53, 10, v2
	v_or_b32_e32 v54, 8, v2
	v_or_b32_e32 v55, 6, v2
	v_or_b32_e32 v56, 4, v2
	v_or_b32_e32 v57, 2, v2
	s_add_i32 s15, s0, 0x7fffcc00
	v_lshl_add_u64 v[24:25], s[30:31], 0, v[0:1]
	s_add_i32 s16, s0, 0x7fffd000
	v_lshl_add_u64 v[26:27], s[28:29], 0, v[0:1]
	s_add_i32 s17, s0, 0x7fffd200
	v_lshl_add_u64 v[28:29], s[22:23], 0, v[0:1]
	s_mov_b32 s18, 0xb800
	v_mov_b32_e32 v58, 0xb800
	s_mov_b32 s19, s84
	v_readlane_b32 s20, v246, 8
	v_readlane_b32 s21, v246, 9
	v_readlane_b32 s24, v246, 12
	s_branch .LBB0_25

.LBB0_57:
	s_cmpk_gt_i32 s84, 0x3fff
	s_cbranch_scc1 .LBB0_62
	v_mbcnt_lo_u32_b32 v0, -1, 0
	v_mbcnt_hi_u32_b32 v0, -1, v0
	v_and_b32_e32 v1, 64, v0
	v_add_u32_e32 v1, 64, v1
	v_xor_b32_e32 v2, 1, v0
	v_cmp_lt_i32_e64 s[0:1], v2, v1
	s_ashr_i32 s85, s84, 31
	v_readlane_b32 s8, v246, 4
	v_cndmask_b32_e64 v2, v0, v2, s[0:1]
	v_lshlrev_b32_e32 v26, 2, v2
	v_xor_b32_e32 v2, 2, v0
	v_cmp_lt_i32_e64 s[0:1], v2, v1
	v_readlane_b32 s9, v246, 5
	v_lshlrev_b32_e32 v16, 4, v170
	v_cndmask_b32_e64 v2, v0, v2, s[0:1]
	v_lshlrev_b32_e32 v27, 2, v2
	v_xor_b32_e32 v2, 4, v0
	v_cmp_lt_i32_e64 s[0:1], v2, v1
	v_mov_b32_e32 v17, 0
	v_readlane_b32 s12, v246, 8
	v_cndmask_b32_e64 v2, v0, v2, s[0:1]
	v_lshlrev_b32_e32 v28, 2, v2
	v_xor_b32_e32 v2, 8, v0
	v_cmp_lt_i32_e64 s[0:1], v2, v1
	v_readlane_b32 s13, v246, 9
	s_nop 0
	v_cndmask_b32_e64 v2, v0, v2, s[0:1]
	v_lshlrev_b32_e32 v29, 2, v2
	v_xor_b32_e32 v2, 16, v0
	v_cmp_lt_i32_e64 s[0:1], v2, v1
	s_nop 1
	v_cndmask_b32_e64 v2, v0, v2, s[0:1]
	v_lshlrev_b32_e32 v30, 2, v2
	v_xor_b32_e32 v2, 32, v0
	v_cmp_lt_i32_e64 s[0:1], v2, v1
	s_nop 1
	v_cndmask_b32_e64 v0, v0, v2, s[0:1]
	s_lshl_b64 s[0:1], s[84:85], 3
	s_add_u32 s0, s76, s0
	s_addc_u32 s1, s77, s1
	s_ashr_i32 s87, s86, 31
	s_lshl_b64 s[4:5], s[86:87], 3
	s_lshl_b64 s[6:7], s[84:85], 12
	s_add_u32 s6, s8, s6
	s_addc_u32 s7, s9, s7
	v_lshl_add_u64 v[20:21], s[12:13], 0, v[16:17]
	v_lshlrev_b32_e32 v31, 2, v0
	v_lshl_add_u64 v[0:1], s[6:7], 0, v[16:17]
	s_mov_b64 s[6:7], 0xc00
	v_lshl_add_u64 v[22:23], v[0:1], 0, s[6:7]
	s_lshl_b64 s[6:7], s[86:87], 12
	s_lshl_b64 s[8:9], s[84:85], 11
	v_readlane_b32 s26, v246, 34
	v_readlane_b32 s10, v246, 6
	v_readlane_b32 s11, v246, 7
	v_readlane_b32 s27, v246, 35
	s_add_u32 s8, s26, s8
	v_lshl_add_u64 v[18:19], s[10:11], 0, v[16:17]
	v_lshlrev_b32_e32 v16, 3, v170
	s_addc_u32 s9, s27, s9
	v_cmp_eq_u32_e32 vcc, 0, v170
	v_lshl_add_u64 v[24:25], s[8:9], 0, v[16:17]
	s_lshl_b64 s[8:9], s[86:87], 11
	v_mov_b32_e32 v32, 0x3727c5ac
	s_mov_b32 s12, s84
	v_readlane_b32 s16, v246, 24
	v_readlane_b32 s17, v246, 25
	v_readlane_b32 s19, v246, 27
	v_readlane_b32 s20, v246, 28
	v_readlane_b32 s21, v246, 29
	v_readlane_b32 s22, v246, 30
	v_readlane_b32 s23, v246, 31
	v_readlane_b32 s24, v246, 32
	global_load_dwordx4 v[96:99], v[18:19], off
	global_load_dwordx4 v[112:115], v[20:21], off
	global_load_dwordx4 v[100:103], v[18:19], off offset:1024
	global_load_dwordx4 v[116:119], v[20:21], off offset:1024
	global_load_dwordx4 v[104:107], v[18:19], off offset:2048
	global_load_dwordx4 v[120:123], v[20:21], off offset:2048
	global_load_dwordx4 v[108:111], v[18:19], off offset:3072
	global_load_dwordx4 v[124:127], v[20:21], off offset:3072
	global_load_dwordx4 v[12:15], v[22:23], off offset:-3072 nt
	global_load_dwordx4 v[8:11], v[22:23], off offset:-2048 nt
	global_load_dwordx4 v[4:7], v[22:23], off offset:-1024 nt
	global_load_dwordx4 v[0:3], v[22:23], off nt
	s_waitcnt vmcnt(0)

.LBB0_112:
	s_cmp_lt_i32 s78, 2
	s_cselect_b64 s[2:3], -1, 0
	s_add_u32 s94, s76, 0x3000000
	v_readlane_b32 s4, v246, 20
	s_addc_u32 s95, s77, 0
	v_readlane_b32 s18, v246, 34
	v_readlane_b32 s19, v246, 35
	s_add_u32 s88, s18, 0x2000000
	s_addc_u32 s89, s19, 0
	s_and_b64 s[6:7], s[2:3], s[0:1]
	s_andn2_b64 vcc, exec, s[6:7]
	v_readlane_b32 s14, v246, 30
	v_readlane_b32 s15, v246, 31
	v_readlane_b32 s16, v246, 32
	v_readlane_b32 s17, v246, 33
	s_cbranch_vccnz .LBB0_227
	s_mov_b32 s87, 0
	s_cmpk_lt_i32 s74, 0x500
	s_cselect_b64 s[0:1], -1, 0
	s_cmpk_gt_i32 s74, 0x4ff
	v_readfirstlane_b32 s12, v171
	s_cbranch_scc1 .LBB0_115
	s_ashr_i32 s2, s74, 31
	s_lshr_b32 s2, s2, 29
	s_add_i32 s2, s74, s2
	s_ashr_i32 s3, s2, 3
	s_and_b32 s2, s2, -8
	s_sub_i32 s2, s74, s2
	s_cmp_lt_i32 s2, 0
	s_movk_i32 s4, 0xa1
	s_cselect_b32 s4, s4, 0xa0
	s_mul_i32 s2, s2, s4
	s_add_i32 s2, s2, s3
	s_mul_hi_i32 s3, s2, 0x66666667
	s_lshr_b32 s4, s3, 31
	s_ashr_i32 s3, s3, 6
	s_add_i32 s3, s3, s4
	s_lshl_b32 s4, s3, 3
	s_mulk_i32 s3, 0xa0
	s_sub_i32 s2, s2, s3
	s_sext_i32_i16 s3, s2
	s_bfe_u32 s3, s3, 0x3001c
	s_add_i32 s3, s2, s3
	s_sext_i32_i16 s5, s3
	s_and_b32 s3, s3, 0xfff8
	s_sub_i32 s2, s2, s3
	s_sext_i32_i16 s2, s2
	s_add_i32 s4, s4, s2
	s_ashr_i32 s24, s5, 3
.LBB0_115:
	s_andn2_b64 vcc, exec, s[0:1]
	s_cbranch_vccnz .LBB0_227
	v_lshrrev_b32_e32 v2, 1, v171
	v_and_b32_e32 v11, 24, v2
	v_lshrrev_b32_e32 v2, 5, v171
	v_and_b32_e32 v2, 4, v2
	v_bfe_u32 v3, v171, 2, 2
	v_lshlrev_b32_e32 v0, 4, v171
	v_and_b32_e32 v1, 32, v171
	v_bfe_u32 v10, v171, 2, 4
	v_or3_b32 v2, v2, v3, v11
	v_lshrrev_b32_e32 v3, 3, v171
	s_movk_i32 s0, 0x70
	v_bitop3_b32 v8, v0, v1, 48 bitop3:0x6c
	v_and_b32_e32 v9, 64, v171
	v_and_or_b32 v4, v3, s0, v10
	s_movk_i32 s0, 0x60
	v_add_u32_e32 v12, 0x2000, v0
	s_add_u32 s15, s76, 0xc00000
	v_or_b32_e32 v1, v8, v9
	v_and_or_b32 v3, v3, s0, v2
	v_lshrrev_b32_e32 v0, 7, v12
	s_movk_i32 s0, 0xf0
	s_addc_u32 s30, s77, 0
	v_lshl_or_b32 v138, v3, 11, v1
	v_and_or_b32 v3, v0, s0, v10
	s_movk_i32 s0, 0xe0
	s_lshr_b32 s1, s12, 6
	s_ashr_i32 s5, s4, 31
	s_ashr_i32 s25, s24, 31
	v_and_or_b32 v0, v0, s0, v2
	s_lshr_b32 s0, s12, 8
	s_lshl_b32 s31, s1, 10
	s_lshl_b64 s[2:3], s[4:5], 19
	s_lshl_b64 s[8:9], s[24:25], 19
	s_add_u32 s26, s15, s8
	s_addc_u32 s27, s30, s9
	s_add_i32 s34, s31, 0
	s_add_i32 m0, s34, 0x10000
	v_lshl_or_b32 v142, v0, 11, v1
	global_load_lds_dwordx4 v138, s[26:27]
	s_add_i32 m0, s34, 0x12000
	s_add_u32 s8, s26, 0x40000
	global_load_lds_dwordx4 v142, s[26:27]
	s_addc_u32 s9, s27, 0
	s_add_i32 m0, s34, 0x14000
	global_load_lds_dwordx4 v138, s[8:9]
	s_add_i32 m0, s34, 0x16000
	v_readlane_b32 s70, v246, 34
	v_readlane_b32 s71, v246, 35
	s_add_u32 s2, s70, s2
	s_addc_u32 s3, s71, s3
	s_add_i32 s35, s34, 0x2000
	v_lshl_or_b32 v136, v4, 11, v1
	global_load_lds_dwordx4 v142, s[8:9]
	s_mov_b32 m0, s34
	s_add_u32 s8, s2, 0x40000
	v_lshl_or_b32 v140, v3, 11, v1
	global_load_lds_dwordx4 v136, s[2:3]
	s_mov_b32 m0, s35
	s_addc_u32 s9, s3, 0
	s_add_i32 s36, s34, 0x4000
	global_load_lds_dwordx4 v140, s[2:3]
	s_mov_b32 m0, s36
	s_add_i32 s37, s34, 0x6000
	global_load_lds_dwordx4 v136, s[8:9]
	s_mov_b32 m0, s37
	v_mov_b32_e32 v139, 0
	global_load_lds_dwordx4 v140, s[8:9]
	v_mov_b32_e32 v143, v139
	v_mov_b32_e32 v137, v139
	v_mov_b32_e32 v141, v139
	s_cmp_eq_u32 s0, 1
	s_mov_b32 s38, 0
	v_lshl_add_u64 v[6:7], s[26:27], 0, v[138:139]
	v_lshl_add_u64 v[4:5], s[26:27], 0, v[142:143]
	v_lshl_add_u64 v[0:1], s[2:3], 0, v[136:137]
	s_cselect_b64 s[8:9], -1, 0
	s_cmp_lg_u32 s0, 1
	v_lshl_add_u64 v[2:3], s[2:3], 0, v[140:141]
	s_cbranch_scc1 .LBB0_118
	s_barrier

.LBB0_123:
	s_ashr_i32 s19, s18, 31
	s_lshl_b64 s[20:21], s[18:19], 19
	v_readlane_b32 s70, v246, 34
	v_readlane_b32 s71, v246, 35
	s_add_u32 s20, s70, s20
	s_addc_u32 s21, s71, s21
	s_and_b64 s[22:23], s[0:1], exec
	s_cselect_b32 s5, s21, s3
	s_cselect_b32 s19, s20, s2
	s_ashr_i32 s17, s16, 31
	s_lshl_b64 s[22:23], s[16:17], 19
	s_add_u32 s22, s15, s22
	s_addc_u32 s23, s30, s23
	s_and_b64 s[28:29], s[0:1], exec
	s_cselect_b32 s17, s23, s27
	s_cselect_b32 s25, s22, s26
	s_add_u32 s2, s2, 0x40080
	s_addc_u32 s3, s3, 0
	s_add_u32 s33, s26, 0x100
	s_addc_u32 s46, s27, 0
	s_mov_b32 s47, -2
	v_readlane_b32 s68, v246, 32
	v_readlane_b32 s69, v246, 33
	ds_read_b128 v[128:131], v161
	ds_read_b128 v[132:135], v161 offset:1024
	ds_read_b128 v[152:155], v161 offset:2048
	ds_read_b128 v[164:167], v161 offset:3072
	ds_read_b128 v[172:175], v162
	ds_read_b128 v[176:179], v162 offset:1024
	ds_read_b128 v[180:183], v162 offset:2048
	ds_read_b128 v[184:187], v162 offset:3072
	s_add_u32 s26, s2, 0xfffc0080
	s_addc_u32 s27, s3, -1
	s_cmp_eq_u32 s47, 12
	s_cselect_b32 s29, s5, s27
	s_cselect_b32 s28, s19, s26
	s_cselect_b32 s27, s17, s46
	s_cselect_b32 s26, s25, s33
	v_lshl_add_u64 v[156:157], s[2:3], 0, v[144:145]
	s_add_i32 m0, s34, 0xc000
	ds_read_b128 v[188:191], v163
	ds_read_b128 v[192:195], v163 offset:1024
	ds_read_b128 v[196:199], v163 offset:2048
	ds_read_b128 v[200:203], v163 offset:3072
	ds_read_b128 v[204:207], v163 offset:4096
	ds_read_b128 v[208:211], v163 offset:5120
	ds_read_b128 v[212:215], v163 offset:6144
	ds_read_b128 v[216:219], v163 offset:7168
	global_load_lds_dwordx4 v[156:157], off
	v_lshl_add_u64 v[156:157], s[2:3], 0, v[146:147]
	s_add_i32 m0, s34, 0xe000
	s_nop 0
	global_load_lds_dwordx4 v[156:157], off
	s_waitcnt vmcnt(8)
	s_waitcnt lgkmcnt(0)
	s_barrier
	s_waitcnt lgkmcnt(0)
	v_mfma_f32_16x16x32_bf16 v[124:127], v[128:131], v[188:191], 0
	v_mfma_f32_16x16x32_bf16 v[120:123], v[152:155], v[188:191], 0
	v_mfma_f32_16x16x32_bf16 v[108:111], v[128:131], v[196:199], 0
	v_mfma_f32_16x16x32_bf16 v[104:107], v[152:155], v[196:199], 0
	v_mfma_f32_16x16x32_bf16 v[92:95], v[128:131], v[204:207], 0
	v_mfma_f32_16x16x32_bf16 v[88:91], v[152:155], v[204:207], 0
	v_mfma_f32_16x16x32_bf16 v[76:79], v[128:131], v[212:215], 0
	v_mfma_f32_16x16x32_bf16 v[72:75], v[152:155], v[212:215], 0
	v_mfma_f32_16x16x32_bf16 v[124:127], v[132:135], v[192:195], v[124:127]
	v_mfma_f32_16x16x32_bf16 v[120:123], v[164:167], v[192:195], v[120:123]
	v_mfma_f32_16x16x32_bf16 v[108:111], v[132:135], v[200:203], v[108:111]
	v_mfma_f32_16x16x32_bf16 v[104:107], v[164:167], v[200:203], v[104:107]
	v_mfma_f32_16x16x32_bf16 v[92:95], v[132:135], v[208:211], v[92:95]
	v_mfma_f32_16x16x32_bf16 v[88:91], v[164:167], v[208:211], v[88:91]
	v_mfma_f32_16x16x32_bf16 v[76:79], v[132:135], v[216:219], v[76:79]
	v_mfma_f32_16x16x32_bf16 v[72:75], v[164:167], v[216:219], v[72:75]
	v_mfma_f32_16x16x32_bf16 v[116:119], v[172:175], v[188:191], 0
	v_mfma_f32_16x16x32_bf16 v[112:115], v[180:183], v[188:191], 0
	v_mfma_f32_16x16x32_bf16 v[100:103], v[172:175], v[196:199], 0
	v_mfma_f32_16x16x32_bf16 v[96:99], v[180:183], v[196:199], 0
	v_mfma_f32_16x16x32_bf16 v[84:87], v[172:175], v[204:207], 0
	v_mfma_f32_16x16x32_bf16 v[80:83], v[180:183], v[204:207], 0
	v_mfma_f32_16x16x32_bf16 v[68:71], v[172:175], v[212:215], 0
	v_mfma_f32_16x16x32_bf16 v[64:67], v[180:183], v[212:215], 0
	v_mfma_f32_16x16x32_bf16 v[116:119], v[176:179], v[192:195], v[116:119]
	v_mfma_f32_16x16x32_bf16 v[112:115], v[184:187], v[192:195], v[112:115]
	v_mfma_f32_16x16x32_bf16 v[100:103], v[176:179], v[200:203], v[100:103]
	v_mfma_f32_16x16x32_bf16 v[96:99], v[184:187], v[200:203], v[96:99]
	v_mfma_f32_16x16x32_bf16 v[84:87], v[176:179], v[208:211], v[84:87]
	v_mfma_f32_16x16x32_bf16 v[80:83], v[184:187], v[208:211], v[80:83]
	v_mfma_f32_16x16x32_bf16 v[68:71], v[176:179], v[216:219], v[68:71]
	v_mfma_f32_16x16x32_bf16 v[64:67], v[184:187], v[216:219], v[64:67]
	s_barrier
	s_add_i32 s49, s44, s31
	v_lshl_add_u64 v[156:157], s[26:27], 0, v[138:139]
	s_mov_b32 m0, s49
	ds_read_b128 v[188:191], v163 offset:16384
	ds_read_b128 v[192:195], v163 offset:17408
	ds_read_b128 v[196:199], v163 offset:18432
	ds_read_b128 v[200:203], v163 offset:19456
	ds_read_b128 v[204:207], v163 offset:20480
	ds_read_b128 v[208:211], v163 offset:21504
	ds_read_b128 v[212:215], v163 offset:22528
	ds_read_b128 v[216:219], v163 offset:23552
	global_load_lds_dwordx4 v[156:157], off
	s_add_i32 m0, s49, 0x2000
	s_add_u32 s50, s26, 0x40000
	v_lshl_add_u64 v[168:169], s[26:27], 0, v[142:143]
	s_addc_u32 s51, s27, 0
	s_add_i32 s49, s45, s31
	global_load_lds_dwordx4 v[168:169], off
	v_lshl_add_u64 v[220:221], s[50:51], 0, v[138:139]
	s_mov_b32 m0, s49
	v_lshl_add_u64 v[222:223], s[28:29], 0, v[140:141]
	global_load_lds_dwordx4 v[220:221], off
	v_lshl_add_u64 v[220:221], s[50:51], 0, v[142:143]
	s_add_i32 m0, s49, 0x2000
	s_nop 0
	global_load_lds_dwordx4 v[220:221], off
	v_lshl_add_u64 v[220:221], s[28:29], 0, v[136:137]
	s_mov_b32 m0, s34
	s_nop 0
	global_load_lds_dwordx4 v[220:221], off
	s_mov_b32 m0, s35
	s_nop 0
	global_load_lds_dwordx4 v[222:223], off
	s_waitcnt vmcnt(8)
	s_waitcnt lgkmcnt(0)
	s_barrier
	s_waitcnt lgkmcnt(0)
	v_mfma_f32_16x16x32_bf16 v[60:63], v[128:131], v[188:191], 0
	v_mfma_f32_16x16x32_bf16 v[56:59], v[152:155], v[188:191], 0
	v_mfma_f32_16x16x32_bf16 v[44:47], v[128:131], v[196:199], 0
	v_mfma_f32_16x16x32_bf16 v[40:43], v[152:155], v[196:199], 0
	v_mfma_f32_16x16x32_bf16 v[28:31], v[128:131], v[204:207], 0
	v_mfma_f32_16x16x32_bf16 v[24:27], v[152:155], v[204:207], 0
	v_mfma_f32_16x16x32_bf16 v[12:15], v[128:131], v[212:215], 0
	v_mfma_f32_16x16x32_bf16 v[8:11], v[152:155], v[212:215], 0
	v_mfma_f32_16x16x32_bf16 v[60:63], v[132:135], v[192:195], v[60:63]
	v_mfma_f32_16x16x32_bf16 v[56:59], v[164:167], v[192:195], v[56:59]
	v_mfma_f32_16x16x32_bf16 v[44:47], v[132:135], v[200:203], v[44:47]
	v_mfma_f32_16x16x32_bf16 v[40:43], v[164:167], v[200:203], v[40:43]
	v_mfma_f32_16x16x32_bf16 v[28:31], v[132:135], v[208:211], v[28:31]
	v_mfma_f32_16x16x32_bf16 v[24:27], v[164:167], v[208:211], v[24:27]
	v_mfma_f32_16x16x32_bf16 v[12:15], v[132:135], v[216:219], v[12:15]
	v_mfma_f32_16x16x32_bf16 v[8:11], v[164:167], v[216:219], v[8:11]
	v_mfma_f32_16x16x32_bf16 v[52:55], v[172:175], v[188:191], 0
	v_mfma_f32_16x16x32_bf16 v[48:51], v[180:183], v[188:191], 0
	v_mfma_f32_16x16x32_bf16 v[36:39], v[172:175], v[196:199], 0
	v_mfma_f32_16x16x32_bf16 v[32:35], v[180:183], v[196:199], 0
	v_mfma_f32_16x16x32_bf16 v[20:23], v[172:175], v[204:207], 0
	v_mfma_f32_16x16x32_bf16 v[16:19], v[180:183], v[204:207], 0
	v_mfma_f32_16x16x32_bf16 v[4:7], v[172:175], v[212:215], 0
	v_mfma_f32_16x16x32_bf16 v[0:3], v[180:183], v[212:215], 0
	v_mfma_f32_16x16x32_bf16 v[52:55], v[176:179], v[192:195], v[52:55]
	v_mfma_f32_16x16x32_bf16 v[48:51], v[184:187], v[192:195], v[48:51]
	v_mfma_f32_16x16x32_bf16 v[36:39], v[176:179], v[200:203], v[36:39]
	v_mfma_f32_16x16x32_bf16 v[32:35], v[184:187], v[200:203], v[32:35]
	v_mfma_f32_16x16x32_bf16 v[20:23], v[176:179], v[208:211], v[20:23]
	v_mfma_f32_16x16x32_bf16 v[16:19], v[184:187], v[208:211], v[16:19]
	v_mfma_f32_16x16x32_bf16 v[4:7], v[176:179], v[216:219], v[4:7]
	v_mfma_f32_16x16x32_bf16 v[0:3], v[184:187], v[216:219], v[0:3]
	s_barrier
	s_branch .Lpeel124_mid

.LBB0_282:
	s_and_b32 s4, s49, 3
	s_cmp_eq_u32 s4, 3
	s_cbranch_scc1 .LBB0_281
	s_bfe_u32 s5, s49, 0x10002
	s_lshl_b32 s7, s49, 4
	s_lshl_b32 s6, s5, 11
	s_and_b32 s8, s7, 0x380
	s_or_b32 s6, s6, s8
	v_add_u32_e32 v74, s6, v73
	v_add_u32_e32 v4, 0x400, v74
	v_readlane_b32 s20, v246, 12
	v_readlane_b32 s21, v246, 13
	v_mov_b32_e32 v5, v75
	s_and_b32 s7, s47, 3
	v_lshl_add_u64 v[8:9], v[74:75], 2, s[20:21]
	v_lshl_add_u64 v[12:13], v[4:5], 2, s[20:21]
	global_load_dwordx4 v[0:3], v[8:9], off
	global_load_dword v15, v[12:13], off
	global_load_dwordx4 v[4:7], v[12:13], off offset:4
	s_nop 0
	global_load_dwordx4 v[8:11], v[8:9], off offset:16
	s_nop 0
	global_load_dwordx3 v[12:14], v[12:13], off offset:20
	s_ashr_i32 s6, s49, 6
	s_lshl_b32 s9, s7, 10
	s_ashr_i32 s7, s6, 31
	s_lshl_b32 s42, s5, 10
	s_lshl_b64 s[6:7], s[6:7], 25
	s_add_u32 s6, s94, s6
	s_addc_u32 s7, s95, s7
	s_lshl_b32 s4, s4, 10
	v_add_u32_e32 v74, s8, v73
	v_or_b32_e32 v18, s4, v142
	v_lshl_add_u64 v[16:17], v[74:75], 0, s[42:43]
	s_cmp_eq_u32 s5, 0
	v_lshl_add_u64 v[116:117], v[16:17], 1, s[6:7]
	v_lshlrev_b32_e32 v16, 12, v18
	v_or_b32_e32 v17, 1, v18
	v_xor_b32_e32 v18, 0xfff000, v16
	s_cselect_b64 vcc, -1, 0
	v_add_lshl_u32 v74, v147, s8, 1
	v_bitop3_b32 v19, s4, v149, v142 bitop3:0x36
	v_cndmask_b32_e32 v16, v18, v16, vcc
	v_lshl_add_u64 v[118:119], s[6:7], 0, v[74:75]
	v_cndmask_b32_e32 v20, v19, v17, vcc
	v_lshlrev_b32_e32 v74, 1, v16
	v_lshl_add_u64 v[16:17], v[116:117], 0, v[74:75]
	v_lshl_add_u64 v[18:19], v[118:119], 0, v[74:75]
	v_lshlrev_b32_e32 v74, 13, v20
	s_waitcnt vmcnt(0)
	s_barrier
	global_load_dwordx4 v[32:35], v[16:17], off offset:2048
	global_load_dwordx4 v[48:51], v[18:19], off
	v_lshl_add_u64 v[16:17], v[116:117], 0, v[74:75]
	v_lshl_add_u64 v[18:19], v[118:119], 0, v[74:75]
	global_load_dwordx4 v[36:39], v[16:17], off offset:2048
	global_load_dwordx4 v[52:55], v[18:19], off
	v_mov_b32_e32 v78, 1.0
	v_mov_b32_e32 v28, 0
	v_or_b32_e32 v158, s9, v142
	v_subrev_u32_e32 v159, s9, v148
	s_movk_i32 s33, 0xfc40
	v_mov_b32_e32 v29, v28
	v_mov_b32_e32 v30, v28
	v_mov_b32_e32 v31, v28
	v_mov_b32_e32 v24, v28
	v_mov_b32_e32 v25, v28
	v_mov_b32_e32 v26, v28
	v_mov_b32_e32 v27, v28
	v_mov_b32_e32 v20, v28
	v_mov_b32_e32 v21, v28
	v_mov_b32_e32 v22, v28
	v_mov_b32_e32 v23, v28
	v_mov_b32_e32 v16, v28
	v_mov_b32_e32 v17, v28
	v_mov_b32_e32 v18, v28
	v_mov_b32_e32 v19, v28
	v_mov_b32_e32 v79, v78
	v_mov_b32_e32 v80, v78
	v_mov_b32_e32 v81, v78
	v_mov_b32_e32 v82, v78
	v_mov_b32_e32 v83, v78
	v_mov_b32_e32 v84, v78
	v_mov_b32_e32 v85, v78
	s_barrier
	v_sub_f32_e32 v0, v15, v0
	v_sub_f32_e32 v1, v4, v1
	v_sub_f32_e32 v2, v5, v2
	v_sub_f32_e32 v3, v6, v3
	v_sub_f32_e32 v4, v7, v8
	v_sub_f32_e32 v5, v12, v9
	v_sub_f32_e32 v6, v13, v10
	v_sub_f32_e32 v7, v14, v11
	v_mul_f32_e32 v0, 0x3fb8aa3b, v0
	v_mul_f32_e32 v1, 0x3fb8aa3b, v1
	v_mul_f32_e32 v2, 0x3fb8aa3b, v2
	v_mul_f32_e32 v3, 0x3fb8aa3b, v3
	v_mul_f32_e32 v4, 0x3fb8aa3b, v4
	v_mul_f32_e32 v5, 0x3fb8aa3b, v5
	v_mul_f32_e32 v6, 0x3fb8aa3b, v6
	v_mul_f32_e32 v7, 0x3fb8aa3b, v7
	v_exp_f32_e32 v0, v0
	v_exp_f32_e32 v1, v1
	v_exp_f32_e32 v2, v2
	v_exp_f32_e32 v3, v3
	v_exp_f32_e32 v4, v4
	v_exp_f32_e32 v5, v5
	v_exp_f32_e32 v6, v6
	v_exp_f32_e32 v7, v7
	v_add_f32_e32 v0, 1.0, v0
	v_add_f32_e32 v1, 1.0, v1
	v_add_f32_e32 v2, 1.0, v2
	v_add_f32_e32 v3, 1.0, v3
	v_add_f32_e32 v4, 1.0, v4
	v_add_f32_e32 v5, 1.0, v5
	v_add_f32_e32 v6, 1.0, v6
	v_add_f32_e32 v7, 1.0, v7
	v_rcp_f32_e32 v102, v0
	v_rcp_f32_e32 v120, v1
	v_rcp_f32_e32 v114, v2
	v_rcp_f32_e32 v112, v3
	v_rcp_f32_e32 v110, v4
	v_rcp_f32_e32 v108, v5
	v_rcp_f32_e32 v106, v6
	v_rcp_f32_e32 v104, v7
	v_sub_f32_e32 v100, 1.0, v102
	v_sub_f32_e32 v98, 1.0, v120
	v_sub_f32_e32 v96, 1.0, v114
	v_sub_f32_e32 v94, 1.0, v112
	v_sub_f32_e32 v92, 1.0, v110
	v_sub_f32_e32 v90, 1.0, v108
	v_sub_f32_e32 v88, 1.0, v106
	v_sub_f32_e32 v86, 1.0, v104
	v_mov_b32_e32 v101, v100
	v_mov_b32_e32 v103, v102
	v_mov_b32_e32 v105, v104
	v_mov_b32_e32 v87, v86
	v_mov_b32_e32 v107, v106
	v_mov_b32_e32 v89, v88
	v_mov_b32_e32 v109, v108
	v_mov_b32_e32 v91, v90
	v_mov_b32_e32 v111, v110
	v_mov_b32_e32 v93, v92
	v_mov_b32_e32 v113, v112
	v_mov_b32_e32 v95, v94
	v_mov_b32_e32 v115, v114
	v_mov_b32_e32 v97, v96
	v_mov_b32_e32 v121, v120
	v_mov_b32_e32 v99, v98
	v_mov_b32_e32 v12, v28
	v_mov_b32_e32 v13, v28
	v_mov_b32_e32 v14, v28
	v_mov_b32_e32 v15, v28
	v_mov_b32_e32 v8, v28
	v_mov_b32_e32 v9, v28
	v_mov_b32_e32 v10, v28
	v_mov_b32_e32 v11, v28
	v_mov_b32_e32 v4, v28
	v_mov_b32_e32 v5, v28
	v_mov_b32_e32 v6, v28
	v_mov_b32_e32 v7, v28
	v_mov_b32_e32 v0, v28
	v_mov_b32_e32 v1, v28
	v_mov_b32_e32 v2, v28
	v_mov_b32_e32 v3, v28

.LBB0_292:
	s_and_b32 s0, s54, 3
	s_cmp_eq_u32 s0, 3
	s_cselect_b64 s[0:1], -1, 0
	s_and_b64 s[0:1], s[92:93], s[0:1]
	s_andn2_b64 vcc, exec, s[0:1]
	s_cbranch_vccnz .LBB0_328
	s_lshl_b32 s0, s54, 1
	s_and_b32 s0, s0, -8
	s_add_i32 s0, s55, s0
	s_add_i32 s8, s0, 0x1700
	s_cmpk_gt_i32 s8, 0x2c7f
	s_waitcnt vmcnt(0)
	s_barrier
	s_cbranch_scc1 .LBB0_328
	v_lshlrev_b32_e32 v0, 3, v171
	s_lshl_b32 s0, s55, 14
	v_lshrrev_b32_e32 v46, 3, v170
	v_and_b32_e32 v0, 56, v0
	s_add_i32 s2, s0, 0
	v_mul_u32_u24_e32 v4, 0x84, v0
	v_lshlrev_b32_e32 v5, 2, v46
	v_add3_u32 v47, s2, v4, v5
	v_readlane_b32 s2, v246, 44
	v_lshlrev_b32_e32 v0, 1, v0
	v_mov_b32_e32 v1, 0
	v_readlane_b32 s3, v246, 45
	v_readlane_b32 s4, v246, 46
	v_lshrrev_b32_e32 v19, 5, v170
	v_lshl_add_u64 v[4:5], s[2:3], 0, v[0:1]
	v_readlane_b32 s2, v246, 42
	v_readlane_b32 s3, v246, 43
	v_readlane_b32 s5, v246, 47
	v_bfe_u32 v18, v171, 5, 1
	v_lshl_add_u64 v[6:7], s[2:3], 0, v[0:1]
	v_readlane_b32 s2, v246, 40
	v_readlane_b32 s3, v246, 41
	v_lshl_add_u64 v[2:3], s[4:5], 0, v[0:1]
	v_readlane_b32 s12, v246, 20
	v_lshl_add_u64 v[8:9], s[2:3], 0, v[0:1]
	v_readlane_b32 s2, v246, 38
	v_readlane_b32 s3, v246, 39
	v_mov_b32_e32 v73, v1
	v_readlane_b32 s13, v246, 21
	v_lshl_add_u64 v[10:11], s[2:3], 0, v[0:1]
	v_readlane_b32 s2, v246, 36
	v_readlane_b32 s3, v246, 37
	s_nop 1
	v_lshl_add_u64 v[12:13], s[2:3], 0, v[0:1]
	v_mul_u32_u24_e32 v0, 0x84, v19
	v_or_b32_e32 v0, s0, v0
	v_add3_u32 v51, v0, v72, 0
	v_mul_u32_u24_e32 v0, 0x5800, v18
	v_readlane_b32 s18, v246, 26
	v_readlane_b32 s19, v246, 27
	v_readlane_b32 s20, v246, 28
	v_readlane_b32 s21, v246, 29
	s_lshl_b32 s0, s54, 2
	v_mul_hi_u32_u24_e32 v21, 0x5800, v18
	v_or_b32_e32 v20, v0, v72
	v_lshl_add_u64 v[14:15], s[20:21], 0, v[72:73]
	s_and_b32 s0, s0, -16
	s_lshl_b32 s2, s55, 1
	v_lshl_add_u64 v[16:17], s[18:19], 0, v[72:73]
	v_lshl_add_u64 v[20:21], s[18:19], 0, v[20:21]
	v_lshl_add_u64 v[22:23], s[12:13], 0, v[72:73]
	s_add_i32 s0, s0, s2
	v_readlane_b32 s18, v246, 10
	v_readlane_b32 s19, v246, 11
	v_readlane_b32 s24, v246, 16
	v_readlane_b32 s25, v246, 17
	v_readlane_b32 s26, v246, 18
	v_readlane_b32 s27, v246, 19
	s_mov_b32 s1, 0
	v_or_b32_e32 v48, 8, v46
	v_or_b32_e32 v49, 16, v46
	v_or_b32_e32 v50, 24, v46
	v_or_b32_e32 v52, 14, v19
	s_add_i32 s9, s0, 0x7fffe000
	s_lshl_b32 s10, s8, 5
	v_or_b32_e32 v53, 12, v19
	v_or_b32_e32 v54, 10, v19
	v_or_b32_e32 v55, 8, v19
	v_or_b32_e32 v56, 6, v19
	v_or_b32_e32 v57, 4, v19
	v_or_b32_e32 v58, 2, v19
	s_add_i32 s11, s0, 0x7ffffa00
	v_lshl_add_u64 v[24:25], s[26:27], 0, v[72:73]
	s_add_i32 s12, s0, 0x7ffffe00
	v_lshl_add_u64 v[26:27], s[24:25], 0, v[72:73]
	s_add_i32 s13, s0, 0x80000000
	v_lshl_add_u64 v[28:29], s[18:19], 0, v[72:73]
	s_mov_b32 s14, 0xb800
	v_mov_b32_e32 v59, 0xb800
	v_readlane_b32 s15, v246, 7
	v_readlane_b32 s16, v246, 8
	v_readlane_b32 s17, v246, 9
	v_readlane_b32 s20, v246, 12
	v_readlane_b32 s21, v246, 13
	v_readlane_b32 s22, v246, 14
	v_readlane_b32 s23, v246, 15
	s_branch .LBB0_296

.LBB0_382:
	s_bfe_u32 s23, s33, 0x10002
	s_lshl_b32 s21, s33, 4
	s_lshl_b32 s20, s23, 11
	s_and_b32 s22, s21, 0x380
	s_or_b32 s20, s20, s22
	v_add_u32_e32 v0, s20, v148
	v_add_u32_e32 v2, 0x400, v0
	v_readlane_b32 s44, v246, 12
	v_readlane_b32 s45, v246, 13
	v_mov_b32_e32 v3, v1
	s_and_b32 s25, s61, 3
	v_lshl_add_u64 v[4:5], v[0:1], 2, s[44:45]
	v_lshl_add_u64 v[2:3], v[2:3], 2, s[44:45]
	global_load_dwordx4 v[34:37], v[4:5], off offset:16
	global_load_dwordx4 v[38:41], v[4:5], off
	global_load_dwordx3 v[46:48], v[2:3], off offset:20
	global_load_dword v49, v[2:3], off
	global_load_dwordx4 v[42:45], v[2:3], off offset:4
	s_and_b32 s24, s33, 3
	s_cmp_eq_u32 s24, 0
	s_waitcnt vmcnt(0)
	s_barrier
	s_cbranch_scc1 .LBB0_385
	s_lshr_b32 s21, s33, 2
	s_lshl_b32 s20, s21, 5
	v_mov_b32_e32 v2, 0
	s_add_i32 s20, s59, s20
	v_lshl_add_u32 v50, s21, 9, v154
	s_mov_b32 s26, s25
	v_mov_b32_e32 v3, v2
	v_mov_b32_e32 v4, v2
	v_mov_b32_e32 v5, v2
	v_mov_b32_e32 v22, v2
	v_mov_b32_e32 v23, v2
	v_mov_b32_e32 v24, v2
	v_mov_b32_e32 v25, v2
	v_mov_b32_e32 v26, v2
	v_mov_b32_e32 v27, v2
	v_mov_b32_e32 v28, v2
	v_mov_b32_e32 v29, v2
	v_mov_b32_e32 v30, v2
	v_mov_b32_e32 v31, v2
	v_mov_b32_e32 v32, v2
	v_mov_b32_e32 v33, v2
	v_mov_b32_e32 v18, v2
	v_mov_b32_e32 v19, v2
	v_mov_b32_e32 v20, v2
	v_mov_b32_e32 v21, v2
	v_mov_b32_e32 v6, v2
	v_mov_b32_e32 v7, v2
	v_mov_b32_e32 v8, v2
	v_mov_b32_e32 v9, v2
	v_mov_b32_e32 v10, v2
	v_mov_b32_e32 v11, v2
	v_mov_b32_e32 v12, v2
	v_mov_b32_e32 v13, v2
	v_mov_b32_e32 v14, v2
	v_mov_b32_e32 v15, v2
	v_mov_b32_e32 v16, v2
	v_mov_b32_e32 v17, v2

.LBB0_447:
	s_cmp_lt_i32 s78, 5
	s_cselect_b64 s[2:3], -1, 0
	s_and_b64 s[2:3], s[2:3], s[0:1]
	s_andn2_b64 vcc, exec, s[2:3]
	s_cbranch_vccnz .LBB0_469
	s_mov_b32 s87, 0
	s_mov_b32 s32, 0
	s_mov_b32 s85, 0
	s_cmpk_gt_i32 s74, 0x47f
	v_readfirstlane_b32 s1, v171
	s_cbranch_scc1 .LBB0_464
	v_lshrrev_b32_e32 v2, 1, v171
	v_and_b32_e32 v11, 24, v2
	v_lshrrev_b32_e32 v2, 5, v171
	v_and_b32_e32 v2, 4, v2
	v_bfe_u32 v3, v171, 2, 2
	v_lshlrev_b32_e32 v0, 4, v171
	v_and_b32_e32 v1, 32, v171
	v_bfe_u32 v10, v171, 2, 4
	v_or3_b32 v2, v2, v3, v11
	v_lshrrev_b32_e32 v3, 3, v171
	s_movk_i32 s0, 0x70
	v_bitop3_b32 v8, v0, v1, 48 bitop3:0x6c
	v_and_b32_e32 v9, 64, v171
	v_and_or_b32 v4, v3, s0, v10
	s_movk_i32 s0, 0x60
	v_add_u32_e32 v12, 0x2000, v0
	v_or_b32_e32 v1, v8, v9
	v_and_or_b32 v3, v3, s0, v2
	v_lshrrev_b32_e32 v0, 7, v12
	s_movk_i32 s0, 0xf0
	v_lshl_or_b32 v130, v3, 11, v1
	v_and_or_b32 v3, v0, s0, v10
	s_movk_i32 s0, 0xe0
	s_ashr_i32 s27, s74, 31
	v_and_or_b32 v0, v0, s0, v2
	s_lshr_b32 s0, s27, 29
	s_add_i32 s0, s74, s0
	s_lshr_b32 s6, s1, 6
	s_ashr_i32 s4, s0, 3
	s_and_b32 s0, s0, -8
	s_lshr_b32 s8, s1, 8
	s_lshl_b32 s26, s6, 10
	s_sub_i32 s0, s74, s0
	s_cmp_lt_i32 s0, 0
	s_movk_i32 s28, 0x91
	s_cselect_b32 s5, s28, 0x90
	s_mul_i32 s0, s0, s5
	s_add_i32 s0, s0, s4
	s_mul_hi_i32 s4, s0, 0x38e38e39
	s_lshr_b32 s5, s4, 31
	s_ashr_i32 s4, s4, 5
	s_add_i32 s4, s4, s5
	s_lshl_b32 s5, s4, 3
	s_mulk_i32 s4, 0x90
	s_sub_i32 s4, s0, s4
	s_sext_i32_i16 s0, s4
	s_bfe_u32 s0, s0, 0x3001c
	s_add_i32 s7, s4, s0
	s_sext_i32_i16 s0, s7
	s_and_b32 s7, s7, 0xfff8
	s_sub_i32 s4, s4, s7
	s_sext_i32_i16 s4, s4
	s_lshr_b32 s0, s0, 3
	s_add_i32 s18, s5, s4
	s_ashr_i32 s19, s18, 31
	s_bfe_i64 s[10:11], s[0:1], 0x100000
	s_lshl_b64 s[4:5], s[18:19], 19
	s_lshl_b64 s[10:11], s[10:11], 19
	v_readlane_b32 s12, v246, 36
	v_readlane_b32 s13, v246, 37
	s_add_u32 s22, s12, s10
	s_addc_u32 s23, s13, s11
	s_add_i32 s19, s26, 0
	s_add_i32 m0, s19, 0x10000
	v_lshl_or_b32 v134, v0, 11, v1
	global_load_lds_dwordx4 v130, s[22:23]
	s_add_i32 m0, s19, 0x12000
	s_add_u32 s10, s22, 0x40000
	global_load_lds_dwordx4 v134, s[22:23]
	s_addc_u32 s11, s23, 0
	s_add_i32 m0, s19, 0x14000
	global_load_lds_dwordx4 v130, s[10:11]
	s_add_i32 m0, s19, 0x16000
	v_readlane_b32 s50, v246, 34
	v_readlane_b32 s51, v246, 35
	s_add_u32 s20, s50, s4
	s_addc_u32 s21, s51, s5
	s_add_i32 s29, s19, 0x2000
	v_lshl_or_b32 v128, v4, 11, v1
	global_load_lds_dwordx4 v134, s[10:11]
	s_mov_b32 m0, s19
	s_add_u32 s4, s20, 0x40000
	v_lshl_or_b32 v132, v3, 11, v1
	global_load_lds_dwordx4 v128, s[20:21]
	s_mov_b32 m0, s29
	s_addc_u32 s5, s21, 0
	s_add_i32 s30, s19, 0x4000
	global_load_lds_dwordx4 v132, s[20:21]
	s_mov_b32 m0, s30
	s_add_i32 s31, s19, 0x6000
	global_load_lds_dwordx4 v128, s[4:5]
	s_mov_b32 m0, s31
	v_mov_b32_e32 v131, 0
	global_load_lds_dwordx4 v132, s[4:5]
	v_mov_b32_e32 v135, v131
	v_mov_b32_e32 v129, v131
	v_mov_b32_e32 v133, v131
	s_cmp_eq_u32 s8, 1
	s_mov_b32 s33, 0
	v_lshl_add_u64 v[6:7], s[22:23], 0, v[130:131]
	v_lshl_add_u64 v[4:5], s[22:23], 0, v[134:135]
	v_lshl_add_u64 v[0:1], s[20:21], 0, v[128:129]
	s_cselect_b64 s[4:5], -1, 0
	s_cmp_lg_u32 s8, 1
	v_lshl_add_u64 v[2:3], s[20:21], 0, v[132:133]
	s_cbranch_scc1 .LBB0_451
	s_barrier
.LBB0_451:
	s_lshl_b32 s6, s6, 5
	s_and_b32 s12, s6, 0x60
	s_mov_b64 s[6:7], 0x80
	v_readlane_b32 s14, v246, 48
	s_add_i32 m0, s19, 0x18000
	v_lshl_add_u64 v[6:7], v[6:7], 0, s[6:7]
	s_ashr_i32 s34, s14, 31
	s_lshl_b32 s9, s8, 13
	s_lshl_b32 s13, s12, 7
	global_load_lds_dwordx4 v[6:7], off
	v_lshl_add_u64 v[4:5], v[4:5], 0, s[6:7]
	s_add_i32 m0, s19, 0x1a000
	s_add_i32 s35, s19, 0x8000
	s_add_i32 s36, s19, 0xa000
	global_load_lds_dwordx4 v[4:5], off
	v_lshl_add_u64 v[0:1], v[0:1], 0, s[6:7]
	s_mov_b32 m0, s35
	s_add_u32 s10, s22, 0x40080
	global_load_lds_dwordx4 v[0:1], off
	v_lshl_add_u64 v[0:1], v[2:3], 0, s[6:7]
	s_mov_b32 m0, s36
	s_addc_u32 s11, s23, 0
	global_load_lds_dwordx4 v[0:1], off
	s_add_i32 m0, s19, 0x1c000
	v_lshl_add_u64 v[0:1], s[10:11], 0, v[130:131]
	global_load_lds_dwordx4 v[0:1], off
	v_lshl_add_u64 v[0:1], s[10:11], 0, v[134:135]
	s_add_i32 m0, s19, 0x1e000
	s_sext_i32_i16 s41, s0
	global_load_lds_dwordx4 v[0:1], off
	s_waitcnt vmcnt(8)
	s_barrier
	v_and_b32_e32 v0, 15, v171
	v_lshlrev_b32_e32 v1, 1, v11
	v_lshlrev_b32_e32 v2, 6, v171
	s_movk_i32 s0, 0x3c0
	v_lshlrev_b32_e32 v3, 2, v171
	v_and_or_b32 v2, v2, s0, v1
	v_and_b32_e32 v3, 32, v3
	v_lshl_or_b32 v145, s8, 6, v0
	v_lshl_or_b32 v0, v0, 6, v1
	v_lshlrev_b32_e32 v1, 8, v171
	v_bitop3_b32 v146, s13, v2, v3 bitop3:0xf6
	v_and_b32_e32 v1, 0x38000, v1
	v_lshlrev_b32_e32 v2, 11, v10
	v_or3_b32 v1, v8, v1, v2
	v_add_u32_e32 v136, v1, v9
	v_lshlrev_b32_e32 v1, 4, v12
	s_waitcnt vmcnt(6)
	s_cmpk_lt_u32 s1, 0x100
	v_and_b32_e32 v1, 0x78000, v1
	v_bitop3_b32 v0, v0, s9, v3 bitop3:0xde
	s_cselect_b64 s[8:9], -1, 0
	v_or3_b32 v1, v8, v1, v2
	s_add_i32 s38, 0, 0x10000
	s_add_i32 s39, 0, 0x14000
	s_mov_b32 s37, s14
	v_or_b32_e32 v147, s12, v11
	v_mov_b32_e32 v137, v131
	v_add_u32_e32 v138, v1, v9
	v_mov_b32_e32 v139, v131
	v_mov_b64_e32 v[140:141], 0x480
	v_mov_b64_e32 v[142:143], 0x47f
	v_add_u32_e32 v148, s38, v146
	v_add_u32_e32 v149, s39, v146
	v_add_u32_e32 v150, 0, v0
	s_movk_i32 s40, 0xc00
	v_mov_b32_e32 v151, 0x3e000000
	s_barrier
	s_branch .LBB0_454

.LBB0_456:
	v_readlane_b32 s68, v246, 32
	v_readlane_b32 s69, v246, 33
	s_ashr_i32 s13, s12, 31
	v_readlane_b32 s70, v246, 34
	v_readlane_b32 s71, v246, 35
	s_mov_b64 s[60:61], s[68:69]
	s_lshl_b64 s[14:15], s[12:13], 19
	s_mov_b64 s[62:63], s[70:71]
	s_add_u32 s14, s62, s14
	s_addc_u32 s15, s63, s15
	s_and_b64 s[16:17], s[0:1], exec
	s_cselect_b32 s13, s15, s21
	s_cselect_b32 s42, s14, s20
	s_ashr_i32 s11, s10, 31
	s_lshl_b64 s[16:17], s[10:11], 19
	v_readlane_b32 s24, v246, 36
	v_readlane_b32 s25, v246, 37
	s_add_u32 s16, s24, s16
	s_addc_u32 s17, s25, s17
	s_and_b64 s[24:25], s[0:1], exec
	s_cselect_b32 s11, s17, s23
	s_cselect_b32 s43, s16, s22
	s_add_u32 s20, s20, 0x40080
	s_addc_u32 s21, s21, 0
	s_add_u32 s44, s22, 0x100
	s_addc_u32 s45, s23, 0
	s_mov_b32 s46, -2
	ds_read_b128 v[152:155], v148
	ds_read_b128 v[156:159], v148 offset:1024
	ds_read_b128 v[160:163], v148 offset:2048
	ds_read_b128 v[164:167], v148 offset:3072
	ds_read_b128 v[172:175], v149
	ds_read_b128 v[176:179], v149 offset:1024
	ds_read_b128 v[180:183], v149 offset:2048
	ds_read_b128 v[184:187], v149 offset:3072
	s_add_u32 s22, s20, 0xfffc0080
	s_addc_u32 s23, s21, -1
	s_cmp_eq_u32 s46, 12
	s_cselect_b32 s25, s13, s23
	s_cselect_b32 s24, s42, s22
	s_cselect_b32 s23, s11, s45
	s_cselect_b32 s22, s43, s44
	v_lshl_add_u64 v[168:169], s[20:21], 0, v[136:137]
	s_add_i32 m0, s19, 0xc000
	ds_read_b128 v[188:191], v150
	ds_read_b128 v[192:195], v150 offset:1024
	ds_read_b128 v[196:199], v150 offset:2048
	ds_read_b128 v[200:203], v150 offset:3072
	ds_read_b128 v[204:207], v150 offset:4096
	ds_read_b128 v[208:211], v150 offset:5120
	ds_read_b128 v[212:215], v150 offset:6144
	ds_read_b128 v[216:219], v150 offset:7168
	global_load_lds_dwordx4 v[168:169], off
	v_lshl_add_u64 v[168:169], s[20:21], 0, v[138:139]
	s_add_i32 m0, s19, 0xe000
	s_nop 0
	global_load_lds_dwordx4 v[168:169], off
	s_waitcnt vmcnt(8)
	s_waitcnt lgkmcnt(0)
	s_barrier
	s_waitcnt lgkmcnt(0)
	v_mfma_f32_16x16x32_bf16 v[124:127], v[152:155], v[188:191], 0
	v_mfma_f32_16x16x32_bf16 v[120:123], v[160:163], v[188:191], 0
	v_mfma_f32_16x16x32_bf16 v[116:119], v[152:155], v[196:199], 0
	v_mfma_f32_16x16x32_bf16 v[108:111], v[160:163], v[196:199], 0
	v_mfma_f32_16x16x32_bf16 v[100:103], v[152:155], v[204:207], 0
	v_mfma_f32_16x16x32_bf16 v[92:95], v[160:163], v[204:207], 0
	v_mfma_f32_16x16x32_bf16 v[84:87], v[152:155], v[212:215], 0
	v_mfma_f32_16x16x32_bf16 v[76:79], v[160:163], v[212:215], 0
	v_mfma_f32_16x16x32_bf16 v[124:127], v[156:159], v[192:195], v[124:127]
	v_mfma_f32_16x16x32_bf16 v[120:123], v[164:167], v[192:195], v[120:123]
	v_mfma_f32_16x16x32_bf16 v[116:119], v[156:159], v[200:203], v[116:119]
	v_mfma_f32_16x16x32_bf16 v[108:111], v[164:167], v[200:203], v[108:111]
	v_mfma_f32_16x16x32_bf16 v[100:103], v[156:159], v[208:211], v[100:103]
	v_mfma_f32_16x16x32_bf16 v[92:95], v[164:167], v[208:211], v[92:95]
	v_mfma_f32_16x16x32_bf16 v[84:87], v[156:159], v[216:219], v[84:87]
	v_mfma_f32_16x16x32_bf16 v[76:79], v[164:167], v[216:219], v[76:79]
	v_mfma_f32_16x16x32_bf16 v[112:115], v[172:175], v[188:191], 0
	v_mfma_f32_16x16x32_bf16 v[104:107], v[180:183], v[188:191], 0
	v_mfma_f32_16x16x32_bf16 v[96:99], v[172:175], v[196:199], 0
	v_mfma_f32_16x16x32_bf16 v[88:91], v[180:183], v[196:199], 0
	v_mfma_f32_16x16x32_bf16 v[80:83], v[172:175], v[204:207], 0
	v_mfma_f32_16x16x32_bf16 v[72:75], v[180:183], v[204:207], 0
	v_mfma_f32_16x16x32_bf16 v[68:71], v[172:175], v[212:215], 0
	v_mfma_f32_16x16x32_bf16 v[64:67], v[180:183], v[212:215], 0
	v_mfma_f32_16x16x32_bf16 v[112:115], v[176:179], v[192:195], v[112:115]
	v_mfma_f32_16x16x32_bf16 v[104:107], v[184:187], v[192:195], v[104:107]
	v_mfma_f32_16x16x32_bf16 v[96:99], v[176:179], v[200:203], v[96:99]
	v_mfma_f32_16x16x32_bf16 v[88:91], v[184:187], v[200:203], v[88:91]
	v_mfma_f32_16x16x32_bf16 v[80:83], v[176:179], v[208:211], v[80:83]
	v_mfma_f32_16x16x32_bf16 v[72:75], v[184:187], v[208:211], v[72:75]
	v_mfma_f32_16x16x32_bf16 v[68:71], v[176:179], v[216:219], v[68:71]
	v_mfma_f32_16x16x32_bf16 v[64:67], v[184:187], v[216:219], v[64:67]
	s_barrier
	s_add_i32 s47, s38, s26
	v_lshl_add_u64 v[168:169], s[22:23], 0, v[130:131]
	s_mov_b32 m0, s47
	ds_read_b128 v[188:191], v150 offset:16384
	ds_read_b128 v[192:195], v150 offset:17408
	ds_read_b128 v[196:199], v150 offset:18432
	ds_read_b128 v[200:203], v150 offset:19456
	ds_read_b128 v[204:207], v150 offset:20480
	ds_read_b128 v[208:211], v150 offset:21504
	ds_read_b128 v[212:215], v150 offset:22528
	ds_read_b128 v[216:219], v150 offset:23552
	global_load_lds_dwordx4 v[168:169], off
	s_add_i32 m0, s47, 0x2000
	s_add_u32 s48, s22, 0x40000
	v_lshl_add_u64 v[220:221], s[22:23], 0, v[134:135]
	s_addc_u32 s49, s23, 0
	s_add_i32 s47, s39, s26
	global_load_lds_dwordx4 v[220:221], off
	v_lshl_add_u64 v[222:223], s[48:49], 0, v[130:131]
	s_mov_b32 m0, s47
	v_lshl_add_u64 v[224:225], s[24:25], 0, v[132:133]
	global_load_lds_dwordx4 v[222:223], off
	v_lshl_add_u64 v[222:223], s[48:49], 0, v[134:135]
	s_add_i32 m0, s47, 0x2000
	s_nop 0
	global_load_lds_dwordx4 v[222:223], off
	v_lshl_add_u64 v[222:223], s[24:25], 0, v[128:129]
	s_mov_b32 m0, s19
	s_nop 0
	global_load_lds_dwordx4 v[222:223], off
	s_mov_b32 m0, s29
	s_nop 0
	global_load_lds_dwordx4 v[224:225], off
	s_waitcnt vmcnt(8)
	s_waitcnt lgkmcnt(0)
	s_barrier
	s_waitcnt lgkmcnt(0)
	v_mfma_f32_16x16x32_bf16 v[60:63], v[152:155], v[188:191], 0
	v_mfma_f32_16x16x32_bf16 v[56:59], v[160:163], v[188:191], 0
	v_mfma_f32_16x16x32_bf16 v[52:55], v[152:155], v[196:199], 0
	v_mfma_f32_16x16x32_bf16 v[44:47], v[160:163], v[196:199], 0
	v_mfma_f32_16x16x32_bf16 v[36:39], v[152:155], v[204:207], 0
	v_mfma_f32_16x16x32_bf16 v[28:31], v[160:163], v[204:207], 0
	v_mfma_f32_16x16x32_bf16 v[20:23], v[152:155], v[212:215], 0
	v_mfma_f32_16x16x32_bf16 v[12:15], v[160:163], v[212:215], 0
	v_mfma_f32_16x16x32_bf16 v[60:63], v[156:159], v[192:195], v[60:63]
	v_mfma_f32_16x16x32_bf16 v[56:59], v[164:167], v[192:195], v[56:59]
	v_mfma_f32_16x16x32_bf16 v[52:55], v[156:159], v[200:203], v[52:55]
	v_mfma_f32_16x16x32_bf16 v[44:47], v[164:167], v[200:203], v[44:47]
	v_mfma_f32_16x16x32_bf16 v[36:39], v[156:159], v[208:211], v[36:39]
	v_mfma_f32_16x16x32_bf16 v[28:31], v[164:167], v[208:211], v[28:31]
	v_mfma_f32_16x16x32_bf16 v[20:23], v[156:159], v[216:219], v[20:23]
	v_mfma_f32_16x16x32_bf16 v[12:15], v[164:167], v[216:219], v[12:15]
	v_mfma_f32_16x16x32_bf16 v[48:51], v[172:175], v[188:191], 0
	v_mfma_f32_16x16x32_bf16 v[40:43], v[180:183], v[188:191], 0
	v_mfma_f32_16x16x32_bf16 v[32:35], v[172:175], v[196:199], 0
	v_mfma_f32_16x16x32_bf16 v[24:27], v[180:183], v[196:199], 0
	v_mfma_f32_16x16x32_bf16 v[16:19], v[172:175], v[204:207], 0
	v_mfma_f32_16x16x32_bf16 v[8:11], v[180:183], v[204:207], 0
	v_mfma_f32_16x16x32_bf16 v[4:7], v[172:175], v[212:215], 0
	v_mfma_f32_16x16x32_bf16 v[0:3], v[180:183], v[212:215], 0
	v_mfma_f32_16x16x32_bf16 v[48:51], v[176:179], v[192:195], v[48:51]
	v_mfma_f32_16x16x32_bf16 v[40:43], v[184:187], v[192:195], v[40:43]
	v_mfma_f32_16x16x32_bf16 v[32:35], v[176:179], v[200:203], v[32:35]
	v_mfma_f32_16x16x32_bf16 v[24:27], v[184:187], v[200:203], v[24:27]
	v_mfma_f32_16x16x32_bf16 v[16:19], v[176:179], v[208:211], v[16:19]
	v_mfma_f32_16x16x32_bf16 v[8:11], v[184:187], v[208:211], v[8:11]
	v_mfma_f32_16x16x32_bf16 v[4:7], v[176:179], v[216:219], v[4:7]
	v_mfma_f32_16x16x32_bf16 v[0:3], v[184:187], v[216:219], v[0:3]
	s_barrier
	s_branch .Lpeel457_mid

.LBB0_464:
	s_cmpk_lt_i32 s74, 0x80
	s_cselect_b64 s[0:1], -1, 0
	s_xor_b64 s[4:5], s[92:93], -1
	s_or_b64 s[0:1], s[0:1], s[4:5]
	s_and_b64 vcc, exec, s[0:1]
	s_cbranch_vccnz .LBB0_469
	s_lshl_b32 s0, s74, 9
	v_add_u32_e32 v5, s0, v171
	v_add_u32_e32 v0, 0xffff0000, v5
	s_mov_b32 s0, 0x140000
	v_cmp_gt_i32_e32 vcc, s0, v0
	s_and_saveexec_b64 s[0:1], vcc
	v_readlane_b32 s18, v246, 14
	v_readlane_b32 s19, v246, 15
	v_readlane_b32 s14, v246, 10
	v_readlane_b32 s15, v246, 11
	v_readlane_b32 s16, v246, 12
	v_readlane_b32 s17, v246, 13
	v_readlane_b32 s20, v246, 16
	v_readlane_b32 s21, v246, 17
	v_readlane_b32 s22, v246, 18
	v_readlane_b32 s23, v246, 19
	s_cbranch_execz .LBB0_468
	v_mbcnt_lo_u32_b32 v0, -1, 0
	v_mbcnt_hi_u32_b32 v3, -1, v0
	v_and_b32_e32 v1, 64, v3
	v_xor_b32_e32 v0, 1, v3
	v_add_u32_e32 v4, 64, v1
	v_cmp_lt_i32_e32 vcc, v0, v4
	v_xor_b32_e32 v1, 2, v3
	v_xor_b32_e32 v2, 4, v3
	v_cndmask_b32_e32 v0, v3, v0, vcc
	v_cmp_lt_i32_e32 vcc, v1, v4
	v_xor_b32_e32 v6, 8, v3
	s_add_u32 s4, s76, 0xe000000
	v_cndmask_b32_e32 v1, v3, v1, vcc
	v_cmp_lt_i32_e32 vcc, v2, v4
	s_addc_u32 s5, s77, 0
	v_lshlrev_b32_e32 v0, 2, v0
	v_cndmask_b32_e32 v2, v3, v2, vcc
	v_cmp_lt_i32_e32 vcc, v6, v4
	v_lshlrev_b32_e32 v1, 2, v1
	v_lshlrev_b32_e32 v2, 2, v2
	v_cndmask_b32_e32 v3, v3, v6, vcc
	v_mov_b32_e32 v6, 0xfff80000
	v_lshlrev_b32_e32 v3, 2, v3
	v_add_u32_e32 v4, 0xfffe0000, v5
	v_lshl_add_u32 v5, v5, 3, v6
	s_mov_b64 s[6:7], 0
	v_mov_b32_e32 v6, 0x358637bd
	s_mov_b32 s8, 0x12ffff

.LBB0_530:
	s_cmp_gt_i32 s79, 6
	s_cselect_b64 s[0:1], -1, 0
	s_and_b64 s[2:3], s[36:37], s[0:1]
	s_andn2_b64 vcc, exec, s[2:3]
	v_readlane_b32 s54, v246, 14
	v_readlane_b32 s55, v246, 15
	s_cbranch_vccnz .LBB0_580
	s_waitcnt vmcnt(0)
	v_cmp_eq_u32_e32 vcc, 0, v171
	s_waitcnt vmcnt(0)
	s_barrier
	s_and_saveexec_b64 s[2:3], vcc
	s_cbranch_execz .LBB0_579
	s_add_i32 s4, 0, 0x20000
	v_mov_b32_e32 v0, s4
	s_waitcnt vmcnt(0) expcnt(0) lgkmcnt(0)
	ds_read_b32 v2, v0
	s_add_i32 s4, 0, 0x20004
	v_mov_b32_e32 v0, s4
	ds_read_b32 v0, v0
	s_waitcnt lgkmcnt(1)
	v_cmp_ne_u32_e32 vcc, 0, v2
	s_cbranch_vccnz .LBB0_547
	v_readlane_b32 s6, v246, 48
	v_readlane_b32 s4, v246, 0
	v_readlane_b32 s7, v246, 49
	s_mul_i32 s33, s7, s4
	s_add_u32 s4, s76, 0x280200
	s_addc_u32 s5, s77, 0
	s_mul_i32 s33, s33, s6
	s_add_u32 s6, s76, 0x280400
	s_addc_u32 s7, s77, 0
	s_add_u32 s8, s76, 0x280500
	s_addc_u32 s9, s77, 0
	s_add_u32 s10, s76, 0x280600
	s_addc_u32 s11, s77, 0
	s_add_u32 s12, s76, 0x280700
	s_addc_u32 s13, s77, 0
	s_add_u32 s14, s76, 0x280800
	s_addc_u32 s15, s77, 0
	s_add_u32 s16, s76, 0x280900
	s_addc_u32 s17, s77, 0
	s_add_u32 s18, s76, 0x280a00
	s_addc_u32 s19, s77, 0
	s_add_u32 s20, s76, 0x280b00
	s_addc_u32 s21, s77, 0
	s_add_u32 s22, s76, 0x280c00
	s_addc_u32 s23, s77, 0
	s_add_u32 s24, s76, 0x280d00
	s_addc_u32 s25, s77, 0
	s_add_u32 s26, s76, 0x280e00
	s_addc_u32 s27, s77, 0
	s_add_u32 s28, s76, 0x280f00
	s_addc_u32 s29, s77, 0
	s_add_u32 s36, s76, 0x281000
	s_addc_u32 s37, s77, 0
	s_add_u32 s38, s76, 0x281100
	s_addc_u32 s39, s77, 0
	s_add_u32 s40, s76, 0x281200
	s_addc_u32 s41, s77, 0
	s_add_u32 s42, s76, 0x281300
	s_addc_u32 s43, s77, 0
	s_mov_b32 s50, 1
	v_mov_b32_e32 v16, 0
	s_branch .LBB0_535

.LBB0_580:
	s_cmp_lt_i32 s78, 7
	s_cselect_b64 s[2:3], -1, 0
	s_and_b64 s[2:3], s[2:3], s[0:1]
	s_andn2_b64 vcc, exec, s[2:3]
	s_cbranch_vccnz .LBB0_588
	v_readlane_b32 s0, v246, 48
	v_lshl_add_u32 v6, s74, 9, v171
	s_lshl_b32 s8, s0, 9
	s_mov_b32 s0, 0x100000
	v_cmp_gt_i32_e32 vcc, s0, v6
	s_and_saveexec_b64 s[0:1], vcc
	s_cbranch_execz .LBB0_584
	v_lshrrev_b32_e32 v8, 3, v170
	v_mov_b32_e32 v1, 0
	v_lshlrev_b32_e32 v0, 4, v170
	v_lshl_add_u64 v[2:3], s[94:95], 0, v[0:1]
	v_lshl_add_u64 v[4:5], s[30:31], 0, v[0:1]
	s_mov_b64 s[4:5], 0
	v_lshlrev_b32_e32 v0, 2, v8
	s_movk_i32 s6, 0xc00
	s_mov_b32 s7, 0xfffff
	v_mov_b32_e32 v7, v6

.LBB0_584:
	s_or_b64 exec, exec, s[0:1]
	s_and_b64 s[0:1], s[92:93], exec
	s_cselect_b32 s0, 0x140000, 0
	v_add_u32_e32 v0, s0, v6
	s_mov_b32 s0, 0x200000
	v_cmp_gt_i32_e32 vcc, s0, v0
	s_and_saveexec_b64 s[0:1], vcc
	s_cbranch_execz .LBB0_587
	v_mbcnt_lo_u32_b32 v1, -1, 0
	v_mbcnt_hi_u32_b32 v4, -1, v1
	v_and_b32_e32 v2, 64, v4
	v_xor_b32_e32 v1, 1, v4
	v_add_u32_e32 v5, 64, v2
	v_cmp_lt_i32_e32 vcc, v1, v5
	v_xor_b32_e32 v2, 2, v4
	v_xor_b32_e32 v3, 4, v4
	v_cndmask_b32_e32 v1, v4, v1, vcc
	v_cmp_lt_i32_e32 vcc, v2, v5
	v_xor_b32_e32 v6, 8, v4
	v_readlane_b32 s6, v246, 48
	v_cndmask_b32_e32 v2, v4, v2, vcc
	v_cmp_lt_i32_e32 vcc, v3, v5
	s_add_u32 s4, s76, 0xe000000
	s_nop 0
	v_cndmask_b32_e32 v3, v4, v3, vcc
	v_cmp_lt_i32_e32 vcc, v6, v5
	s_addc_u32 s5, s77, 0
	v_lshlrev_b32_e32 v1, 2, v1
	v_cndmask_b32_e32 v4, v4, v6, vcc
	v_lshlrev_b32_e32 v2, 2, v2
	v_lshlrev_b32_e32 v3, 2, v3
	v_lshlrev_b32_e32 v4, 2, v4
	v_lshlrev_b32_e32 v5, 3, v0
	s_lshl_b32 s9, s6, 12
	s_mov_b64 s[6:7], 0
	v_mov_b32_e32 v6, 0x358637bd
	s_mov_b32 s10, 0x1fffff

.LBB0_638:
	s_cmp_lt_i32 s78, 8
	s_cselect_b64 s[2:3], -1, 0
	s_and_b64 s[4:5], s[2:3], s[0:1]
	s_andn2_b64 vcc, exec, s[4:5]
	v_bfe_u32 v175, v171, 2, 4
	v_lshlrev_b32_e32 v176, 4, v171
	v_and_b32_e32 v178, 32, v171
	v_and_b32_e32 v173, 64, v171
	v_lshrrev_b32_e32 v177, 3, v171
	v_and_b32_e32 v172, 15, v171
	v_lshlrev_b32_e32 v174, 2, v171
	s_cbranch_vccnz .LBB0_693
	v_lshrrev_b32_e32 v0, 5, v171
	v_lshrrev_b32_e32 v2, 1, v171
	s_add_u32 s6, s76, 0x7000000
	v_and_b32_e32 v0, 4, v0
	v_bfe_u32 v1, v171, 2, 2
	v_and_b32_e32 v181, 24, v2
	s_movk_i32 s0, 0x70
	s_addc_u32 s7, s77, 0
	v_or3_b32 v0, v0, v1, v181
	v_and_or_b32 v148, v177, s0, v175
	s_movk_i32 s0, 0x60
	v_add_u32_e32 v180, 0x2000, v176
	v_and_or_b32 v150, v177, s0, v0
	v_lshrrev_b32_e32 v1, 7, v180
	s_movk_i32 s0, 0xf0
	s_cmpk_lt_i32 s74, 0x100
	v_and_or_b32 v151, v1, s0, v175
	s_movk_i32 s0, 0xe0
	s_cselect_b64 s[2:3], -1, 0
	s_ashr_i32 s33, s74, 31
	v_and_or_b32 v153, v1, s0, v0
	s_lshr_b32 s0, s33, 29
	s_add_i32 s0, s74, s0
	s_ashr_i32 s36, s0, 3
	s_and_b32 s0, s0, -8
	s_sub_i32 s39, s74, s0
	v_bitop3_b32 v179, v176, v178, 48 bitop3:0x6c
	v_lshlrev_b32_e32 v0, 6, v171
	s_cmp_lt_i32 s39, 0
	v_or_b32_e32 v149, v179, v173
	v_lshlrev_b32_e32 v182, 1, v181
	v_and_b32_e32 v0, 0x3c0, v0
	v_and_b32_e32 v1, 32, v174
	s_cselect_b64 s[8:9], -1, 0
	s_lshl_b32 s37, s39, 5
	v_mov_b32_e32 v143, 0
	v_lshl_or_b32 v140, v148, 11, v149
	v_lshl_or_b32 v142, v150, 11, v149
	v_lshl_or_b32 v144, v151, 11, v149
	v_lshl_or_b32 v146, v153, 11, v149
	v_bitop3_b32 v183, v182, v1, v0 bitop3:0x36
	s_cmpk_gt_i32 s74, 0xff
	v_mov_b32_e32 v147, v143
	v_mov_b32_e32 v141, v143
	v_mov_b32_e32 v145, v143
	s_mul_i32 s39, s39, 33
	v_readfirstlane_b32 s14, v171
	s_cbranch_scc1 .LBB0_653
	s_add_u32 s38, s76, 0x1600000
	s_addc_u32 s40, s77, 0
	s_lshr_b32 s12, s14, 6
	s_lshr_b32 s15, s14, 8
	s_lshl_b32 s41, s12, 10
	s_and_b64 s[0:1], s[8:9], exec
	s_cselect_b32 s0, s39, s37
	s_add_i32 s0, s0, s36
	s_ashr_i32 s1, s0, 31
	s_lshr_b32 s1, s1, 27
	s_add_i32 s10, s0, s1
	s_ashr_i32 s1, s10, 5
	s_andn2_b32 s10, s10, 31
	s_sub_i32 s16, s0, s10
	s_bfe_i32 s0, s16, 0x80000
	s_bfe_u32 s0, s0, 0x3000c
	s_add_i32 s10, s16, s0
	s_bfe_i32 s0, s10, 0x80000
	s_and_b32 s10, s10, 0xf8
	s_sub_i32 s10, s16, s10
	s_lshl_b32 s1, s1, 3
	s_sext_i32_i16 s0, s0
	s_sext_i32_i8 s10, s10
	s_lshr_b32 s0, s0, 3
	s_add_i32 s24, s1, s10
	s_ashr_i32 s25, s24, 31
	s_bfe_i64 s[18:19], s[0:1], 0x100000
	s_lshl_b64 s[10:11], s[24:25], 19
	s_lshl_b64 s[18:19], s[18:19], 19
	s_add_u32 s28, s38, s18
	s_addc_u32 s29, s40, s19
	s_add_i32 s25, s41, 0
	s_add_i32 m0, s25, 0x10000
	v_lshl_add_u64 v[0:1], s[28:29], 0, v[142:143]
	global_load_lds_dwordx4 v[0:1], off
	s_add_i32 m0, s25, 0x12000
	s_add_u32 s18, s28, 0x40000
	v_lshl_add_u64 v[2:3], s[28:29], 0, v[146:147]
	s_addc_u32 s19, s29, 0
	v_readlane_b32 s56, v246, 32
	v_readlane_b32 s57, v246, 33
	global_load_lds_dwordx4 v[2:3], off
	s_add_i32 m0, s25, 0x14000
	v_lshl_add_u64 v[4:5], s[18:19], 0, v[142:143]
	v_readlane_b32 s58, v246, 34
	v_readlane_b32 s59, v246, 35
	s_mov_b64 s[52:53], s[56:57]
	global_load_lds_dwordx4 v[4:5], off
	s_add_i32 m0, s25, 0x16000
	s_mov_b64 s[54:55], s[58:59]
	s_add_u32 s26, s54, s10
	v_lshl_add_u64 v[4:5], s[18:19], 0, v[146:147]
	s_addc_u32 s27, s55, s11
	s_add_i32 s42, s25, 0x2000
	global_load_lds_dwordx4 v[4:5], off
	v_lshl_add_u64 v[6:7], s[26:27], 0, v[140:141]
	s_mov_b32 m0, s25
	s_add_u32 s10, s26, 0x40000
	global_load_lds_dwordx4 v[6:7], off
	v_lshl_add_u64 v[4:5], s[26:27], 0, v[144:145]
	s_mov_b32 m0, s42
	s_addc_u32 s11, s27, 0
	s_add_i32 s43, s25, 0x4000
	global_load_lds_dwordx4 v[4:5], off
	v_lshl_add_u64 v[8:9], s[10:11], 0, v[140:141]
	s_mov_b32 m0, s43
	s_add_i32 s44, s25, 0x6000
	global_load_lds_dwordx4 v[8:9], off
	v_lshl_add_u64 v[8:9], s[10:11], 0, v[144:145]
	s_mov_b32 m0, s44
	s_cmp_eq_u32 s15, 1
	global_load_lds_dwordx4 v[8:9], off
	s_cselect_b64 s[10:11], -1, 0
	s_cmp_lg_u32 s15, 1
	s_cbranch_scc1 .LBB0_642
	s_barrier

.LBB0_645:
	v_readlane_b32 s64, v246, 32
	v_readlane_b32 s65, v246, 33
	s_ashr_i32 s17, s16, 31
	v_readlane_b32 s66, v246, 34
	v_readlane_b32 s67, v246, 35
	s_mov_b64 s[60:61], s[64:65]
	s_andn2_b64 vcc, exec, s[34:35]
	s_lshl_b64 s[20:21], s[16:17], 19
	s_mov_b64 s[62:63], s[66:67]
	s_add_u32 s20, s62, s20
	s_addc_u32 s21, s63, s21
	s_and_b64 s[22:23], s[34:35], exec
	s_cselect_b32 s17, s21, s27
	s_cselect_b32 s50, s20, s26
	s_ashr_i32 s19, s18, 31
	s_lshl_b64 s[22:23], s[18:19], 19
	s_add_u32 s22, s38, s22
	s_addc_u32 s23, s40, s23
	v_cndmask_b32_e64 v0, 0, 1, s[34:35]
	s_and_b64 s[34:35], s[34:35], exec
	s_cselect_b32 s19, s23, s29
	s_cselect_b32 s51, s22, s28
	s_add_u32 s26, s26, 0x40080
	s_addc_u32 s27, s27, 0
	v_cmp_ne_u32_e64 s[0:1], 1, v0
	s_add_u32 s52, s28, 0x100
	s_addc_u32 s53, s29, 0
	s_mov_b32 s54, -2
	ds_read_b128 v[134:137], v156
	ds_read_b128 v[160:163], v156 offset:1024
	ds_read_b128 v[164:167], v156 offset:2048
	ds_read_b128 v[184:187], v156 offset:3072
	ds_read_b128 v[188:191], v157
	ds_read_b128 v[192:195], v157 offset:1024
	ds_read_b128 v[196:199], v157 offset:2048
	ds_read_b128 v[200:203], v157 offset:3072
	s_add_u32 s28, s26, 0xfffc0080
	s_addc_u32 s29, s27, -1
	s_cmp_eq_u32 s54, 12
	s_cselect_b32 s35, s17, s29
	s_cselect_b32 s34, s50, s28
	s_cselect_b32 s29, s19, s53
	s_cselect_b32 s28, s51, s52
	v_lshl_add_u64 v[138:139], s[26:27], 0, v[128:129]
	s_add_i32 m0, s25, 0xc000
	ds_read_b128 v[204:207], v158
	ds_read_b128 v[208:211], v158 offset:1024
	ds_read_b128 v[212:215], v158 offset:2048
	ds_read_b128 v[216:219], v158 offset:3072
	ds_read_b128 v[220:223], v158 offset:4096
	ds_read_b128 v[224:227], v158 offset:5120
	ds_read_b128 v[228:231], v158 offset:6144
	ds_read_b128 v[232:235], v158 offset:7168
	global_load_lds_dwordx4 v[138:139], off
	v_lshl_add_u64 v[138:139], s[26:27], 0, v[132:133]
	s_add_i32 m0, s25, 0xe000
	s_nop 0
	global_load_lds_dwordx4 v[138:139], off
	s_waitcnt vmcnt(8)
	s_waitcnt lgkmcnt(0)
	s_barrier
	s_waitcnt lgkmcnt(0)
	v_mfma_f32_16x16x32_bf16 v[124:127], v[134:137], v[204:207], 0
	v_mfma_f32_16x16x32_bf16 v[120:123], v[164:167], v[204:207], 0
	v_mfma_f32_16x16x32_bf16 v[108:111], v[134:137], v[212:215], 0
	v_mfma_f32_16x16x32_bf16 v[104:107], v[164:167], v[212:215], 0
	v_mfma_f32_16x16x32_bf16 v[92:95], v[134:137], v[220:223], 0
	v_mfma_f32_16x16x32_bf16 v[88:91], v[164:167], v[220:223], 0
	v_mfma_f32_16x16x32_bf16 v[76:79], v[134:137], v[228:231], 0
	v_mfma_f32_16x16x32_bf16 v[72:75], v[164:167], v[228:231], 0
	v_mfma_f32_16x16x32_bf16 v[124:127], v[160:163], v[208:211], v[124:127]
	v_mfma_f32_16x16x32_bf16 v[120:123], v[184:187], v[208:211], v[120:123]
	v_mfma_f32_16x16x32_bf16 v[108:111], v[160:163], v[216:219], v[108:111]
	v_mfma_f32_16x16x32_bf16 v[104:107], v[184:187], v[216:219], v[104:107]
	v_mfma_f32_16x16x32_bf16 v[92:95], v[160:163], v[224:227], v[92:95]
	v_mfma_f32_16x16x32_bf16 v[88:91], v[184:187], v[224:227], v[88:91]
	v_mfma_f32_16x16x32_bf16 v[76:79], v[160:163], v[232:235], v[76:79]
	v_mfma_f32_16x16x32_bf16 v[72:75], v[184:187], v[232:235], v[72:75]
	v_mfma_f32_16x16x32_bf16 v[116:119], v[188:191], v[204:207], 0
	v_mfma_f32_16x16x32_bf16 v[112:115], v[196:199], v[204:207], 0
	v_mfma_f32_16x16x32_bf16 v[100:103], v[188:191], v[212:215], 0
	v_mfma_f32_16x16x32_bf16 v[96:99], v[196:199], v[212:215], 0
	v_mfma_f32_16x16x32_bf16 v[84:87], v[188:191], v[220:223], 0
	v_mfma_f32_16x16x32_bf16 v[80:83], v[196:199], v[220:223], 0
	v_mfma_f32_16x16x32_bf16 v[68:71], v[188:191], v[228:231], 0
	v_mfma_f32_16x16x32_bf16 v[64:67], v[196:199], v[228:231], 0
	v_mfma_f32_16x16x32_bf16 v[116:119], v[192:195], v[208:211], v[116:119]
	v_mfma_f32_16x16x32_bf16 v[112:115], v[200:203], v[208:211], v[112:115]
	v_mfma_f32_16x16x32_bf16 v[100:103], v[192:195], v[216:219], v[100:103]
	v_mfma_f32_16x16x32_bf16 v[96:99], v[200:203], v[216:219], v[96:99]
	v_mfma_f32_16x16x32_bf16 v[84:87], v[192:195], v[224:227], v[84:87]
	v_mfma_f32_16x16x32_bf16 v[80:83], v[200:203], v[224:227], v[80:83]
	v_mfma_f32_16x16x32_bf16 v[68:71], v[192:195], v[232:235], v[68:71]
	v_mfma_f32_16x16x32_bf16 v[64:67], v[200:203], v[232:235], v[64:67]
	s_barrier
	s_add_i32 s55, s47, s41
	v_lshl_add_u64 v[138:139], s[28:29], 0, v[142:143]
	s_mov_b32 m0, s55
	ds_read_b128 v[204:207], v158 offset:16384
	ds_read_b128 v[208:211], v158 offset:17408
	ds_read_b128 v[212:215], v158 offset:18432
	ds_read_b128 v[216:219], v158 offset:19456
	ds_read_b128 v[220:223], v158 offset:20480
	ds_read_b128 v[224:227], v158 offset:21504
	ds_read_b128 v[228:231], v158 offset:22528
	ds_read_b128 v[232:235], v158 offset:23552
	global_load_lds_dwordx4 v[138:139], off
	s_add_i32 m0, s55, 0x2000
	s_add_u32 s56, s28, 0x40000
	v_lshl_add_u64 v[168:169], s[28:29], 0, v[146:147]
	s_addc_u32 s57, s29, 0
	s_add_i32 s55, s48, s41
	global_load_lds_dwordx4 v[168:169], off
	v_lshl_add_u64 v[236:237], s[56:57], 0, v[142:143]
	s_mov_b32 m0, s55
	v_lshl_add_u64 v[238:239], s[34:35], 0, v[144:145]
	global_load_lds_dwordx4 v[236:237], off
	v_lshl_add_u64 v[236:237], s[56:57], 0, v[146:147]
	s_add_i32 m0, s55, 0x2000
	s_nop 0
	global_load_lds_dwordx4 v[236:237], off
	v_lshl_add_u64 v[236:237], s[34:35], 0, v[140:141]
	s_mov_b32 m0, s25
	s_nop 0
	global_load_lds_dwordx4 v[236:237], off
	s_mov_b32 m0, s42
	s_nop 0
	global_load_lds_dwordx4 v[238:239], off
	s_waitcnt vmcnt(8)
	s_waitcnt lgkmcnt(0)
	s_barrier
	s_waitcnt lgkmcnt(0)
	v_mfma_f32_16x16x32_bf16 v[60:63], v[134:137], v[204:207], 0
	v_mfma_f32_16x16x32_bf16 v[56:59], v[164:167], v[204:207], 0
	v_mfma_f32_16x16x32_bf16 v[44:47], v[134:137], v[212:215], 0
	v_mfma_f32_16x16x32_bf16 v[40:43], v[164:167], v[212:215], 0
	v_mfma_f32_16x16x32_bf16 v[28:31], v[134:137], v[220:223], 0
	v_mfma_f32_16x16x32_bf16 v[24:27], v[164:167], v[220:223], 0
	v_mfma_f32_16x16x32_bf16 v[12:15], v[134:137], v[228:231], 0
	v_mfma_f32_16x16x32_bf16 v[8:11], v[164:167], v[228:231], 0
	v_mfma_f32_16x16x32_bf16 v[60:63], v[160:163], v[208:211], v[60:63]
	v_mfma_f32_16x16x32_bf16 v[56:59], v[184:187], v[208:211], v[56:59]
	v_mfma_f32_16x16x32_bf16 v[44:47], v[160:163], v[216:219], v[44:47]
	v_mfma_f32_16x16x32_bf16 v[40:43], v[184:187], v[216:219], v[40:43]
	v_mfma_f32_16x16x32_bf16 v[28:31], v[160:163], v[224:227], v[28:31]
	v_mfma_f32_16x16x32_bf16 v[24:27], v[184:187], v[224:227], v[24:27]
	v_mfma_f32_16x16x32_bf16 v[12:15], v[160:163], v[232:235], v[12:15]
	v_mfma_f32_16x16x32_bf16 v[8:11], v[184:187], v[232:235], v[8:11]
	v_mfma_f32_16x16x32_bf16 v[52:55], v[188:191], v[204:207], 0
	v_mfma_f32_16x16x32_bf16 v[48:51], v[196:199], v[204:207], 0
	v_mfma_f32_16x16x32_bf16 v[36:39], v[188:191], v[212:215], 0
	v_mfma_f32_16x16x32_bf16 v[32:35], v[196:199], v[212:215], 0
	v_mfma_f32_16x16x32_bf16 v[20:23], v[188:191], v[220:223], 0
	v_mfma_f32_16x16x32_bf16 v[16:19], v[196:199], v[220:223], 0
	v_mfma_f32_16x16x32_bf16 v[4:7], v[188:191], v[228:231], 0
	v_mfma_f32_16x16x32_bf16 v[0:3], v[196:199], v[228:231], 0
	v_mfma_f32_16x16x32_bf16 v[52:55], v[192:195], v[208:211], v[52:55]
	v_mfma_f32_16x16x32_bf16 v[48:51], v[200:203], v[208:211], v[48:51]
	v_mfma_f32_16x16x32_bf16 v[36:39], v[192:195], v[216:219], v[36:39]
	v_mfma_f32_16x16x32_bf16 v[32:35], v[200:203], v[216:219], v[32:35]
	v_mfma_f32_16x16x32_bf16 v[20:23], v[192:195], v[224:227], v[20:23]
	v_mfma_f32_16x16x32_bf16 v[16:19], v[200:203], v[224:227], v[16:19]
	v_mfma_f32_16x16x32_bf16 v[4:7], v[192:195], v[232:235], v[4:7]
	v_mfma_f32_16x16x32_bf16 v[0:3], v[200:203], v[232:235], v[0:3]
	s_barrier
	s_branch .Lpeel646_mid

.LBB0_653:
	v_readlane_b32 s0, v246, 48
	v_cndmask_b32_e64 v0, 0, 1, s[2:3]
	s_ashr_i32 s38, s0, 31
	v_cmp_ne_u32_e64 s[0:1], 1, v0
	s_andn2_b64 vcc, exec, s[2:3]
	v_readfirstlane_b32 s3, v171
	s_cbranch_vccnz .LBB0_673
	s_lshr_b32 s12, s3, 6
	s_lshr_b32 s14, s3, 8
	s_lshl_b32 s40, s12, 10
	s_and_b64 s[10:11], s[8:9], exec
	s_cselect_b32 s2, s39, s37
	s_add_i32 s2, s2, s36
	s_ashr_i32 s10, s2, 31
	s_lshr_b32 s10, s10, 27
	s_add_i32 s10, s2, s10
	s_ashr_i32 s11, s10, 5
	s_andn2_b32 s10, s10, 31
	s_sub_i32 s10, s2, s10
	s_bfe_i32 s2, s10, 0x80000
	s_bfe_u32 s2, s2, 0x3000c
	s_add_i32 s13, s10, s2
	s_bfe_i32 s2, s13, 0x80000
	s_and_b32 s13, s13, 0xf8
	s_sub_i32 s10, s10, s13
	s_lshl_b32 s11, s11, 3
	s_sext_i32_i16 s2, s2
	s_sext_i32_i8 s10, s10
	s_lshr_b32 s2, s2, 3
	s_add_i32 s24, s11, s10
	s_ashr_i32 s25, s24, 31
	s_bfe_i64 s[16:17], s[2:3], 0x100000
	s_lshl_b64 s[10:11], s[24:25], 18
	s_lshl_b64 s[16:17], s[16:17], 18
	v_readlane_b32 s18, v246, 38
	v_readlane_b32 s19, v246, 39
	s_add_u32 s28, s18, s16
	s_addc_u32 s29, s19, s17
	s_add_i32 s25, s40, 0
	v_lshl_or_b32 v150, v150, 10, v149
	s_add_i32 m0, s25, 0x10000
	v_lshl_or_b32 v154, v153, 10, v149
	global_load_lds_dwordx4 v150, s[28:29]
	s_add_i32 m0, s25, 0x12000
	s_add_u32 s16, s28, 0x20000
	global_load_lds_dwordx4 v154, s[28:29]
	s_addc_u32 s17, s29, 0
	s_add_i32 m0, s25, 0x14000
	v_lshl_or_b32 v148, v148, 10, v149
	global_load_lds_dwordx4 v150, s[16:17]
	s_add_i32 m0, s25, 0x16000
	s_add_u32 s26, s30, s10
	s_addc_u32 s27, s31, s11
	s_add_i32 s41, s25, 0x2000
	global_load_lds_dwordx4 v154, s[16:17]
	s_mov_b32 m0, s25
	s_add_u32 s10, s26, 0x20000
	v_lshl_or_b32 v152, v151, 10, v149
	global_load_lds_dwordx4 v148, s[26:27]
	s_mov_b32 m0, s41
	s_addc_u32 s11, s27, 0
	s_add_i32 s42, s25, 0x4000
	global_load_lds_dwordx4 v152, s[26:27]
	s_mov_b32 m0, s42
	s_add_i32 s43, s25, 0x6000
	global_load_lds_dwordx4 v148, s[10:11]
	s_mov_b32 m0, s43
	v_mov_b32_e32 v151, 0
	global_load_lds_dwordx4 v152, s[10:11]
	v_mov_b32_e32 v155, v151
	v_mov_b32_e32 v149, v151
	v_mov_b32_e32 v153, v151
	s_cmp_eq_u32 s14, 1
	s_mov_b32 s44, 0
	v_lshl_add_u64 v[6:7], s[28:29], 0, v[150:151]
	v_lshl_add_u64 v[4:5], s[28:29], 0, v[154:155]
	v_lshl_add_u64 v[0:1], s[26:27], 0, v[148:149]
	s_cselect_b64 s[10:11], -1, 0
	s_cmp_lg_u32 s14, 1
	v_lshl_add_u64 v[2:3], s[26:27], 0, v[152:153]
	s_cbranch_scc1 .LBB0_656
	s_barrier

.LBB0_659:
	s_add_i32 s44, s44, 1
	v_readlane_b32 s20, v246, 48
	s_mul_i32 s2, s44, s38
	s_mul_hi_u32 s3, s44, s20
	s_add_i32 s3, s3, s2
	s_mul_i32 s2, s44, s20
	s_add_u32 s20, s2, s74
	s_addc_u32 s21, s3, s33
	v_cmp_gt_i64_e32 vcc, s[20:21], v[162:163]
	v_cmp_lt_i64_e64 s[2:3], s[20:21], v[160:161]
	s_cbranch_vccnz .LBB0_665
	s_ashr_i32 s16, s20, 31
	s_lshr_b32 s16, s16, 29
	s_add_i32 s18, s20, s16
	s_and_b32 s16, s18, -8
	s_sub_i32 s19, s20, s16
	s_cmp_gt_i32 s19, -1
	s_mov_b64 s[16:17], -1
	s_cbranch_scc0 .LBB0_662
	s_lshl_b32 s20, s19, 5
	s_mov_b64 s[16:17], 0

.LBB0_679:
	s_add_i32 s43, s43, 1
	v_readlane_b32 s24, v246, 48
	s_mul_i32 s0, s43, s38
	s_mul_hi_u32 s1, s43, s24
	s_add_i32 s1, s1, s0
	s_mul_i32 s0, s43, s24
	s_add_u32 s24, s0, s74
	s_addc_u32 s25, s1, s33
	v_cmp_gt_i64_e32 vcc, s[24:25], v[134:135]
	v_cmp_lt_i64_e64 s[0:1], s[24:25], v[132:133]
	s_cbranch_vccnz .LBB0_685
	s_ashr_i32 s20, s24, 31
	s_lshr_b32 s20, s20, 29
	s_add_i32 s22, s24, s20
	s_and_b32 s20, s22, -8
	s_sub_i32 s23, s24, s20
	s_cmp_gt_i32 s23, -1
	s_mov_b64 s[20:21], -1
	s_cbranch_scc0 .LBB0_682
	s_lshl_b32 s24, s23, 5
	s_mov_b64 s[20:21], 0

.LBB0_748:
	s_lshl_b32 s12, s12, 5
	s_and_b32 s16, s12, 0x60
	s_mov_b64 s[12:13], 0x80
	v_readlane_b32 s22, v246, 48
	s_add_i32 m0, s31, 0x18000
	v_lshl_add_u64 v[0:1], v[0:1], 0, s[12:13]
	s_lshl_b32 s15, s14, 13
	s_lshl_b32 s20, s16, 7
	s_ashr_i32 s47, s22, 31
	global_load_lds_dwordx4 v[0:1], off
	v_lshl_add_u64 v[0:1], v[2:3], 0, s[12:13]
	s_add_i32 m0, s31, 0x1a000
	s_add_i32 s48, s31, 0x8000
	s_add_i32 s49, s31, 0xa000
	global_load_lds_dwordx4 v[0:1], off
	v_lshl_add_u64 v[0:1], v[6:7], 0, s[12:13]
	s_mov_b32 m0, s48
	s_add_u32 s18, s36, 0x40080
	global_load_lds_dwordx4 v[0:1], off
	v_lshl_add_u64 v[0:1], v[4:5], 0, s[12:13]
	s_mov_b32 m0, s49
	s_addc_u32 s19, s37, 0
	global_load_lds_dwordx4 v[0:1], off
	s_add_i32 m0, s31, 0x1c000
	v_lshl_add_u64 v[0:1], s[18:19], 0, v[128:129]
	global_load_lds_dwordx4 v[0:1], off
	v_lshl_add_u64 v[0:1], s[18:19], 0, v[130:131]
	s_add_i32 m0, s31, 0x1e000
	s_sext_i32_i8 s53, s2
	global_load_lds_dwordx4 v[0:1], off
	s_waitcnt vmcnt(8)
	s_barrier
	v_bfe_u32 v0, v171, 4, 2
	v_lshlrev_b32_e32 v1, 4, v0
	v_lshlrev_b32_e32 v2, 6, v171
	s_movk_i32 s2, 0x3c0
	v_and_or_b32 v2, v2, s2, v1
	v_lshl_or_b32 v182, v0, 2, s16
	v_lshlrev_b32_e32 v0, 8, v171
	v_bitop3_b32 v181, s20, v2, v180 bitop3:0xf6
	v_and_b32_e32 v0, 0x38000, v0
	v_lshlrev_b32_e32 v2, 11, v175
	v_or3_b32 v0, v168, v0, v2
	v_lshlrev_b32_e32 v3, 2, v172
	v_add_u32_e32 v132, v0, v173
	v_lshlrev_b32_e32 v0, 4, v169
	v_lshl_or_b32 v1, v172, 6, v1
	v_and_b32_e32 v3, 32, v3
	s_waitcnt vmcnt(6)
	s_cmpk_lt_u32 s3, 0x100
	v_and_b32_e32 v0, 0x78000, v0
	v_lshl_or_b32 v179, s14, 6, v172
	v_bitop3_b32 v1, v1, s15, v3 bitop3:0xde
	s_cselect_b64 s[14:15], -1, 0
	v_mov_b32_e32 v133, 0
	v_or3_b32 v0, v168, v0, v2
	s_add_i32 s51, 0, 0x10000
	s_add_i32 s52, 0, 0x14000
	s_mov_b32 s50, s22
	v_add_u32_e32 v134, v0, v173
	v_mov_b32_e32 v135, v133
	v_mov_b64_e32 v[136:137], 0x100
	v_mov_b64_e32 v[138:139], 0xff
	v_add_u32_e32 v183, s51, v181
	v_add_u32_e32 v184, s52, v181
	v_add_u32_e32 v185, 0, v1
	s_mov_b32 s16, 0x3f9837f0
	s_mov_b64 s[18:19], 0xa0000
	s_mov_b64 s[20:21], 0xb0000
	s_barrier
	s_branch .LBB0_751

.LBB0_761:
	v_lshl_or_b32 v164, s53, 8, v182
	v_ashrrev_i32_e32 v165, 31, v164
	v_readlane_b32 s56, v246, 4
	v_lshl_add_u32 v166, s30, 8, v179
	v_lshlrev_b64 v[140:141], 2, v[164:165]
	v_readlane_b32 s58, v246, 6
	v_readlane_b32 s59, v246, 7
	v_readlane_b32 s60, v246, 8
	v_readlane_b32 s61, v246, 9
	v_ashrrev_i32_e32 v167, 31, v166
	v_lshl_add_u64 v[142:143], s[58:59], 0, v[140:141]
	v_lshl_add_u64 v[156:157], s[60:61], 0, v[140:141]
	v_lshl_add_u64 v[140:141], v[166:167], 3, s[76:77]
	global_load_dwordx4 v[144:147], v[142:143], off
	global_load_dwordx4 v[148:151], v[156:157], off
	global_load_dwordx2 v[206:207], v[140:141], off
	v_lshlrev_b64 v[152:153], 10, v[166:167]
	v_lshl_add_u64 v[152:153], v[152:153], 0, v[164:165]
	v_readlane_b32 s57, v246, 5
	v_lshlrev_b64 v[158:159], 2, v[152:153]
	v_lshl_add_u64 v[210:211], s[72:73], 0, v[158:159]
	v_lshl_add_u64 v[208:209], s[56:57], 0, v[158:159]
	global_load_dwordx4 v[152:155], v[208:209], off
	global_load_dwordx4 v[160:163], v[142:143], off offset:64
	global_load_dwordx4 v[186:189], v[156:157], off offset:64
	global_load_dwordx4 v[190:193], v[142:143], off offset:512
	global_load_dwordx4 v[194:197], v[142:143], off offset:576
	global_load_dwordx4 v[198:201], v[156:157], off offset:512
	global_load_dwordx4 v[202:205], v[156:157], off offset:576
	s_mov_b64 s[34:35], 0x80000
	s_andn2_b64 vcc, exec, s[2:3]
	s_mov_b64 s[2:3], -1
	v_readlane_b32 s68, v246, 16
	v_readlane_b32 s69, v246, 17
	s_waitcnt vmcnt(0)
	v_pk_mul_f32 v[142:143], v[146:147], s[16:17] op_sel_hi:[1,0]
	v_pk_mul_f32 v[146:147], v[150:151], s[16:17] op_sel_hi:[1,0]
	v_pk_mul_f32 v[150:151], v[148:149], s[16:17] op_sel_hi:[1,0]
	v_sub_f32_e32 v149, v153, v206
	v_sub_f32_e32 v148, v152, v206
	v_sub_f32_e32 v153, v155, v206
	v_sub_f32_e32 v152, v154, v206
	v_pk_mul_f32 v[144:145], v[144:145], s[16:17] op_sel_hi:[1,0]
	v_pk_mul_f32 v[152:153], v[206:207], v[152:153] op_sel:[1,0]
	v_pk_mul_f32 v[148:149], v[206:207], v[148:149] op_sel:[1,0]
	v_pk_fma_f32 v[152:153], v[142:143], v[152:153], v[146:147]
	v_pk_fma_f32 v[148:149], v[144:145], v[148:149], v[150:151]
	v_pk_add_f32 v[126:127], v[126:127], v[152:153]
	v_pk_add_f32 v[124:125], v[124:125], v[148:149]
	global_store_dwordx4 v[210:211], v[124:127], off
	global_load_dwordx4 v[154:157], v[208:209], off offset:64
	v_pk_mul_f32 v[148:149], v[188:189], s[16:17] op_sel_hi:[1,0]
	v_pk_mul_f32 v[124:125], v[162:163], s[16:17] op_sel_hi:[1,0]
	v_pk_mul_f32 v[126:127], v[160:161], s[16:17] op_sel_hi:[1,0]
	v_pk_mul_f32 v[152:153], v[186:187], s[16:17] op_sel_hi:[1,0]
	s_waitcnt vmcnt(0)
	v_sub_f32_e32 v155, v155, v206
	v_sub_f32_e32 v154, v154, v206
	v_sub_f32_e32 v157, v157, v206
	v_sub_f32_e32 v156, v156, v206
	v_pk_mul_f32 v[156:157], v[206:207], v[156:157] op_sel:[1,0]
	v_pk_mul_f32 v[154:155], v[206:207], v[154:155] op_sel:[1,0]
	v_pk_fma_f32 v[156:157], v[124:125], v[156:157], v[148:149]
	v_pk_fma_f32 v[154:155], v[126:127], v[154:155], v[152:153]
	v_pk_add_f32 v[122:123], v[122:123], v[156:157]
	v_pk_add_f32 v[120:121], v[120:121], v[154:155]
	global_store_dwordx4 v[210:211], v[120:123], off offset:64
	global_load_dwordx4 v[160:163], v[208:209], off offset:512
	v_pk_mul_f32 v[154:155], v[200:201], s[16:17] op_sel_hi:[1,0]
	v_pk_mul_f32 v[120:121], v[192:193], s[16:17] op_sel_hi:[1,0]
	v_pk_mul_f32 v[122:123], v[190:191], s[16:17] op_sel_hi:[1,0]
	v_pk_mul_f32 v[156:157], v[198:199], s[16:17] op_sel_hi:[1,0]
	s_waitcnt vmcnt(0)
	v_sub_f32_e32 v161, v161, v206
	v_sub_f32_e32 v160, v160, v206
	v_sub_f32_e32 v163, v163, v206
	v_sub_f32_e32 v162, v162, v206
	v_pk_mul_f32 v[162:163], v[206:207], v[162:163] op_sel:[1,0]
	v_pk_mul_f32 v[160:161], v[206:207], v[160:161] op_sel:[1,0]
	v_pk_fma_f32 v[162:163], v[120:121], v[162:163], v[154:155]
	v_pk_fma_f32 v[160:161], v[122:123], v[160:161], v[156:157]
	v_pk_add_f32 v[118:119], v[118:119], v[162:163]
	v_pk_add_f32 v[116:117], v[116:117], v[160:161]
	global_store_dwordx4 v[210:211], v[116:119], off offset:512
	global_load_dwordx4 v[186:189], v[208:209], off offset:576
	v_pk_mul_f32 v[160:161], v[204:205], s[16:17] op_sel_hi:[1,0]
	v_or_b32_e32 v116, 16, v166
	v_ashrrev_i32_e32 v117, 31, v116
	v_lshlrev_b64 v[116:117], 10, v[116:117]
	v_lshl_add_u64 v[116:117], v[116:117], 0, v[164:165]
	v_lshlrev_b64 v[190:191], 2, v[116:117]
	v_pk_mul_f32 v[116:117], v[196:197], s[16:17] op_sel_hi:[1,0]
	v_pk_mul_f32 v[118:119], v[194:195], s[16:17] op_sel_hi:[1,0]
	v_pk_mul_f32 v[162:163], v[202:203], s[16:17] op_sel_hi:[1,0]
	v_lshl_add_u64 v[192:193], s[56:57], 0, v[190:191]
	s_waitcnt vmcnt(0)
	v_sub_f32_e32 v187, v187, v206
	v_sub_f32_e32 v186, v186, v206
	v_sub_f32_e32 v189, v189, v206
	v_sub_f32_e32 v188, v188, v206
	v_pk_mul_f32 v[188:189], v[206:207], v[188:189] op_sel:[1,0]
	v_pk_mul_f32 v[186:187], v[206:207], v[186:187] op_sel:[1,0]
	v_pk_fma_f32 v[188:189], v[116:117], v[188:189], v[160:161]
	v_pk_fma_f32 v[186:187], v[118:119], v[186:187], v[162:163]
	v_pk_add_f32 v[114:115], v[114:115], v[188:189]
	v_pk_add_f32 v[112:113], v[112:113], v[186:187]
	global_store_dwordx4 v[210:211], v[112:115], off offset:576
	global_load_dwordx2 v[186:187], v[140:141], off offset:128
	global_load_dwordx4 v[112:115], v[192:193], off
	v_lshl_add_u64 v[188:189], s[72:73], 0, v[190:191]
	s_waitcnt vmcnt(0)
	v_sub_f32_e32 v113, v113, v186
	v_sub_f32_e32 v112, v112, v186
	v_sub_f32_e32 v115, v115, v186
	v_sub_f32_e32 v114, v114, v186
	v_pk_mul_f32 v[114:115], v[186:187], v[114:115] op_sel:[1,0]
	v_pk_mul_f32 v[112:113], v[186:187], v[112:113] op_sel:[1,0]
	v_pk_fma_f32 v[114:115], v[142:143], v[114:115], v[146:147]
	v_pk_fma_f32 v[112:113], v[144:145], v[112:113], v[150:151]
	v_pk_add_f32 v[110:111], v[110:111], v[114:115]
	v_pk_add_f32 v[108:109], v[108:109], v[112:113]
	global_store_dwordx4 v[188:189], v[108:111], off
	global_load_dwordx4 v[108:111], v[192:193], off offset:64
	s_waitcnt vmcnt(0)
	v_sub_f32_e32 v109, v109, v186
	v_sub_f32_e32 v108, v108, v186
	v_sub_f32_e32 v111, v111, v186
	v_sub_f32_e32 v110, v110, v186
	v_pk_mul_f32 v[110:111], v[186:187], v[110:111] op_sel:[1,0]
	v_pk_mul_f32 v[108:109], v[186:187], v[108:109] op_sel:[1,0]
	v_pk_fma_f32 v[110:111], v[124:125], v[110:111], v[148:149]
	v_pk_fma_f32 v[108:109], v[126:127], v[108:109], v[152:153]
	v_pk_add_f32 v[106:107], v[106:107], v[110:111]
	v_pk_add_f32 v[104:105], v[104:105], v[108:109]
	global_store_dwordx4 v[188:189], v[104:107], off offset:64
	global_load_dwordx4 v[104:107], v[192:193], off offset:512
	s_waitcnt vmcnt(0)
	v_sub_f32_e32 v105, v105, v186
	v_sub_f32_e32 v104, v104, v186
	v_sub_f32_e32 v107, v107, v186
	v_sub_f32_e32 v106, v106, v186
	v_pk_mul_f32 v[106:107], v[186:187], v[106:107] op_sel:[1,0]
	v_pk_mul_f32 v[104:105], v[186:187], v[104:105] op_sel:[1,0]
	v_pk_fma_f32 v[106:107], v[120:121], v[106:107], v[154:155]
	v_pk_fma_f32 v[104:105], v[122:123], v[104:105], v[156:157]
	v_pk_add_f32 v[102:103], v[102:103], v[106:107]
	v_pk_add_f32 v[100:101], v[100:101], v[104:105]
	global_store_dwordx4 v[188:189], v[100:103], off offset:512
	global_load_dwordx4 v[100:103], v[192:193], off offset:576
	v_or_b32_e32 v104, 32, v166
	v_ashrrev_i32_e32 v105, 31, v104
	v_lshlrev_b64 v[104:105], 10, v[104:105]
	v_lshl_add_u64 v[104:105], v[104:105], 0, v[164:165]
	v_lshlrev_b64 v[104:105], 2, v[104:105]
	v_lshl_add_u64 v[106:107], s[56:57], 0, v[104:105]
	s_waitcnt vmcnt(0)
	v_sub_f32_e32 v101, v101, v186
	v_sub_f32_e32 v100, v100, v186
	v_sub_f32_e32 v103, v103, v186
	v_sub_f32_e32 v102, v102, v186
	v_pk_mul_f32 v[102:103], v[186:187], v[102:103] op_sel:[1,0]
	v_pk_mul_f32 v[100:101], v[186:187], v[100:101] op_sel:[1,0]
	v_pk_fma_f32 v[102:103], v[116:117], v[102:103], v[160:161]
	v_pk_fma_f32 v[100:101], v[118:119], v[100:101], v[162:163]
	v_pk_add_f32 v[98:99], v[98:99], v[102:103]
	v_pk_add_f32 v[96:97], v[96:97], v[100:101]
	global_store_dwordx4 v[188:189], v[96:99], off offset:576
	global_load_dwordx2 v[100:101], v[140:141], off offset:256
	global_load_dwordx4 v[96:99], v[106:107], off
	v_lshl_add_u64 v[102:103], s[72:73], 0, v[104:105]
	s_waitcnt vmcnt(0)
	v_sub_f32_e32 v97, v97, v100
	v_sub_f32_e32 v96, v96, v100
	v_sub_f32_e32 v99, v99, v100
	v_sub_f32_e32 v98, v98, v100
	v_pk_mul_f32 v[98:99], v[100:101], v[98:99] op_sel:[1,0]
	v_pk_mul_f32 v[96:97], v[100:101], v[96:97] op_sel:[1,0]
	v_pk_fma_f32 v[98:99], v[142:143], v[98:99], v[146:147]
	v_pk_fma_f32 v[96:97], v[144:145], v[96:97], v[150:151]
	v_pk_add_f32 v[94:95], v[94:95], v[98:99]
	v_pk_add_f32 v[92:93], v[92:93], v[96:97]
	global_store_dwordx4 v[102:103], v[92:95], off
	global_load_dwordx4 v[92:95], v[106:107], off offset:64
	s_waitcnt vmcnt(0)
	v_sub_f32_e32 v93, v93, v100
	v_sub_f32_e32 v92, v92, v100
	v_sub_f32_e32 v95, v95, v100
	v_sub_f32_e32 v94, v94, v100
	v_pk_mul_f32 v[94:95], v[100:101], v[94:95] op_sel:[1,0]
	v_pk_mul_f32 v[92:93], v[100:101], v[92:93] op_sel:[1,0]
	v_pk_fma_f32 v[94:95], v[124:125], v[94:95], v[148:149]
	v_pk_fma_f32 v[92:93], v[126:127], v[92:93], v[152:153]
	v_pk_add_f32 v[90:91], v[90:91], v[94:95]
	v_pk_add_f32 v[88:89], v[88:89], v[92:93]
	global_store_dwordx4 v[102:103], v[88:91], off offset:64
	global_load_dwordx4 v[88:91], v[106:107], off offset:512
	s_waitcnt vmcnt(0)
	v_sub_f32_e32 v89, v89, v100
	v_sub_f32_e32 v88, v88, v100
	v_sub_f32_e32 v91, v91, v100
	v_sub_f32_e32 v90, v90, v100
	v_pk_mul_f32 v[90:91], v[100:101], v[90:91] op_sel:[1,0]
	v_pk_mul_f32 v[88:89], v[100:101], v[88:89] op_sel:[1,0]
	v_pk_fma_f32 v[90:91], v[120:121], v[90:91], v[154:155]
	v_pk_fma_f32 v[88:89], v[122:123], v[88:89], v[156:157]
	v_pk_add_f32 v[86:87], v[86:87], v[90:91]
	v_pk_add_f32 v[84:85], v[84:85], v[88:89]
	global_store_dwordx4 v[102:103], v[84:87], off offset:512
	global_load_dwordx4 v[84:87], v[106:107], off offset:576
	v_or_b32_e32 v88, 48, v166
	v_ashrrev_i32_e32 v89, 31, v88
	v_lshlrev_b64 v[88:89], 10, v[88:89]
	v_lshl_add_u64 v[88:89], v[88:89], 0, v[164:165]
	v_lshlrev_b64 v[88:89], 2, v[88:89]
	v_lshl_add_u64 v[90:91], s[56:57], 0, v[88:89]
	s_waitcnt vmcnt(0)
	v_sub_f32_e32 v85, v85, v100
	v_sub_f32_e32 v84, v84, v100
	v_sub_f32_e32 v87, v87, v100
	v_sub_f32_e32 v86, v86, v100
	v_pk_mul_f32 v[86:87], v[100:101], v[86:87] op_sel:[1,0]
	v_pk_mul_f32 v[84:85], v[100:101], v[84:85] op_sel:[1,0]
	v_pk_fma_f32 v[86:87], v[116:117], v[86:87], v[160:161]
	v_pk_fma_f32 v[84:85], v[118:119], v[84:85], v[162:163]
	v_pk_add_f32 v[82:83], v[82:83], v[86:87]
	v_pk_add_f32 v[80:81], v[80:81], v[84:85]
	global_store_dwordx4 v[102:103], v[80:83], off offset:576
	global_load_dwordx2 v[84:85], v[140:141], off offset:384
	global_load_dwordx4 v[80:83], v[90:91], off
	v_lshl_add_u64 v[86:87], s[72:73], 0, v[88:89]
	s_waitcnt vmcnt(0)
	v_sub_f32_e32 v81, v81, v84
	v_sub_f32_e32 v80, v80, v84
	v_sub_f32_e32 v83, v83, v84
	v_sub_f32_e32 v82, v82, v84
	v_pk_mul_f32 v[82:83], v[84:85], v[82:83] op_sel:[1,0]
	v_pk_mul_f32 v[80:81], v[84:85], v[80:81] op_sel:[1,0]
	v_pk_fma_f32 v[82:83], v[142:143], v[82:83], v[146:147]
	v_pk_fma_f32 v[80:81], v[144:145], v[80:81], v[150:151]
	v_pk_add_f32 v[78:79], v[78:79], v[82:83]
	v_pk_add_f32 v[76:77], v[76:77], v[80:81]
	global_store_dwordx4 v[86:87], v[76:79], off
	global_load_dwordx4 v[76:79], v[90:91], off offset:64
	s_waitcnt vmcnt(0)
	v_sub_f32_e32 v77, v77, v84
	v_sub_f32_e32 v76, v76, v84
	v_sub_f32_e32 v79, v79, v84
	v_sub_f32_e32 v78, v78, v84
	v_pk_mul_f32 v[78:79], v[84:85], v[78:79] op_sel:[1,0]
	v_pk_mul_f32 v[76:77], v[84:85], v[76:77] op_sel:[1,0]
	v_pk_fma_f32 v[78:79], v[124:125], v[78:79], v[148:149]
	v_pk_fma_f32 v[76:77], v[126:127], v[76:77], v[152:153]
	v_pk_add_f32 v[74:75], v[74:75], v[78:79]
	v_pk_add_f32 v[72:73], v[72:73], v[76:77]
	global_store_dwordx4 v[86:87], v[72:75], off offset:64
	global_load_dwordx4 v[72:75], v[90:91], off offset:512
	s_waitcnt vmcnt(0)
	v_sub_f32_e32 v73, v73, v84
	v_sub_f32_e32 v72, v72, v84
	v_sub_f32_e32 v75, v75, v84
	v_sub_f32_e32 v74, v74, v84
	v_pk_mul_f32 v[74:75], v[84:85], v[74:75] op_sel:[1,0]
	v_pk_mul_f32 v[72:73], v[84:85], v[72:73] op_sel:[1,0]
	v_pk_fma_f32 v[74:75], v[120:121], v[74:75], v[154:155]
	v_pk_fma_f32 v[72:73], v[122:123], v[72:73], v[156:157]
	v_pk_add_f32 v[70:71], v[70:71], v[74:75]
	v_pk_add_f32 v[68:69], v[68:69], v[72:73]
	global_store_dwordx4 v[86:87], v[68:71], off offset:512
	global_load_dwordx4 v[68:71], v[90:91], off offset:576
	v_lshl_add_u64 v[72:73], v[158:159], 0, s[34:35]
	v_lshl_add_u64 v[74:75], s[56:57], 0, v[72:73]
	s_mov_b64 s[34:35], 0x90000
	s_waitcnt vmcnt(0)
	v_sub_f32_e32 v69, v69, v84
	v_sub_f32_e32 v68, v68, v84
	v_sub_f32_e32 v71, v71, v84
	v_sub_f32_e32 v70, v70, v84
	v_pk_mul_f32 v[70:71], v[84:85], v[70:71] op_sel:[1,0]
	v_pk_mul_f32 v[68:69], v[84:85], v[68:69] op_sel:[1,0]
	v_pk_fma_f32 v[70:71], v[116:117], v[70:71], v[160:161]
	v_pk_fma_f32 v[68:69], v[118:119], v[68:69], v[162:163]
	v_pk_add_f32 v[66:67], v[66:67], v[70:71]
	v_pk_add_f32 v[64:65], v[64:65], v[68:69]
	global_store_dwordx4 v[86:87], v[64:67], off offset:576
	global_load_dwordx2 v[68:69], v[140:141], off offset:1024
	global_load_dwordx4 v[64:67], v[74:75], off
	v_lshl_add_u64 v[70:71], s[72:73], 0, v[72:73]
	s_waitcnt vmcnt(0)
	v_sub_f32_e32 v65, v65, v68
	v_sub_f32_e32 v64, v64, v68
	v_sub_f32_e32 v67, v67, v68
	v_sub_f32_e32 v66, v66, v68
	v_pk_mul_f32 v[66:67], v[68:69], v[66:67] op_sel:[1,0]
	v_pk_mul_f32 v[64:65], v[68:69], v[64:65] op_sel:[1,0]
	v_pk_fma_f32 v[66:67], v[142:143], v[66:67], v[146:147]
	v_pk_fma_f32 v[64:65], v[144:145], v[64:65], v[150:151]
	v_pk_add_f32 v[62:63], v[62:63], v[66:67]
	v_pk_add_f32 v[60:61], v[60:61], v[64:65]
	global_store_dwordx4 v[70:71], v[60:63], off
	global_load_dwordx4 v[60:63], v[74:75], off offset:64
	s_waitcnt vmcnt(0)
	v_sub_f32_e32 v61, v61, v68
	v_sub_f32_e32 v60, v60, v68
	v_sub_f32_e32 v63, v63, v68
	v_sub_f32_e32 v62, v62, v68
	v_pk_mul_f32 v[62:63], v[68:69], v[62:63] op_sel:[1,0]
	v_pk_mul_f32 v[60:61], v[68:69], v[60:61] op_sel:[1,0]
	v_pk_fma_f32 v[62:63], v[124:125], v[62:63], v[148:149]
	v_pk_fma_f32 v[60:61], v[126:127], v[60:61], v[152:153]
	v_pk_add_f32 v[58:59], v[58:59], v[62:63]
	v_pk_add_f32 v[56:57], v[56:57], v[60:61]
	global_store_dwordx4 v[70:71], v[56:59], off offset:64
	global_load_dwordx4 v[56:59], v[74:75], off offset:512
	s_waitcnt vmcnt(0)
	v_sub_f32_e32 v57, v57, v68
	v_sub_f32_e32 v56, v56, v68
	v_sub_f32_e32 v59, v59, v68
	v_sub_f32_e32 v58, v58, v68
	v_pk_mul_f32 v[58:59], v[68:69], v[58:59] op_sel:[1,0]
	v_pk_mul_f32 v[56:57], v[68:69], v[56:57] op_sel:[1,0]
	v_pk_fma_f32 v[58:59], v[120:121], v[58:59], v[154:155]
	v_pk_fma_f32 v[56:57], v[122:123], v[56:57], v[156:157]
	v_pk_add_f32 v[54:55], v[54:55], v[58:59]
	v_pk_add_f32 v[52:53], v[52:53], v[56:57]
	global_store_dwordx4 v[70:71], v[52:55], off offset:512
	global_load_dwordx4 v[52:55], v[74:75], off offset:576
	v_lshl_add_u64 v[56:57], v[158:159], 0, s[34:35]
	v_lshl_add_u64 v[58:59], s[56:57], 0, v[56:57]
	s_waitcnt vmcnt(0)
	v_sub_f32_e32 v53, v53, v68
	v_sub_f32_e32 v52, v52, v68
	v_sub_f32_e32 v55, v55, v68
	v_sub_f32_e32 v54, v54, v68
	v_pk_mul_f32 v[54:55], v[68:69], v[54:55] op_sel:[1,0]
	v_pk_mul_f32 v[52:53], v[68:69], v[52:53] op_sel:[1,0]
	v_pk_fma_f32 v[54:55], v[116:117], v[54:55], v[160:161]
	v_pk_fma_f32 v[52:53], v[118:119], v[52:53], v[162:163]
	v_pk_add_f32 v[50:51], v[50:51], v[54:55]
	v_pk_add_f32 v[48:49], v[48:49], v[52:53]
	global_store_dwordx4 v[70:71], v[48:51], off offset:576
	global_load_dwordx2 v[52:53], v[140:141], off offset:1152
	global_load_dwordx4 v[48:51], v[58:59], off
	v_lshl_add_u64 v[54:55], s[72:73], 0, v[56:57]
	s_waitcnt vmcnt(0)
	v_sub_f32_e32 v49, v49, v52
	v_sub_f32_e32 v48, v48, v52
	v_sub_f32_e32 v51, v51, v52
	v_sub_f32_e32 v50, v50, v52
	v_pk_mul_f32 v[50:51], v[52:53], v[50:51] op_sel:[1,0]
	v_pk_mul_f32 v[48:49], v[52:53], v[48:49] op_sel:[1,0]
	v_pk_fma_f32 v[50:51], v[142:143], v[50:51], v[146:147]
	v_pk_fma_f32 v[48:49], v[144:145], v[48:49], v[150:151]
	v_pk_add_f32 v[46:47], v[46:47], v[50:51]
	v_pk_add_f32 v[44:45], v[44:45], v[48:49]
	global_store_dwordx4 v[54:55], v[44:47], off
	global_load_dwordx4 v[44:47], v[58:59], off offset:64
	s_waitcnt vmcnt(0)
	v_sub_f32_e32 v45, v45, v52
	v_sub_f32_e32 v44, v44, v52
	v_sub_f32_e32 v47, v47, v52
	v_sub_f32_e32 v46, v46, v52
	v_pk_mul_f32 v[46:47], v[52:53], v[46:47] op_sel:[1,0]
	v_pk_mul_f32 v[44:45], v[52:53], v[44:45] op_sel:[1,0]
	v_pk_fma_f32 v[46:47], v[124:125], v[46:47], v[148:149]
	v_pk_fma_f32 v[44:45], v[126:127], v[44:45], v[152:153]
	v_pk_add_f32 v[42:43], v[42:43], v[46:47]
	v_pk_add_f32 v[40:41], v[40:41], v[44:45]
	global_store_dwordx4 v[54:55], v[40:43], off offset:64
	global_load_dwordx4 v[40:43], v[58:59], off offset:512
	s_waitcnt vmcnt(0)
	v_sub_f32_e32 v41, v41, v52
	v_sub_f32_e32 v40, v40, v52
	v_sub_f32_e32 v43, v43, v52
	v_sub_f32_e32 v42, v42, v52
	v_pk_mul_f32 v[42:43], v[52:53], v[42:43] op_sel:[1,0]
	v_pk_mul_f32 v[40:41], v[52:53], v[40:41] op_sel:[1,0]
	v_pk_fma_f32 v[42:43], v[120:121], v[42:43], v[154:155]
	v_pk_fma_f32 v[40:41], v[122:123], v[40:41], v[156:157]
	v_pk_add_f32 v[38:39], v[38:39], v[42:43]
	v_pk_add_f32 v[36:37], v[36:37], v[40:41]
	global_store_dwordx4 v[54:55], v[36:39], off offset:512
	global_load_dwordx4 v[36:39], v[58:59], off offset:576
	v_lshl_add_u64 v[40:41], v[158:159], 0, s[18:19]
	v_lshl_add_u64 v[42:43], s[56:57], 0, v[40:41]
	s_waitcnt vmcnt(0)
	v_sub_f32_e32 v37, v37, v52
	v_sub_f32_e32 v36, v36, v52
	v_sub_f32_e32 v39, v39, v52
	v_sub_f32_e32 v38, v38, v52
	v_pk_mul_f32 v[38:39], v[52:53], v[38:39] op_sel:[1,0]
	v_pk_mul_f32 v[36:37], v[52:53], v[36:37] op_sel:[1,0]
	v_pk_fma_f32 v[38:39], v[116:117], v[38:39], v[160:161]
	v_pk_fma_f32 v[36:37], v[118:119], v[36:37], v[162:163]
	v_pk_add_f32 v[34:35], v[34:35], v[38:39]
	v_pk_add_f32 v[32:33], v[32:33], v[36:37]
	global_store_dwordx4 v[54:55], v[32:35], off offset:576
	global_load_dwordx2 v[36:37], v[140:141], off offset:1280
	global_load_dwordx4 v[32:35], v[42:43], off
	v_lshl_add_u64 v[38:39], s[72:73], 0, v[40:41]
	s_waitcnt vmcnt(0)
	v_sub_f32_e32 v33, v33, v36
	v_sub_f32_e32 v32, v32, v36
	v_sub_f32_e32 v35, v35, v36
	v_sub_f32_e32 v34, v34, v36
	v_pk_mul_f32 v[34:35], v[36:37], v[34:35] op_sel:[1,0]
	v_pk_mul_f32 v[32:33], v[36:37], v[32:33] op_sel:[1,0]
	v_pk_fma_f32 v[34:35], v[142:143], v[34:35], v[146:147]
	v_pk_fma_f32 v[32:33], v[144:145], v[32:33], v[150:151]
	v_pk_add_f32 v[30:31], v[30:31], v[34:35]
	v_pk_add_f32 v[28:29], v[28:29], v[32:33]
	global_store_dwordx4 v[38:39], v[28:31], off
	global_load_dwordx4 v[28:31], v[42:43], off offset:64
	s_waitcnt vmcnt(0)
	v_sub_f32_e32 v29, v29, v36
	v_sub_f32_e32 v28, v28, v36
	v_sub_f32_e32 v31, v31, v36
	v_sub_f32_e32 v30, v30, v36
	v_pk_mul_f32 v[30:31], v[36:37], v[30:31] op_sel:[1,0]
	v_pk_mul_f32 v[28:29], v[36:37], v[28:29] op_sel:[1,0]
	v_pk_fma_f32 v[30:31], v[124:125], v[30:31], v[148:149]
	v_pk_fma_f32 v[28:29], v[126:127], v[28:29], v[152:153]
	v_pk_add_f32 v[26:27], v[26:27], v[30:31]
	v_pk_add_f32 v[24:25], v[24:25], v[28:29]
	global_store_dwordx4 v[38:39], v[24:27], off offset:64
	global_load_dwordx4 v[24:27], v[42:43], off offset:512
	s_waitcnt vmcnt(0)
	v_sub_f32_e32 v25, v25, v36
	v_sub_f32_e32 v24, v24, v36
	v_sub_f32_e32 v27, v27, v36
	v_sub_f32_e32 v26, v26, v36
	v_pk_mul_f32 v[26:27], v[36:37], v[26:27] op_sel:[1,0]
	v_pk_mul_f32 v[24:25], v[36:37], v[24:25] op_sel:[1,0]
	v_pk_fma_f32 v[26:27], v[120:121], v[26:27], v[154:155]
	v_pk_fma_f32 v[24:25], v[122:123], v[24:25], v[156:157]
	v_pk_add_f32 v[22:23], v[22:23], v[26:27]
	v_pk_add_f32 v[20:21], v[20:21], v[24:25]
	global_store_dwordx4 v[38:39], v[20:23], off offset:512
	global_load_dwordx4 v[20:23], v[42:43], off offset:576
	v_lshl_add_u64 v[24:25], v[158:159], 0, s[20:21]
	v_lshl_add_u64 v[26:27], s[56:57], 0, v[24:25]
	s_waitcnt vmcnt(0)
	v_sub_f32_e32 v21, v21, v36
	v_sub_f32_e32 v20, v20, v36
	v_sub_f32_e32 v23, v23, v36
	v_sub_f32_e32 v22, v22, v36
	v_pk_mul_f32 v[22:23], v[36:37], v[22:23] op_sel:[1,0]
	v_pk_mul_f32 v[20:21], v[36:37], v[20:21] op_sel:[1,0]
	v_pk_fma_f32 v[22:23], v[116:117], v[22:23], v[160:161]
	v_pk_fma_f32 v[20:21], v[118:119], v[20:21], v[162:163]
	v_pk_add_f32 v[18:19], v[18:19], v[22:23]
	v_pk_add_f32 v[16:17], v[16:17], v[20:21]
	global_store_dwordx4 v[38:39], v[16:19], off offset:576
	global_load_dwordx2 v[20:21], v[140:141], off offset:1408
	global_load_dwordx4 v[16:19], v[26:27], off
	v_lshl_add_u64 v[22:23], s[72:73], 0, v[24:25]
	s_waitcnt vmcnt(0)
	v_sub_f32_e32 v17, v17, v20
	v_sub_f32_e32 v16, v16, v20
	v_sub_f32_e32 v19, v19, v20
	v_sub_f32_e32 v18, v18, v20
	v_pk_mul_f32 v[18:19], v[20:21], v[18:19] op_sel:[1,0]
	v_pk_mul_f32 v[16:17], v[20:21], v[16:17] op_sel:[1,0]
	v_pk_fma_f32 v[18:19], v[142:143], v[18:19], v[146:147]
	v_pk_fma_f32 v[16:17], v[144:145], v[16:17], v[150:151]
	v_pk_add_f32 v[14:15], v[14:15], v[18:19]
	v_pk_add_f32 v[12:13], v[12:13], v[16:17]
	global_store_dwordx4 v[22:23], v[12:15], off
	global_load_dwordx4 v[12:15], v[26:27], off offset:64
	s_waitcnt vmcnt(0)
	v_sub_f32_e32 v13, v13, v20
	v_sub_f32_e32 v12, v12, v20
	v_sub_f32_e32 v15, v15, v20
	v_sub_f32_e32 v14, v14, v20
	v_pk_mul_f32 v[14:15], v[20:21], v[14:15] op_sel:[1,0]
	v_pk_mul_f32 v[12:13], v[20:21], v[12:13] op_sel:[1,0]
	v_pk_fma_f32 v[14:15], v[124:125], v[14:15], v[148:149]
	v_pk_fma_f32 v[12:13], v[126:127], v[12:13], v[152:153]
	v_pk_add_f32 v[10:11], v[10:11], v[14:15]
	v_pk_add_f32 v[8:9], v[8:9], v[12:13]
	global_store_dwordx4 v[22:23], v[8:11], off offset:64
	global_load_dwordx4 v[8:11], v[26:27], off offset:512
	s_waitcnt vmcnt(0)
	v_sub_f32_e32 v9, v9, v20
	v_sub_f32_e32 v8, v8, v20
	v_sub_f32_e32 v11, v11, v20
	v_sub_f32_e32 v10, v10, v20
	v_pk_mul_f32 v[10:11], v[20:21], v[10:11] op_sel:[1,0]
	v_pk_mul_f32 v[8:9], v[20:21], v[8:9] op_sel:[1,0]
	v_pk_fma_f32 v[10:11], v[120:121], v[10:11], v[154:155]
	v_pk_fma_f32 v[8:9], v[122:123], v[8:9], v[156:157]
	v_pk_add_f32 v[6:7], v[6:7], v[10:11]
	v_pk_add_f32 v[4:5], v[4:5], v[8:9]
	global_store_dwordx4 v[22:23], v[4:7], off offset:512
	global_load_dwordx4 v[4:7], v[26:27], off offset:576
	s_waitcnt vmcnt(0)
	v_sub_f32_e32 v5, v5, v20
	v_sub_f32_e32 v4, v4, v20
	v_sub_f32_e32 v7, v7, v20
	v_sub_f32_e32 v6, v6, v20
	v_pk_mul_f32 v[6:7], v[20:21], v[6:7] op_sel:[1,0]
	v_pk_mul_f32 v[4:5], v[20:21], v[4:5] op_sel:[1,0]
	v_pk_fma_f32 v[6:7], v[116:117], v[6:7], v[160:161]
	v_pk_fma_f32 v[4:5], v[118:119], v[4:5], v[162:163]
	v_pk_add_f32 v[2:3], v[2:3], v[6:7]
	v_pk_add_f32 v[0:1], v[0:1], v[4:5]
	global_store_dwordx4 v[22:23], v[0:3], off offset:576
	s_cbranch_vccnz .LBB0_750
	s_andn2_b64 vcc, exec, s[10:11]
	s_cbranch_vccnz .LBB0_749
	s_barrier
	s_branch .LBB0_749

.LBB0_771:
	s_add_i32 s45, s40, 1
	s_ashr_i32 s0, s45, 31
	v_readlane_b32 s2, v246, 48
	s_mul_i32 s0, s0, s2
	s_mul_hi_u32 s1, s45, s2
	s_add_i32 s1, s1, s0
	s_mul_i32 s0, s45, s2
	s_add_u32 s20, s0, s74
	s_addc_u32 s21, s1, s33
	v_cmp_gt_i64_e64 s[0:1], s[20:21], v[138:139]
	v_cmp_lt_i64_e64 s[2:3], s[20:21], v[136:137]
	s_and_b64 vcc, exec, s[0:1]
	s_cbranch_vccnz .LBB0_777
	s_ashr_i32 s16, s20, 31
	s_lshr_b32 s16, s16, 29
	s_add_i32 s18, s20, s16
	s_and_b32 s16, s18, -8
	s_sub_i32 s19, s20, s16
	s_cmp_gt_i32 s19, -1
	s_mov_b64 s[16:17], -1
	s_cbranch_scc0 .LBB0_774
	s_lshl_b32 s20, s19, 5
	s_mov_b64 s[16:17], 0

.LBB0_782:
	v_readlane_b32 s48, v246, 4
	v_readlane_b32 s49, v246, 5
	v_readlane_b32 s50, v246, 6
	v_readlane_b32 s51, v246, 7
	v_readlane_b32 s52, v246, 8
	v_readlane_b32 s53, v246, 9
	s_andn2_b64 vcc, exec, s[0:1]
	s_cbranch_vccz .LBB0_784
	s_mov_b64 s[24:25], s[20:21]
	s_branch .LBB0_771

.LBB0_827:
	s_or_b64 exec, exec, s[2:3]
	v_readlane_b32 s36, v246, 20
	v_readlane_b32 s38, v246, 22
	v_readlane_b32 s39, v246, 23
	v_readlane_b32 s40, v246, 24
	v_readlane_b32 s41, v246, 25
	s_mov_b64 s[2:3], s[38:39]
	s_mov_b64 s[4:5], s[40:41]
	s_waitcnt lgkmcnt(0)
	s_barrier
	v_lshl_add_u64 v[130:131], s[2:3], 0, v[128:129]
	v_lshl_add_u64 v[132:133], s[4:5], 0, v[128:129]
	global_load_dwordx4 v[152:155], v[132:133], off
	global_load_dwordx4 v[156:159], v[130:131], off
	global_load_dwordx4 v[144:147], v[130:131], off offset:64
	global_load_dwordx4 v[148:151], v[132:133], off offset:64
	global_load_dwordx4 v[136:139], v[132:133], off offset:512
	global_load_dwordx4 v[140:143], v[130:131], off offset:512
	s_nop 0
	global_load_dwordx4 v[128:131], v[130:131], off offset:576
	s_nop 0
	global_load_dwordx4 v[132:135], v[132:133], off offset:576
	v_lshl_add_u32 v165, v179, 3, 0
	ds_read_b64 v[168:169], v165 offset:8192
	v_add_u32_e32 v162, s22, v179
	v_ashrrev_i32_e32 v163, 31, v162
	v_readlane_b32 s48, v246, 32
	v_readlane_b32 s49, v246, 33
	s_waitcnt lgkmcnt(0)
	v_sub_f32_e32 v101, v101, v168
	v_sub_f32_e32 v100, v100, v168
	v_sub_f32_e32 v103, v103, v168
	v_sub_f32_e32 v102, v102, v168
	v_sub_f32_e32 v69, v69, v168
	v_sub_f32_e32 v68, v68, v168
	v_sub_f32_e32 v71, v71, v168
	v_sub_f32_e32 v70, v70, v168
	v_lshlrev_b64 v[180:181], 10, v[162:163]
	v_sub_f32_e32 v97, v97, v168
	v_sub_f32_e32 v96, v96, v168
	v_sub_f32_e32 v99, v99, v168
	v_sub_f32_e32 v98, v98, v168
	v_sub_f32_e32 v77, v77, v168
	v_sub_f32_e32 v76, v76, v168
	v_sub_f32_e32 v79, v79, v168
	v_sub_f32_e32 v78, v78, v168
	v_pk_mul_f32 v[102:103], v[168:169], v[102:103] op_sel:[1,0]
	v_pk_mul_f32 v[100:101], v[168:169], v[100:101] op_sel:[1,0]
	v_pk_mul_f32 v[70:71], v[168:169], v[70:71] op_sel:[1,0]
	v_pk_mul_f32 v[68:69], v[168:169], v[68:69] op_sel:[1,0]
	v_readlane_b32 s50, v246, 34
	v_readlane_b32 s51, v246, 35
	s_mov_b64 s[12:13], s[48:49]
	v_mov_b32_e32 v164, 0x7fc00000
	v_lshl_add_u64 v[180:181], v[180:181], 0, v[160:161]
	v_pk_mul_f32 v[98:99], v[168:169], v[98:99] op_sel:[1,0]
	v_pk_mul_f32 v[96:97], v[168:169], v[96:97] op_sel:[1,0]
	v_pk_mul_f32 v[78:79], v[168:169], v[78:79] op_sel:[1,0]
	v_pk_mul_f32 v[76:77], v[168:169], v[76:77] op_sel:[1,0]
	v_cmp_eq_u32_e32 vcc, 0, v166
	s_mov_b64 s[14:15], s[50:51]
	v_lshl_add_u64 v[182:183], v[180:181], 2, s[72:73]
	v_lshl_add_u64 v[180:181], v[180:181], 1, s[14:15]
	v_readlane_b32 s42, v246, 26
	s_waitcnt vmcnt(6)
	v_pk_fma_f32 v[100:101], v[156:157], v[100:101], v[152:153]
	v_pk_fma_f32 v[102:103], v[158:159], v[102:103], v[154:155]
	s_waitcnt vmcnt(4)
	v_pk_fma_f32 v[96:97], v[144:145], v[96:97], v[148:149]
	v_pk_fma_f32 v[98:99], v[146:147], v[98:99], v[150:151]
	s_waitcnt vmcnt(2)
	v_pk_fma_f32 v[168:169], v[140:141], v[76:77], v[136:137]
	v_pk_fma_f32 v[184:185], v[142:143], v[78:79], v[138:139]
	s_waitcnt vmcnt(0)
	v_pk_fma_f32 v[186:187], v[128:129], v[68:69], v[132:133]
	v_pk_fma_f32 v[188:189], v[130:131], v[70:71], v[134:135]
	v_cndmask_b32_e32 v71, v164, v103, vcc
	v_cndmask_b32_e32 v70, v164, v102, vcc
	v_cndmask_b32_e32 v69, v164, v101, vcc
	v_cndmask_b32_e32 v68, v164, v100, vcc
	v_cndmask_b32_e32 v103, v164, v189, vcc
	v_cndmask_b32_e32 v102, v164, v188, vcc
	v_cndmask_b32_e32 v101, v164, v187, vcc
	v_cndmask_b32_e32 v100, v164, v186, vcc
	v_cndmask_b32_e32 v79, v164, v99, vcc
	v_cndmask_b32_e32 v78, v164, v98, vcc
	v_cndmask_b32_e32 v77, v164, v97, vcc
	v_cndmask_b32_e32 v76, v164, v96, vcc
	v_cndmask_b32_e32 v99, v164, v185, vcc
	v_cndmask_b32_e32 v98, v164, v184, vcc
	v_cndmask_b32_e32 v97, v164, v169, vcc
	v_cndmask_b32_e32 v96, v164, v168, vcc
	global_store_dwordx4 v[182:183], v[68:71], off
	v_cvt_pk_bf16_f32 v168, v100, v101
	v_cvt_pk_bf16_f32 v169, v102, v103
	v_cvt_pk_bf16_f32 v68, v68, v69
	v_cvt_pk_bf16_f32 v69, v70, v71
	v_cvt_pk_bf16_f32 v70, v76, v77
	v_cvt_pk_bf16_f32 v71, v78, v79
	v_cvt_pk_bf16_f32 v166, v96, v97
	v_cvt_pk_bf16_f32 v167, v98, v99
	global_store_dwordx2 v[180:181], v[68:69], off
	global_store_dwordx4 v[182:183], v[76:79], off offset:64
	global_store_dwordx2 v[180:181], v[70:71], off offset:32
	global_store_dwordx4 v[182:183], v[96:99], off offset:512
	global_store_dwordx2 v[180:181], v[166:167], off offset:256
	global_store_dwordx4 v[182:183], v[100:103], off offset:576
	global_store_dwordx2 v[180:181], v[168:169], off offset:288
	ds_read_b64 v[76:77], v165 offset:8320
	v_add_u32_e32 v68, 16, v162
	v_ashrrev_i32_e32 v69, 31, v68
	v_lshlrev_b64 v[68:69], 10, v[68:69]
	v_lshl_add_u64 v[78:79], v[68:69], 0, v[160:161]
	s_waitcnt lgkmcnt(0)
	v_sub_f32_e32 v69, v109, v76
	v_sub_f32_e32 v68, v108, v76
	v_sub_f32_e32 v71, v111, v76
	v_sub_f32_e32 v70, v110, v76
	v_pk_mul_f32 v[70:71], v[76:77], v[70:71] op_sel:[1,0]
	v_pk_mul_f32 v[68:69], v[76:77], v[68:69] op_sel:[1,0]
	v_pk_fma_f32 v[70:71], v[158:159], v[70:71], v[154:155]
	v_pk_fma_f32 v[68:69], v[156:157], v[68:69], v[152:153]
	v_cndmask_b32_e32 v71, v164, v71, vcc
	v_cndmask_b32_e32 v70, v164, v70, vcc
	v_cndmask_b32_e32 v69, v164, v69, vcc
	v_cndmask_b32_e32 v68, v164, v68, vcc
	v_lshl_add_u64 v[96:97], v[78:79], 2, s[72:73]
	global_store_dwordx4 v[96:97], v[68:71], off
	v_lshl_add_u64 v[78:79], v[78:79], 1, s[14:15]
	v_sub_f32_e32 v65, v65, v76
	v_cvt_pk_bf16_f32 v68, v68, v69
	v_cvt_pk_bf16_f32 v69, v70, v71
	global_store_dwordx2 v[78:79], v[68:69], off
	v_sub_f32_e32 v69, v85, v76
	v_sub_f32_e32 v68, v84, v76
	v_sub_f32_e32 v71, v87, v76
	v_sub_f32_e32 v70, v86, v76
	v_pk_mul_f32 v[70:71], v[76:77], v[70:71] op_sel:[1,0]
	v_pk_mul_f32 v[68:69], v[76:77], v[68:69] op_sel:[1,0]
	v_pk_fma_f32 v[70:71], v[146:147], v[70:71], v[150:151]
	v_pk_fma_f32 v[68:69], v[144:145], v[68:69], v[148:149]
	v_cndmask_b32_e32 v71, v164, v71, vcc
	v_cndmask_b32_e32 v70, v164, v70, vcc
	v_cndmask_b32_e32 v69, v164, v69, vcc
	v_cndmask_b32_e32 v68, v164, v68, vcc
	global_store_dwordx4 v[96:97], v[68:71], off offset:64
	v_sub_f32_e32 v64, v64, v76
	v_sub_f32_e32 v67, v67, v76
	v_cvt_pk_bf16_f32 v68, v68, v69
	v_cvt_pk_bf16_f32 v69, v70, v71
	global_store_dwordx2 v[78:79], v[68:69], off offset:32
	v_sub_f32_e32 v69, v73, v76
	v_sub_f32_e32 v68, v72, v76
	v_sub_f32_e32 v71, v75, v76
	v_sub_f32_e32 v70, v74, v76
	v_pk_mul_f32 v[70:71], v[76:77], v[70:71] op_sel:[1,0]
	v_pk_mul_f32 v[68:69], v[76:77], v[68:69] op_sel:[1,0]
	v_sub_f32_e32 v66, v66, v76
	v_pk_fma_f32 v[68:69], v[140:141], v[68:69], v[136:137]
	v_pk_fma_f32 v[70:71], v[142:143], v[70:71], v[138:139]
	v_pk_mul_f32 v[66:67], v[76:77], v[66:67] op_sel:[1,0]
	v_pk_mul_f32 v[64:65], v[76:77], v[64:65] op_sel:[1,0]
	v_cndmask_b32_e32 v71, v164, v71, vcc
	v_cndmask_b32_e32 v70, v164, v70, vcc
	v_cndmask_b32_e32 v69, v164, v69, vcc
	v_cndmask_b32_e32 v68, v164, v68, vcc
	v_pk_fma_f32 v[64:65], v[128:129], v[64:65], v[132:133]
	v_pk_fma_f32 v[66:67], v[130:131], v[66:67], v[134:135]
	global_store_dwordx4 v[96:97], v[68:71], off offset:512
	v_cndmask_b32_e32 v67, v164, v67, vcc
	v_cndmask_b32_e32 v66, v164, v66, vcc
	v_cvt_pk_bf16_f32 v68, v68, v69
	v_cvt_pk_bf16_f32 v69, v70, v71
	v_cndmask_b32_e32 v65, v164, v65, vcc
	v_cndmask_b32_e32 v64, v164, v64, vcc
	global_store_dwordx2 v[78:79], v[68:69], off offset:256
	global_store_dwordx4 v[96:97], v[64:67], off offset:576
	s_nop 1
	v_cvt_pk_bf16_f32 v64, v64, v65
	v_cvt_pk_bf16_f32 v65, v66, v67
	global_store_dwordx2 v[78:79], v[64:65], off offset:288
	ds_read_b64 v[68:69], v165 offset:8448
	v_add_u32_e32 v64, 32, v162
	v_ashrrev_i32_e32 v65, 31, v64
	v_lshlrev_b64 v[64:65], 10, v[64:65]
	v_lshl_add_u64 v[70:71], v[64:65], 0, v[160:161]
	s_waitcnt lgkmcnt(0)
	v_sub_f32_e32 v65, v117, v68
	v_sub_f32_e32 v64, v116, v68
	v_sub_f32_e32 v67, v119, v68
	v_sub_f32_e32 v66, v118, v68
	v_pk_mul_f32 v[66:67], v[68:69], v[66:67] op_sel:[1,0]
	v_pk_mul_f32 v[64:65], v[68:69], v[64:65] op_sel:[1,0]
	v_pk_fma_f32 v[66:67], v[158:159], v[66:67], v[154:155]
	v_pk_fma_f32 v[64:65], v[156:157], v[64:65], v[152:153]
	v_cndmask_b32_e32 v67, v164, v67, vcc
	v_cndmask_b32_e32 v66, v164, v66, vcc
	v_cndmask_b32_e32 v65, v164, v65, vcc
	v_cndmask_b32_e32 v64, v164, v64, vcc
	v_lshl_add_u64 v[72:73], v[70:71], 2, s[72:73]
	global_store_dwordx4 v[72:73], v[64:67], off
	v_lshl_add_u64 v[70:71], v[70:71], 1, s[14:15]
	s_nop 0
	v_cvt_pk_bf16_f32 v64, v64, v65
	v_cvt_pk_bf16_f32 v65, v66, v67
	global_store_dwordx2 v[70:71], v[64:65], off
	v_sub_f32_e32 v65, v113, v68
	v_sub_f32_e32 v64, v112, v68
	v_sub_f32_e32 v67, v115, v68
	v_sub_f32_e32 v66, v114, v68
	v_pk_mul_f32 v[66:67], v[68:69], v[66:67] op_sel:[1,0]
	v_pk_mul_f32 v[64:65], v[68:69], v[64:65] op_sel:[1,0]
	v_pk_fma_f32 v[66:67], v[146:147], v[66:67], v[150:151]
	v_pk_fma_f32 v[64:65], v[144:145], v[64:65], v[148:149]
	v_cndmask_b32_e32 v67, v164, v67, vcc
	v_cndmask_b32_e32 v66, v164, v66, vcc
	v_cndmask_b32_e32 v65, v164, v65, vcc
	v_cndmask_b32_e32 v64, v164, v64, vcc
	global_store_dwordx4 v[72:73], v[64:67], off offset:64
	s_nop 1
	v_cvt_pk_bf16_f32 v64, v64, v65
	v_cvt_pk_bf16_f32 v65, v66, v67
	global_store_dwordx2 v[70:71], v[64:65], off offset:32
	v_sub_f32_e32 v65, v89, v68
	v_sub_f32_e32 v64, v88, v68
	v_sub_f32_e32 v67, v91, v68
	v_sub_f32_e32 v66, v90, v68
	v_pk_mul_f32 v[66:67], v[68:69], v[66:67] op_sel:[1,0]
	v_pk_mul_f32 v[64:65], v[68:69], v[64:65] op_sel:[1,0]
	v_pk_fma_f32 v[66:67], v[142:143], v[66:67], v[138:139]
	v_pk_fma_f32 v[64:65], v[140:141], v[64:65], v[136:137]
	v_cndmask_b32_e32 v67, v164, v67, vcc
	v_cndmask_b32_e32 v66, v164, v66, vcc
	v_cndmask_b32_e32 v65, v164, v65, vcc
	v_cndmask_b32_e32 v64, v164, v64, vcc
	global_store_dwordx4 v[72:73], v[64:67], off offset:512
	s_nop 1
	v_cvt_pk_bf16_f32 v64, v64, v65
	v_cvt_pk_bf16_f32 v65, v66, v67
	global_store_dwordx2 v[70:71], v[64:65], off offset:256
	v_sub_f32_e32 v65, v81, v68
	v_sub_f32_e32 v64, v80, v68
	v_sub_f32_e32 v67, v83, v68
	v_sub_f32_e32 v66, v82, v68
	v_pk_mul_f32 v[66:67], v[68:69], v[66:67] op_sel:[1,0]
	v_pk_mul_f32 v[64:65], v[68:69], v[64:65] op_sel:[1,0]
	v_pk_fma_f32 v[66:67], v[130:131], v[66:67], v[134:135]
	v_pk_fma_f32 v[64:65], v[128:129], v[64:65], v[132:133]
	v_cndmask_b32_e32 v67, v164, v67, vcc
	v_cndmask_b32_e32 v66, v164, v66, vcc
	v_cndmask_b32_e32 v65, v164, v65, vcc
	v_cndmask_b32_e32 v64, v164, v64, vcc
	global_store_dwordx4 v[72:73], v[64:67], off offset:576
	s_nop 1
	v_cvt_pk_bf16_f32 v64, v64, v65
	v_cvt_pk_bf16_f32 v65, v66, v67
	global_store_dwordx2 v[70:71], v[64:65], off offset:288
	ds_read_b64 v[68:69], v165 offset:8576
	v_add_u32_e32 v64, 48, v162
	v_ashrrev_i32_e32 v65, 31, v64
	v_lshlrev_b64 v[64:65], 10, v[64:65]
	v_lshl_add_u64 v[70:71], v[64:65], 0, v[160:161]
	s_waitcnt lgkmcnt(0)
	v_sub_f32_e32 v65, v125, v68
	v_sub_f32_e32 v64, v124, v68
	v_sub_f32_e32 v67, v127, v68
	v_sub_f32_e32 v66, v126, v68
	v_pk_mul_f32 v[66:67], v[68:69], v[66:67] op_sel:[1,0]
	v_pk_mul_f32 v[64:65], v[68:69], v[64:65] op_sel:[1,0]
	v_pk_fma_f32 v[66:67], v[158:159], v[66:67], v[154:155]
	v_pk_fma_f32 v[64:65], v[156:157], v[64:65], v[152:153]
	v_cndmask_b32_e32 v67, v164, v67, vcc
	v_cndmask_b32_e32 v66, v164, v66, vcc
	v_cndmask_b32_e32 v65, v164, v65, vcc
	v_cndmask_b32_e32 v64, v164, v64, vcc
	v_lshl_add_u64 v[72:73], v[70:71], 2, s[72:73]
	global_store_dwordx4 v[72:73], v[64:67], off
	v_lshl_add_u64 v[70:71], v[70:71], 1, s[14:15]
	s_nop 0
	v_cvt_pk_bf16_f32 v64, v64, v65
	v_cvt_pk_bf16_f32 v65, v66, v67
	global_store_dwordx2 v[70:71], v[64:65], off
	v_sub_f32_e32 v65, v121, v68
	v_sub_f32_e32 v64, v120, v68
	v_sub_f32_e32 v67, v123, v68
	v_sub_f32_e32 v66, v122, v68
	v_pk_mul_f32 v[66:67], v[68:69], v[66:67] op_sel:[1,0]
	v_pk_mul_f32 v[64:65], v[68:69], v[64:65] op_sel:[1,0]
	v_pk_fma_f32 v[66:67], v[146:147], v[66:67], v[150:151]
	v_pk_fma_f32 v[64:65], v[144:145], v[64:65], v[148:149]
	v_cndmask_b32_e32 v67, v164, v67, vcc
	v_cndmask_b32_e32 v66, v164, v66, vcc
	v_cndmask_b32_e32 v65, v164, v65, vcc
	v_cndmask_b32_e32 v64, v164, v64, vcc
	global_store_dwordx4 v[72:73], v[64:67], off offset:64
	s_nop 1
	v_cvt_pk_bf16_f32 v64, v64, v65
	v_cvt_pk_bf16_f32 v65, v66, v67
	global_store_dwordx2 v[70:71], v[64:65], off offset:32
	v_sub_f32_e32 v65, v105, v68
	v_sub_f32_e32 v64, v104, v68
	v_sub_f32_e32 v67, v107, v68
	v_sub_f32_e32 v66, v106, v68
	v_pk_mul_f32 v[66:67], v[68:69], v[66:67] op_sel:[1,0]
	v_pk_mul_f32 v[64:65], v[68:69], v[64:65] op_sel:[1,0]
	v_pk_fma_f32 v[66:67], v[142:143], v[66:67], v[138:139]
	v_pk_fma_f32 v[64:65], v[140:141], v[64:65], v[136:137]
	v_cndmask_b32_e32 v67, v164, v67, vcc
	v_cndmask_b32_e32 v66, v164, v66, vcc
	v_cndmask_b32_e32 v65, v164, v65, vcc
	v_cndmask_b32_e32 v64, v164, v64, vcc
	global_store_dwordx4 v[72:73], v[64:67], off offset:512
	s_nop 1
	v_cvt_pk_bf16_f32 v64, v64, v65
	v_cvt_pk_bf16_f32 v65, v66, v67
	global_store_dwordx2 v[70:71], v[64:65], off offset:256
	v_sub_f32_e32 v65, v93, v68
	v_sub_f32_e32 v64, v92, v68
	v_sub_f32_e32 v67, v95, v68
	v_sub_f32_e32 v66, v94, v68
	v_pk_mul_f32 v[66:67], v[68:69], v[66:67] op_sel:[1,0]
	v_pk_mul_f32 v[64:65], v[68:69], v[64:65] op_sel:[1,0]
	v_pk_fma_f32 v[66:67], v[130:131], v[66:67], v[134:135]
	v_pk_fma_f32 v[64:65], v[128:129], v[64:65], v[132:133]
	v_cndmask_b32_e32 v67, v164, v67, vcc
	v_cndmask_b32_e32 v66, v164, v66, vcc
	v_cndmask_b32_e32 v65, v164, v65, vcc
	v_cndmask_b32_e32 v64, v164, v64, vcc
	global_store_dwordx4 v[72:73], v[64:67], off offset:576
	s_nop 1
	v_cvt_pk_bf16_f32 v64, v64, v65
	v_cvt_pk_bf16_f32 v65, v66, v67
	global_store_dwordx2 v[70:71], v[64:65], off offset:288
	ds_read_b64 v[64:65], v165 offset:9216
	v_add_u32_e32 v66, 0x80, v162
	v_ashrrev_i32_e32 v67, 31, v66
	v_lshlrev_b64 v[66:67], 10, v[66:67]
	v_lshl_add_u64 v[66:67], v[66:67], 0, v[160:161]
	s_waitcnt lgkmcnt(0)
	v_sub_f32_e32 v61, v61, v64
	v_sub_f32_e32 v60, v60, v64
	v_sub_f32_e32 v63, v63, v64
	v_sub_f32_e32 v62, v62, v64
	v_pk_mul_f32 v[62:63], v[64:65], v[62:63] op_sel:[1,0]
	v_pk_mul_f32 v[60:61], v[64:65], v[60:61] op_sel:[1,0]
	v_sub_f32_e32 v57, v57, v64
	v_sub_f32_e32 v56, v56, v64
	v_sub_f32_e32 v59, v59, v64
	v_sub_f32_e32 v58, v58, v64
	v_pk_fma_f32 v[60:61], v[156:157], v[60:61], v[152:153]
	v_pk_fma_f32 v[62:63], v[158:159], v[62:63], v[154:155]
	v_pk_mul_f32 v[58:59], v[64:65], v[58:59] op_sel:[1,0]
	v_pk_mul_f32 v[56:57], v[64:65], v[56:57] op_sel:[1,0]
	v_sub_f32_e32 v53, v53, v64
	v_sub_f32_e32 v52, v52, v64
	v_sub_f32_e32 v55, v55, v64
	v_sub_f32_e32 v54, v54, v64
	v_cndmask_b32_e32 v63, v164, v63, vcc
	v_cndmask_b32_e32 v62, v164, v62, vcc
	v_cndmask_b32_e32 v61, v164, v61, vcc
	v_cndmask_b32_e32 v60, v164, v60, vcc
	v_lshl_add_u64 v[68:69], v[66:67], 2, s[72:73]
	v_pk_fma_f32 v[56:57], v[144:145], v[56:57], v[148:149]
	v_pk_fma_f32 v[58:59], v[146:147], v[58:59], v[150:151]
	v_pk_mul_f32 v[54:55], v[64:65], v[54:55] op_sel:[1,0]
	v_pk_mul_f32 v[52:53], v[64:65], v[52:53] op_sel:[1,0]
	v_sub_f32_e32 v49, v49, v64
	v_sub_f32_e32 v48, v48, v64
	v_sub_f32_e32 v51, v51, v64
	v_sub_f32_e32 v50, v50, v64
	global_store_dwordx4 v[68:69], v[60:63], off
	v_cndmask_b32_e32 v59, v164, v59, vcc
	v_cndmask_b32_e32 v58, v164, v58, vcc
	v_cvt_pk_bf16_f32 v60, v60, v61
	v_cvt_pk_bf16_f32 v61, v62, v63
	v_lshl_add_u64 v[62:63], v[66:67], 1, s[14:15]
	v_cndmask_b32_e32 v57, v164, v57, vcc
	v_cndmask_b32_e32 v56, v164, v56, vcc
	v_pk_fma_f32 v[52:53], v[140:141], v[52:53], v[136:137]
	v_pk_fma_f32 v[54:55], v[142:143], v[54:55], v[138:139]
	v_pk_mul_f32 v[50:51], v[64:65], v[50:51] op_sel:[1,0]
	v_pk_mul_f32 v[48:49], v[64:65], v[48:49] op_sel:[1,0]
	global_store_dwordx2 v[62:63], v[60:61], off
	global_store_dwordx4 v[68:69], v[56:59], off offset:64
	v_cndmask_b32_e32 v55, v164, v55, vcc
	v_cndmask_b32_e32 v54, v164, v54, vcc
	v_cvt_pk_bf16_f32 v56, v56, v57
	v_cvt_pk_bf16_f32 v57, v58, v59
	v_cndmask_b32_e32 v53, v164, v53, vcc
	v_cndmask_b32_e32 v52, v164, v52, vcc
	v_pk_fma_f32 v[48:49], v[128:129], v[48:49], v[132:133]
	v_pk_fma_f32 v[50:51], v[130:131], v[50:51], v[134:135]
	global_store_dwordx2 v[62:63], v[56:57], off offset:32
	global_store_dwordx4 v[68:69], v[52:55], off offset:512
	v_cndmask_b32_e32 v51, v164, v51, vcc
	v_cndmask_b32_e32 v50, v164, v50, vcc
	v_cvt_pk_bf16_f32 v52, v52, v53
	v_cvt_pk_bf16_f32 v53, v54, v55
	v_cndmask_b32_e32 v49, v164, v49, vcc
	v_cndmask_b32_e32 v48, v164, v48, vcc
	global_store_dwordx2 v[62:63], v[52:53], off offset:256
	global_store_dwordx4 v[68:69], v[48:51], off offset:576
	s_nop 1
	v_cvt_pk_bf16_f32 v48, v48, v49
	v_cvt_pk_bf16_f32 v49, v50, v51
	global_store_dwordx2 v[62:63], v[48:49], off offset:288
	ds_read_b64 v[48:49], v165 offset:9344
	v_add_u32_e32 v50, 0x90, v162
	v_ashrrev_i32_e32 v51, 31, v50
	v_lshlrev_b64 v[50:51], 10, v[50:51]
	v_lshl_add_u64 v[50:51], v[50:51], 0, v[160:161]
	s_waitcnt lgkmcnt(0)
	v_sub_f32_e32 v45, v45, v48
	v_sub_f32_e32 v44, v44, v48
	v_sub_f32_e32 v47, v47, v48
	v_sub_f32_e32 v46, v46, v48
	v_pk_mul_f32 v[46:47], v[48:49], v[46:47] op_sel:[1,0]
	v_pk_mul_f32 v[44:45], v[48:49], v[44:45] op_sel:[1,0]
	v_sub_f32_e32 v41, v41, v48
	v_sub_f32_e32 v40, v40, v48
	v_sub_f32_e32 v43, v43, v48
	v_sub_f32_e32 v42, v42, v48
	v_pk_fma_f32 v[44:45], v[156:157], v[44:45], v[152:153]
	v_pk_fma_f32 v[46:47], v[158:159], v[46:47], v[154:155]
	v_pk_mul_f32 v[42:43], v[48:49], v[42:43] op_sel:[1,0]
	v_pk_mul_f32 v[40:41], v[48:49], v[40:41] op_sel:[1,0]
	v_sub_f32_e32 v37, v37, v48
	v_sub_f32_e32 v36, v36, v48
	v_sub_f32_e32 v39, v39, v48
	v_sub_f32_e32 v38, v38, v48
	v_cndmask_b32_e32 v47, v164, v47, vcc
	v_cndmask_b32_e32 v46, v164, v46, vcc
	v_cndmask_b32_e32 v45, v164, v45, vcc
	v_cndmask_b32_e32 v44, v164, v44, vcc
	v_lshl_add_u64 v[52:53], v[50:51], 2, s[72:73]
	v_pk_fma_f32 v[40:41], v[144:145], v[40:41], v[148:149]
	v_pk_fma_f32 v[42:43], v[146:147], v[42:43], v[150:151]
	v_pk_mul_f32 v[38:39], v[48:49], v[38:39] op_sel:[1,0]
	v_pk_mul_f32 v[36:37], v[48:49], v[36:37] op_sel:[1,0]
	v_sub_f32_e32 v33, v33, v48
	v_sub_f32_e32 v32, v32, v48
	v_sub_f32_e32 v35, v35, v48
	v_sub_f32_e32 v34, v34, v48
	global_store_dwordx4 v[52:53], v[44:47], off
	v_cndmask_b32_e32 v43, v164, v43, vcc
	v_cndmask_b32_e32 v42, v164, v42, vcc
	v_cvt_pk_bf16_f32 v44, v44, v45
	v_cvt_pk_bf16_f32 v45, v46, v47
	v_lshl_add_u64 v[46:47], v[50:51], 1, s[14:15]
	v_cndmask_b32_e32 v41, v164, v41, vcc
	v_cndmask_b32_e32 v40, v164, v40, vcc
	v_pk_fma_f32 v[36:37], v[140:141], v[36:37], v[136:137]
	v_pk_fma_f32 v[38:39], v[142:143], v[38:39], v[138:139]
	v_pk_mul_f32 v[34:35], v[48:49], v[34:35] op_sel:[1,0]
	v_pk_mul_f32 v[32:33], v[48:49], v[32:33] op_sel:[1,0]
	global_store_dwordx2 v[46:47], v[44:45], off
	global_store_dwordx4 v[52:53], v[40:43], off offset:64
	v_cndmask_b32_e32 v39, v164, v39, vcc
	v_cndmask_b32_e32 v38, v164, v38, vcc
	v_cvt_pk_bf16_f32 v40, v40, v41
	v_cvt_pk_bf16_f32 v41, v42, v43
	v_cndmask_b32_e32 v37, v164, v37, vcc
	v_cndmask_b32_e32 v36, v164, v36, vcc
	v_pk_fma_f32 v[32:33], v[128:129], v[32:33], v[132:133]
	v_pk_fma_f32 v[34:35], v[130:131], v[34:35], v[134:135]
	global_store_dwordx2 v[46:47], v[40:41], off offset:32
	global_store_dwordx4 v[52:53], v[36:39], off offset:512
	v_cndmask_b32_e32 v35, v164, v35, vcc
	v_cndmask_b32_e32 v34, v164, v34, vcc
	v_cvt_pk_bf16_f32 v36, v36, v37
	v_cvt_pk_bf16_f32 v37, v38, v39
	v_cndmask_b32_e32 v33, v164, v33, vcc
	v_cndmask_b32_e32 v32, v164, v32, vcc
	global_store_dwordx2 v[46:47], v[36:37], off offset:256
	global_store_dwordx4 v[52:53], v[32:35], off offset:576
	s_nop 1
	v_cvt_pk_bf16_f32 v32, v32, v33
	v_cvt_pk_bf16_f32 v33, v34, v35
	global_store_dwordx2 v[46:47], v[32:33], off offset:288
	ds_read_b64 v[32:33], v165 offset:9472
	v_add_u32_e32 v34, 0xa0, v162
	v_ashrrev_i32_e32 v35, 31, v34
	v_lshlrev_b64 v[34:35], 10, v[34:35]
	v_lshl_add_u64 v[34:35], v[34:35], 0, v[160:161]
	s_waitcnt lgkmcnt(0)
	v_sub_f32_e32 v29, v29, v32
	v_sub_f32_e32 v28, v28, v32
	v_sub_f32_e32 v31, v31, v32
	v_sub_f32_e32 v30, v30, v32
	v_pk_mul_f32 v[30:31], v[32:33], v[30:31] op_sel:[1,0]
	v_pk_mul_f32 v[28:29], v[32:33], v[28:29] op_sel:[1,0]
	v_sub_f32_e32 v25, v25, v32
	v_sub_f32_e32 v24, v24, v32
	v_sub_f32_e32 v27, v27, v32
	v_sub_f32_e32 v26, v26, v32
	v_pk_fma_f32 v[28:29], v[156:157], v[28:29], v[152:153]
	v_pk_fma_f32 v[30:31], v[158:159], v[30:31], v[154:155]
	v_pk_mul_f32 v[26:27], v[32:33], v[26:27] op_sel:[1,0]
	v_pk_mul_f32 v[24:25], v[32:33], v[24:25] op_sel:[1,0]
	v_sub_f32_e32 v21, v21, v32
	v_sub_f32_e32 v20, v20, v32
	v_sub_f32_e32 v23, v23, v32
	v_sub_f32_e32 v22, v22, v32
	v_cndmask_b32_e32 v31, v164, v31, vcc
	v_cndmask_b32_e32 v30, v164, v30, vcc
	v_cndmask_b32_e32 v29, v164, v29, vcc
	v_cndmask_b32_e32 v28, v164, v28, vcc
	v_lshl_add_u64 v[36:37], v[34:35], 2, s[72:73]
	v_pk_fma_f32 v[24:25], v[144:145], v[24:25], v[148:149]
	v_pk_fma_f32 v[26:27], v[146:147], v[26:27], v[150:151]
	v_pk_mul_f32 v[22:23], v[32:33], v[22:23] op_sel:[1,0]
	v_pk_mul_f32 v[20:21], v[32:33], v[20:21] op_sel:[1,0]
	v_sub_f32_e32 v17, v17, v32
	v_sub_f32_e32 v16, v16, v32
	v_sub_f32_e32 v19, v19, v32
	v_sub_f32_e32 v18, v18, v32
	global_store_dwordx4 v[36:37], v[28:31], off
	v_cndmask_b32_e32 v27, v164, v27, vcc
	v_cndmask_b32_e32 v26, v164, v26, vcc
	v_cvt_pk_bf16_f32 v28, v28, v29
	v_cvt_pk_bf16_f32 v29, v30, v31
	v_lshl_add_u64 v[30:31], v[34:35], 1, s[14:15]
	v_cndmask_b32_e32 v25, v164, v25, vcc
	v_cndmask_b32_e32 v24, v164, v24, vcc
	v_pk_fma_f32 v[20:21], v[140:141], v[20:21], v[136:137]
	v_pk_fma_f32 v[22:23], v[142:143], v[22:23], v[138:139]
	v_pk_mul_f32 v[18:19], v[32:33], v[18:19] op_sel:[1,0]
	v_pk_mul_f32 v[16:17], v[32:33], v[16:17] op_sel:[1,0]
	global_store_dwordx2 v[30:31], v[28:29], off
	global_store_dwordx4 v[36:37], v[24:27], off offset:64
	v_cndmask_b32_e32 v23, v164, v23, vcc
	v_cndmask_b32_e32 v22, v164, v22, vcc
	v_cvt_pk_bf16_f32 v24, v24, v25
	v_cvt_pk_bf16_f32 v25, v26, v27
	v_cndmask_b32_e32 v21, v164, v21, vcc
	v_cndmask_b32_e32 v20, v164, v20, vcc
	v_pk_fma_f32 v[16:17], v[128:129], v[16:17], v[132:133]
	v_pk_fma_f32 v[18:19], v[130:131], v[18:19], v[134:135]
	global_store_dwordx2 v[30:31], v[24:25], off offset:32
	global_store_dwordx4 v[36:37], v[20:23], off offset:512
	v_cndmask_b32_e32 v19, v164, v19, vcc
	v_cndmask_b32_e32 v18, v164, v18, vcc
	v_cvt_pk_bf16_f32 v20, v20, v21
	v_cvt_pk_bf16_f32 v21, v22, v23
	v_cndmask_b32_e32 v17, v164, v17, vcc
	v_cndmask_b32_e32 v16, v164, v16, vcc
	global_store_dwordx2 v[30:31], v[20:21], off offset:256
	global_store_dwordx4 v[36:37], v[16:19], off offset:576
	s_nop 1
	v_cvt_pk_bf16_f32 v16, v16, v17
	v_cvt_pk_bf16_f32 v17, v18, v19
	global_store_dwordx2 v[30:31], v[16:17], off offset:288
	ds_read_b64 v[16:17], v165 offset:9600
	v_add_u32_e32 v18, 0xb0, v162
	v_ashrrev_i32_e32 v19, 31, v18
	v_lshlrev_b64 v[18:19], 10, v[18:19]
	v_lshl_add_u64 v[18:19], v[18:19], 0, v[160:161]
	s_waitcnt lgkmcnt(0)
	v_sub_f32_e32 v13, v13, v16
	v_sub_f32_e32 v12, v12, v16
	v_sub_f32_e32 v15, v15, v16
	v_sub_f32_e32 v14, v14, v16
	v_pk_mul_f32 v[14:15], v[16:17], v[14:15] op_sel:[1,0]
	v_pk_mul_f32 v[12:13], v[16:17], v[12:13] op_sel:[1,0]
	v_sub_f32_e32 v9, v9, v16
	v_sub_f32_e32 v8, v8, v16
	v_sub_f32_e32 v11, v11, v16
	v_sub_f32_e32 v10, v10, v16
	v_pk_fma_f32 v[12:13], v[156:157], v[12:13], v[152:153]
	v_pk_fma_f32 v[14:15], v[158:159], v[14:15], v[154:155]
	v_pk_mul_f32 v[10:11], v[16:17], v[10:11] op_sel:[1,0]
	v_pk_mul_f32 v[8:9], v[16:17], v[8:9] op_sel:[1,0]
	v_sub_f32_e32 v5, v5, v16
	v_sub_f32_e32 v4, v4, v16
	v_sub_f32_e32 v7, v7, v16
	v_sub_f32_e32 v6, v6, v16
	v_cndmask_b32_e32 v15, v164, v15, vcc
	v_cndmask_b32_e32 v14, v164, v14, vcc
	v_cndmask_b32_e32 v13, v164, v13, vcc
	v_cndmask_b32_e32 v12, v164, v12, vcc
	v_lshl_add_u64 v[20:21], v[18:19], 2, s[72:73]
	v_pk_fma_f32 v[8:9], v[144:145], v[8:9], v[148:149]
	v_pk_fma_f32 v[10:11], v[146:147], v[10:11], v[150:151]
	v_pk_mul_f32 v[6:7], v[16:17], v[6:7] op_sel:[1,0]
	v_pk_mul_f32 v[4:5], v[16:17], v[4:5] op_sel:[1,0]
	v_sub_f32_e32 v1, v1, v16
	v_sub_f32_e32 v0, v0, v16
	v_sub_f32_e32 v3, v3, v16
	v_sub_f32_e32 v2, v2, v16
	global_store_dwordx4 v[20:21], v[12:15], off
	v_cndmask_b32_e32 v11, v164, v11, vcc
	v_cndmask_b32_e32 v10, v164, v10, vcc
	v_cvt_pk_bf16_f32 v12, v12, v13
	v_cvt_pk_bf16_f32 v13, v14, v15
	v_lshl_add_u64 v[14:15], v[18:19], 1, s[14:15]
	v_cndmask_b32_e32 v9, v164, v9, vcc
	v_cndmask_b32_e32 v8, v164, v8, vcc
	v_pk_fma_f32 v[4:5], v[140:141], v[4:5], v[136:137]
	v_pk_fma_f32 v[6:7], v[142:143], v[6:7], v[138:139]
	v_pk_mul_f32 v[2:3], v[16:17], v[2:3] op_sel:[1,0]
	v_pk_mul_f32 v[0:1], v[16:17], v[0:1] op_sel:[1,0]
	global_store_dwordx2 v[14:15], v[12:13], off
	global_store_dwordx4 v[20:21], v[8:11], off offset:64
	v_cndmask_b32_e32 v7, v164, v7, vcc
	v_cndmask_b32_e32 v6, v164, v6, vcc
	v_cvt_pk_bf16_f32 v8, v8, v9
	v_cvt_pk_bf16_f32 v9, v10, v11
	v_cndmask_b32_e32 v5, v164, v5, vcc
	v_cndmask_b32_e32 v4, v164, v4, vcc
	v_pk_fma_f32 v[0:1], v[128:129], v[0:1], v[132:133]
	v_pk_fma_f32 v[2:3], v[130:131], v[2:3], v[134:135]
	global_store_dwordx2 v[14:15], v[8:9], off offset:32
	global_store_dwordx4 v[20:21], v[4:7], off offset:512
	v_cndmask_b32_e32 v3, v164, v3, vcc
	v_cndmask_b32_e32 v2, v164, v2, vcc
	v_cvt_pk_bf16_f32 v4, v4, v5
	v_cvt_pk_bf16_f32 v5, v6, v7
	v_cndmask_b32_e32 v1, v164, v1, vcc
	v_cndmask_b32_e32 v0, v164, v0, vcc
	global_store_dwordx2 v[14:15], v[4:5], off offset:256
	global_store_dwordx4 v[20:21], v[0:3], off offset:576
	s_nop 1
	v_cvt_pk_bf16_f32 v0, v0, v1
	v_cvt_pk_bf16_f32 v1, v2, v3
	global_store_dwordx2 v[14:15], v[0:1], off offset:288

.LBB0_878:
	s_cmp_lt_i32 s78, 10
	s_cselect_b64 s[2:3], -1, 0
	s_and_b64 s[2:3], s[2:3], s[0:1]
	s_xor_b64 s[0:1], s[2:3], -1
	s_or_b64 s[0:1], s[92:93], s[0:1]
	s_and_b64 vcc, exec, s[0:1]
	s_cbranch_vccnz .LBB0_882
	s_cmpk_gt_i32 s84, 0x3fff
	s_cbranch_scc1 .LBB0_882
	v_mbcnt_lo_u32_b32 v2, -1, 0
	v_mbcnt_hi_u32_b32 v2, -1, v2
	v_and_b32_e32 v3, 64, v2
	v_add_u32_e32 v3, 64, v3
	v_xor_b32_e32 v8, 1, v2
	v_cmp_lt_i32_e32 vcc, v8, v3
	s_ashr_i32 s85, s84, 31
	s_lshl_b64 s[0:1], s[84:85], 12
	v_cndmask_b32_e32 v8, v2, v8, vcc
	v_lshlrev_b32_e32 v12, 2, v8
	v_xor_b32_e32 v8, 2, v2
	v_cmp_lt_i32_e32 vcc, v8, v3
	s_add_u32 s0, s76, s0
	v_lshlrev_b32_e32 v0, 4, v170
	v_cndmask_b32_e32 v8, v2, v8, vcc
	v_lshlrev_b32_e32 v13, 2, v8
	v_xor_b32_e32 v8, 4, v2
	v_cmp_lt_i32_e32 vcc, v8, v3
	v_mov_b32_e32 v1, 0
	s_addc_u32 s1, s77, s1
	v_cndmask_b32_e32 v8, v2, v8, vcc
	v_lshlrev_b32_e32 v14, 2, v8
	v_xor_b32_e32 v8, 8, v2
	v_cmp_lt_i32_e32 vcc, v8, v3
	s_ashr_i32 s87, s86, 31
	s_nop 0
	v_cndmask_b32_e32 v8, v2, v8, vcc
	v_lshlrev_b32_e32 v15, 2, v8
	v_xor_b32_e32 v8, 16, v2
	v_cmp_lt_i32_e32 vcc, v8, v3
	v_readlane_b32 s22, v246, 34
	s_lshl_b64 s[4:5], s[84:85], 11
	v_cndmask_b32_e32 v8, v2, v8, vcc
	v_lshlrev_b32_e32 v16, 2, v8
	v_xor_b32_e32 v8, 32, v2
	v_cmp_lt_i32_e32 vcc, v8, v3
	v_readlane_b32 s10, v246, 22
	v_readlane_b32 s11, v246, 23
	v_cndmask_b32_e32 v2, v2, v8, vcc
	v_lshlrev_b32_e32 v17, 2, v2
	v_lshl_add_u64 v[2:3], s[0:1], 0, v[0:1]
	s_mov_b64 s[0:1], 0xc000c00
	v_lshl_add_u64 v[8:9], v[2:3], 0, s[0:1]
	s_lshl_b64 s[0:1], s[86:87], 12
	v_readlane_b32 s12, v246, 24
	v_readlane_b32 s13, v246, 25
	v_readlane_b32 s23, v246, 35
	s_add_u32 s4, s22, s4
	v_lshl_add_u64 v[4:5], s[10:11], 0, v[0:1]
	v_lshl_add_u64 v[6:7], s[12:13], 0, v[0:1]
	v_lshlrev_b32_e32 v0, 3, v170
	s_addc_u32 s5, s23, s5
	v_lshl_add_u64 v[0:1], s[4:5], 0, v[0:1]
	s_mov_b64 s[4:5], 0x400
	v_lshl_add_u64 v[10:11], v[0:1], 0, s[4:5]
	s_lshl_b64 s[4:5], s[86:87], 11
	v_mov_b32_e32 v18, 0x3727c5ac
	s_mov_b32 s8, s84
	v_readlane_b32 s14, v246, 26
	v_readlane_b32 s15, v246, 27
	v_readlane_b32 s17, v246, 29
	v_readlane_b32 s18, v246, 30
	v_readlane_b32 s19, v246, 31
	v_readlane_b32 s20, v246, 32
	v_readlane_b32 s21, v246, 33

.LBB0_932:
	s_cmp_lt_i32 s78, 11
	s_cselect_b64 s[2:3], -1, 0
	s_and_b64 s[2:3], s[2:3], s[0:1]
	s_andn2_b64 vcc, exec, s[2:3]
	s_cbranch_vccnz .LBB0_949
	s_cmpk_gt_i32 s74, 0x57f
	v_readfirstlane_b32 s1, v171
	s_cbranch_scc1 .LBB0_949
	v_lshrrev_b32_e32 v1, 1, v171
	v_and_b32_e32 v9, 24, v1
	v_lshrrev_b32_e32 v1, 5, v171
	v_bitop3_b32 v8, v176, v178, 48 bitop3:0x6c
	v_and_b32_e32 v1, 4, v1
	v_bfe_u32 v2, v171, 2, 2
	s_movk_i32 s0, 0x70
	v_or_b32_e32 v0, v8, v173
	v_or3_b32 v1, v1, v2, v9
	v_and_or_b32 v2, v177, s0, v175
	s_movk_i32 s0, 0x60
	v_add_u32_e32 v10, 0x2000, v176
	v_and_or_b32 v3, v177, s0, v1
	v_lshl_or_b32 v128, v2, 11, v0
	v_lshrrev_b32_e32 v2, 7, v10
	s_movk_i32 s0, 0xf0
	v_lshl_or_b32 v130, v3, 11, v0
	v_and_or_b32 v3, v2, s0, v175
	s_movk_i32 s0, 0xe0
	s_ashr_i32 s29, s74, 31
	v_and_or_b32 v1, v2, s0, v1
	s_lshr_b32 s0, s29, 29
	s_add_i32 s0, s74, s0
	s_lshr_b32 s8, s1, 6
	s_ashr_i32 s4, s0, 3
	s_and_b32 s0, s0, -8
	s_lshr_b32 s10, s1, 8
	s_lshl_b32 s28, s8, 10
	s_sub_i32 s0, s74, s0
	s_cmp_lt_i32 s0, 0
	s_movk_i32 s30, 0xb1
	s_cselect_b32 s5, s30, 0xb0
	s_mul_i32 s0, s0, s5
	s_add_i32 s0, s0, s4
	s_mul_hi_i32 s4, s0, 0x2e8ba2e9
	s_lshr_b32 s5, s4, 31
	s_ashr_i32 s4, s4, 5
	s_add_i32 s4, s4, s5
	s_lshl_b32 s5, s4, 3
	s_mulk_i32 s4, 0xb0
	s_sub_i32 s4, s0, s4
	s_sext_i32_i16 s0, s4
	s_bfe_u32 s0, s0, 0x3001c
	s_add_i32 s9, s4, s0
	s_sext_i32_i16 s0, s9
	s_and_b32 s9, s9, 0xfff8
	s_sub_i32 s4, s4, s9
	s_sext_i32_i16 s4, s4
	s_lshr_b32 s0, s0, 3
	s_add_i32 s20, s5, s4
	s_ashr_i32 s21, s20, 31
	s_bfe_i64 s[12:13], s[0:1], 0x100000
	s_lshl_b64 s[4:5], s[20:21], 19
	s_lshl_b64 s[12:13], s[12:13], 19
	v_readlane_b32 s14, v246, 44
	v_readlane_b32 s15, v246, 45
	s_add_u32 s24, s14, s12
	s_addc_u32 s25, s15, s13
	s_add_i32 s21, s28, 0
	s_add_i32 m0, s21, 0x10000
	global_load_lds_dwordx4 v130, s[24:25]
	s_add_i32 m0, s21, 0x12000
	v_lshl_or_b32 v134, v1, 11, v0
	s_add_u32 s12, s24, 0x40000
	v_readlane_b32 s48, v246, 32
	v_readlane_b32 s49, v246, 33
	global_load_lds_dwordx4 v134, s[24:25]
	s_addc_u32 s13, s25, 0
	s_add_i32 m0, s21, 0x14000
	v_readlane_b32 s50, v246, 34
	v_readlane_b32 s51, v246, 35
	s_mov_b64 s[16:17], s[48:49]
	global_load_lds_dwordx4 v130, s[12:13]
	s_add_i32 m0, s21, 0x16000
	s_mov_b64 s[18:19], s[50:51]
	s_add_u32 s22, s18, s4
	s_addc_u32 s23, s19, s5
	s_add_i32 s31, s21, 0x2000
	global_load_lds_dwordx4 v134, s[12:13]
	s_mov_b32 m0, s21
	s_add_u32 s4, s22, 0x40000
	v_lshl_or_b32 v132, v3, 11, v0
	global_load_lds_dwordx4 v128, s[22:23]
	s_mov_b32 m0, s31
	s_addc_u32 s5, s23, 0
	s_add_i32 s33, s21, 0x4000
	global_load_lds_dwordx4 v132, s[22:23]
	s_mov_b32 m0, s33
	s_add_i32 s34, s21, 0x6000
	global_load_lds_dwordx4 v128, s[4:5]
	s_mov_b32 m0, s34
	v_mov_b32_e32 v131, 0
	global_load_lds_dwordx4 v132, s[4:5]
	v_mov_b32_e32 v135, v131
	v_mov_b32_e32 v129, v131
	v_mov_b32_e32 v133, v131
	s_cmp_eq_u32 s10, 1
	s_mov_b32 s35, 0
	v_lshl_add_u64 v[6:7], s[24:25], 0, v[130:131]
	v_lshl_add_u64 v[4:5], s[24:25], 0, v[134:135]
	v_lshl_add_u64 v[0:1], s[22:23], 0, v[128:129]
	s_cselect_b64 s[4:5], -1, 0
	s_cmp_lg_u32 s10, 1
	v_lshl_add_u64 v[2:3], s[22:23], 0, v[132:133]
	s_cbranch_scc1 .LBB0_936
	s_barrier
.LBB0_936:
	s_lshl_b32 s8, s8, 5
	s_and_b32 s14, s8, 0x60
	s_mov_b64 s[8:9], 0x80
	v_readlane_b32 s16, v246, 48
	s_add_i32 m0, s21, 0x18000
	v_lshl_add_u64 v[6:7], v[6:7], 0, s[8:9]
	s_ashr_i32 s36, s16, 31
	s_lshl_b32 s11, s10, 13
	s_lshl_b32 s15, s14, 7
	global_load_lds_dwordx4 v[6:7], off
	v_lshl_add_u64 v[4:5], v[4:5], 0, s[8:9]
	s_add_i32 m0, s21, 0x1a000
	s_add_i32 s37, s21, 0x8000
	s_add_i32 s38, s21, 0xa000
	global_load_lds_dwordx4 v[4:5], off
	v_lshl_add_u64 v[0:1], v[0:1], 0, s[8:9]
	s_mov_b32 m0, s37
	s_add_u32 s12, s24, 0x40080
	global_load_lds_dwordx4 v[0:1], off
	v_lshl_add_u64 v[0:1], v[2:3], 0, s[8:9]
	s_mov_b32 m0, s38
	s_addc_u32 s13, s25, 0
	global_load_lds_dwordx4 v[0:1], off
	s_add_i32 m0, s21, 0x1c000
	v_lshl_add_u64 v[0:1], s[12:13], 0, v[130:131]
	global_load_lds_dwordx4 v[0:1], off
	v_lshl_add_u64 v[0:1], s[12:13], 0, v[134:135]
	s_add_i32 m0, s21, 0x1e000
	s_sext_i32_i16 s43, s0
	global_load_lds_dwordx4 v[0:1], off
	s_waitcnt vmcnt(8)
	s_barrier
	v_lshlrev_b32_e32 v0, 1, v9
	v_lshlrev_b32_e32 v1, 6, v171
	s_movk_i32 s0, 0x3c0
	v_and_or_b32 v1, v1, s0, v0
	v_and_b32_e32 v2, 32, v174
	v_lshl_or_b32 v0, v172, 6, v0
	v_bitop3_b32 v145, s15, v1, v2 bitop3:0xf6
	v_lshlrev_b32_e32 v1, 8, v171
	v_bitop3_b32 v0, v0, s11, v2 bitop3:0xde
	v_and_b32_e32 v1, 0x38000, v1
	v_lshlrev_b32_e32 v2, 11, v175
	v_or3_b32 v1, v8, v1, v2
	v_add_u32_e32 v136, v1, v173
	v_lshlrev_b32_e32 v1, 4, v10
	s_waitcnt vmcnt(6)
	s_cmpk_lt_u32 s1, 0x100
	v_and_b32_e32 v1, 0x78000, v1
	v_lshl_or_b32 v144, s10, 6, v172
	s_cselect_b64 s[10:11], -1, 0
	v_or3_b32 v1, v8, v1, v2
	s_add_i32 s40, 0, 0x10000
	s_add_i32 s41, 0, 0x14000
	s_mov_b32 s39, s16
	v_or_b32_e32 v146, s14, v9
	v_mov_b32_e32 v137, v131
	v_add_u32_e32 v138, v1, v173
	v_mov_b32_e32 v139, v131
	v_mov_b64_e32 v[140:141], 0x580
	v_mov_b64_e32 v[142:143], 0x57f
	v_add_u32_e32 v147, s40, v145
	v_add_u32_e32 v148, s41, v145
	v_add_u32_e32 v149, 0, v0
	s_movk_i32 s42, 0x1600
	s_barrier
	s_branch .LBB0_939

.LBB0_941:
	v_readlane_b32 s56, v246, 32
	v_readlane_b32 s57, v246, 33
	s_ashr_i32 s15, s14, 31
	v_readlane_b32 s58, v246, 34
	v_readlane_b32 s59, v246, 35
	s_mov_b64 s[48:49], s[56:57]
	s_lshl_b64 s[16:17], s[14:15], 19
	s_mov_b64 s[50:51], s[58:59]
	s_add_u32 s16, s50, s16
	s_addc_u32 s17, s51, s17
	s_and_b64 s[18:19], s[0:1], exec
	s_cselect_b32 s15, s17, s23
	s_cselect_b32 s44, s16, s22
	s_ashr_i32 s13, s12, 31
	s_lshl_b64 s[18:19], s[12:13], 19
	v_readlane_b32 s26, v246, 44
	v_readlane_b32 s27, v246, 45
	s_add_u32 s18, s26, s18
	s_addc_u32 s19, s27, s19
	s_and_b64 s[26:27], s[0:1], exec
	s_cselect_b32 s13, s19, s25
	s_cselect_b32 s45, s18, s24
	s_add_u32 s22, s22, 0x40080
	s_addc_u32 s23, s23, 0
	s_add_u32 s46, s24, 0x100
	s_addc_u32 s47, s25, 0
	s_mov_b32 s48, -2
	ds_read_b128 v[150:153], v147
	ds_read_b128 v[154:157], v147 offset:1024
	ds_read_b128 v[158:161], v147 offset:2048
	ds_read_b128 v[162:165], v147 offset:3072
	ds_read_b128 v[166:169], v148
	ds_read_b128 v[180:183], v148 offset:1024
	ds_read_b128 v[184:187], v148 offset:2048
	ds_read_b128 v[188:191], v148 offset:3072
	s_add_u32 s24, s22, 0xfffc0080
	s_addc_u32 s25, s23, -1
	s_cmp_eq_u32 s48, 12
	s_cselect_b32 s27, s15, s25
	s_cselect_b32 s26, s44, s24
	s_cselect_b32 s25, s13, s47
	s_cselect_b32 s24, s45, s46
	v_lshl_add_u64 v[224:225], s[22:23], 0, v[136:137]
	s_add_i32 m0, s21, 0xc000
	ds_read_b128 v[192:195], v149
	ds_read_b128 v[196:199], v149 offset:1024
	ds_read_b128 v[200:203], v149 offset:2048
	ds_read_b128 v[204:207], v149 offset:3072
	ds_read_b128 v[208:211], v149 offset:4096
	ds_read_b128 v[212:215], v149 offset:5120
	ds_read_b128 v[216:219], v149 offset:6144
	ds_read_b128 v[220:223], v149 offset:7168
	global_load_lds_dwordx4 v[224:225], off
	v_lshl_add_u64 v[224:225], s[22:23], 0, v[138:139]
	s_add_i32 m0, s21, 0xe000
	s_nop 0
	global_load_lds_dwordx4 v[224:225], off
	s_waitcnt vmcnt(8)
	s_waitcnt lgkmcnt(0)
	s_barrier
	s_waitcnt lgkmcnt(0)
	v_mfma_f32_16x16x32_bf16 v[124:127], v[150:153], v[192:195], 0
	v_mfma_f32_16x16x32_bf16 v[120:123], v[158:161], v[192:195], 0
	v_mfma_f32_16x16x32_bf16 v[108:111], v[150:153], v[200:203], 0
	v_mfma_f32_16x16x32_bf16 v[104:107], v[158:161], v[200:203], 0
	v_mfma_f32_16x16x32_bf16 v[92:95], v[150:153], v[208:211], 0
	v_mfma_f32_16x16x32_bf16 v[88:91], v[158:161], v[208:211], 0
	v_mfma_f32_16x16x32_bf16 v[76:79], v[150:153], v[216:219], 0
	v_mfma_f32_16x16x32_bf16 v[72:75], v[158:161], v[216:219], 0
	v_mfma_f32_16x16x32_bf16 v[124:127], v[154:157], v[196:199], v[124:127]
	v_mfma_f32_16x16x32_bf16 v[120:123], v[162:165], v[196:199], v[120:123]
	v_mfma_f32_16x16x32_bf16 v[108:111], v[154:157], v[204:207], v[108:111]
	v_mfma_f32_16x16x32_bf16 v[104:107], v[162:165], v[204:207], v[104:107]
	v_mfma_f32_16x16x32_bf16 v[92:95], v[154:157], v[212:215], v[92:95]
	v_mfma_f32_16x16x32_bf16 v[88:91], v[162:165], v[212:215], v[88:91]
	v_mfma_f32_16x16x32_bf16 v[76:79], v[154:157], v[220:223], v[76:79]
	v_mfma_f32_16x16x32_bf16 v[72:75], v[162:165], v[220:223], v[72:75]
	v_mfma_f32_16x16x32_bf16 v[116:119], v[166:169], v[192:195], 0
	v_mfma_f32_16x16x32_bf16 v[112:115], v[184:187], v[192:195], 0
	v_mfma_f32_16x16x32_bf16 v[100:103], v[166:169], v[200:203], 0
	v_mfma_f32_16x16x32_bf16 v[96:99], v[184:187], v[200:203], 0
	v_mfma_f32_16x16x32_bf16 v[84:87], v[166:169], v[208:211], 0
	v_mfma_f32_16x16x32_bf16 v[80:83], v[184:187], v[208:211], 0
	v_mfma_f32_16x16x32_bf16 v[68:71], v[166:169], v[216:219], 0
	v_mfma_f32_16x16x32_bf16 v[64:67], v[184:187], v[216:219], 0
	v_mfma_f32_16x16x32_bf16 v[116:119], v[180:183], v[196:199], v[116:119]
	v_mfma_f32_16x16x32_bf16 v[112:115], v[188:191], v[196:199], v[112:115]
	v_mfma_f32_16x16x32_bf16 v[100:103], v[180:183], v[204:207], v[100:103]
	v_mfma_f32_16x16x32_bf16 v[96:99], v[188:191], v[204:207], v[96:99]
	v_mfma_f32_16x16x32_bf16 v[84:87], v[180:183], v[212:215], v[84:87]
	v_mfma_f32_16x16x32_bf16 v[80:83], v[188:191], v[212:215], v[80:83]
	v_mfma_f32_16x16x32_bf16 v[68:71], v[180:183], v[220:223], v[68:71]
	v_mfma_f32_16x16x32_bf16 v[64:67], v[188:191], v[220:223], v[64:67]
	s_barrier
	s_add_i32 s49, s40, s28
	v_lshl_add_u64 v[224:225], s[24:25], 0, v[130:131]
	s_mov_b32 m0, s49
	ds_read_b128 v[192:195], v149 offset:16384
	ds_read_b128 v[196:199], v149 offset:17408
	ds_read_b128 v[200:203], v149 offset:18432
	ds_read_b128 v[204:207], v149 offset:19456
	ds_read_b128 v[208:211], v149 offset:20480
	ds_read_b128 v[212:215], v149 offset:21504
	ds_read_b128 v[216:219], v149 offset:22528
	ds_read_b128 v[220:223], v149 offset:23552
	global_load_lds_dwordx4 v[224:225], off
	s_add_i32 m0, s49, 0x2000
	s_add_u32 s50, s24, 0x40000
	v_lshl_add_u64 v[226:227], s[24:25], 0, v[134:135]
	s_addc_u32 s51, s25, 0
	s_add_i32 s49, s41, s28
	global_load_lds_dwordx4 v[226:227], off
	v_lshl_add_u64 v[228:229], s[50:51], 0, v[130:131]
	s_mov_b32 m0, s49
	v_lshl_add_u64 v[230:231], s[26:27], 0, v[132:133]
	global_load_lds_dwordx4 v[228:229], off
	v_lshl_add_u64 v[228:229], s[50:51], 0, v[134:135]
	s_add_i32 m0, s49, 0x2000
	s_nop 0
	global_load_lds_dwordx4 v[228:229], off
	v_lshl_add_u64 v[228:229], s[26:27], 0, v[128:129]
	s_mov_b32 m0, s21
	s_nop 0
	global_load_lds_dwordx4 v[228:229], off
	s_mov_b32 m0, s31
	s_nop 0
	global_load_lds_dwordx4 v[230:231], off
	s_waitcnt vmcnt(8)
	s_waitcnt lgkmcnt(0)
	s_barrier
	s_waitcnt lgkmcnt(0)
	v_mfma_f32_16x16x32_bf16 v[60:63], v[150:153], v[192:195], 0
	v_mfma_f32_16x16x32_bf16 v[56:59], v[158:161], v[192:195], 0
	v_mfma_f32_16x16x32_bf16 v[44:47], v[150:153], v[200:203], 0
	v_mfma_f32_16x16x32_bf16 v[40:43], v[158:161], v[200:203], 0
	v_mfma_f32_16x16x32_bf16 v[28:31], v[150:153], v[208:211], 0
	v_mfma_f32_16x16x32_bf16 v[24:27], v[158:161], v[208:211], 0
	v_mfma_f32_16x16x32_bf16 v[12:15], v[150:153], v[216:219], 0
	v_mfma_f32_16x16x32_bf16 v[8:11], v[158:161], v[216:219], 0
	v_mfma_f32_16x16x32_bf16 v[60:63], v[154:157], v[196:199], v[60:63]
	v_mfma_f32_16x16x32_bf16 v[56:59], v[162:165], v[196:199], v[56:59]
	v_mfma_f32_16x16x32_bf16 v[44:47], v[154:157], v[204:207], v[44:47]
	v_mfma_f32_16x16x32_bf16 v[40:43], v[162:165], v[204:207], v[40:43]
	v_mfma_f32_16x16x32_bf16 v[28:31], v[154:157], v[212:215], v[28:31]
	v_mfma_f32_16x16x32_bf16 v[24:27], v[162:165], v[212:215], v[24:27]
	v_mfma_f32_16x16x32_bf16 v[12:15], v[154:157], v[220:223], v[12:15]
	v_mfma_f32_16x16x32_bf16 v[8:11], v[162:165], v[220:223], v[8:11]
	v_mfma_f32_16x16x32_bf16 v[52:55], v[166:169], v[192:195], 0
	v_mfma_f32_16x16x32_bf16 v[48:51], v[184:187], v[192:195], 0
	v_mfma_f32_16x16x32_bf16 v[36:39], v[166:169], v[200:203], 0
	v_mfma_f32_16x16x32_bf16 v[32:35], v[184:187], v[200:203], 0
	v_mfma_f32_16x16x32_bf16 v[20:23], v[166:169], v[208:211], 0
	v_mfma_f32_16x16x32_bf16 v[16:19], v[184:187], v[208:211], 0
	v_mfma_f32_16x16x32_bf16 v[4:7], v[166:169], v[216:219], 0
	v_mfma_f32_16x16x32_bf16 v[0:3], v[184:187], v[216:219], 0
	v_mfma_f32_16x16x32_bf16 v[52:55], v[180:183], v[196:199], v[52:55]
	v_mfma_f32_16x16x32_bf16 v[48:51], v[188:191], v[196:199], v[48:51]
	v_mfma_f32_16x16x32_bf16 v[36:39], v[180:183], v[204:207], v[36:39]
	v_mfma_f32_16x16x32_bf16 v[32:35], v[188:191], v[204:207], v[32:35]
	v_mfma_f32_16x16x32_bf16 v[20:23], v[180:183], v[212:215], v[20:23]
	v_mfma_f32_16x16x32_bf16 v[16:19], v[188:191], v[212:215], v[16:19]
	v_mfma_f32_16x16x32_bf16 v[4:7], v[180:183], v[220:223], v[4:7]
	v_mfma_f32_16x16x32_bf16 v[0:3], v[188:191], v[220:223], v[0:3]
	s_barrier
	s_branch .Lpeel942_mid

.LBB0_1004:
	s_lshl_b32 s5, s5, 5
	s_mov_b64 s[16:17], 0x80
	s_and_b32 s5, s5, 0x60
	v_readlane_b32 s24, v246, 48
	s_add_i32 m0, s41, 0x18000
	v_lshl_add_u64 v[0:1], v[0:1], 0, s[16:17]
	s_lshl_b32 s20, s3, 13
	s_lshl_b32 s22, s5, 7
	s_ashr_i32 s46, s24, 31
	global_load_lds_dwordx4 v[0:1], off
	v_lshl_add_u64 v[0:1], v[2:3], 0, s[16:17]
	s_add_i32 m0, s41, 0x1a000
	s_add_i32 s47, s41, 0x8000
	s_add_i32 s48, s41, 0xa000
	global_load_lds_dwordx4 v[0:1], off
	v_lshl_add_u64 v[0:1], v[6:7], 0, s[16:17]
	s_mov_b32 m0, s47
	s_add_u32 s18, s34, 0xb0080
	global_load_lds_dwordx4 v[0:1], off
	v_lshl_add_u64 v[0:1], v[4:5], 0, s[16:17]
	s_mov_b32 m0, s48
	s_addc_u32 s19, s35, 0
	global_load_lds_dwordx4 v[0:1], off
	s_add_i32 m0, s41, 0x1c000
	v_lshl_add_u64 v[0:1], s[18:19], 0, v[128:129]
	global_load_lds_dwordx4 v[0:1], off
	v_lshl_add_u64 v[0:1], s[18:19], 0, v[130:131]
	s_add_i32 m0, s41, 0x1e000
	s_sext_i32_i8 s55, s4
	global_load_lds_dwordx4 v[0:1], off
	s_waitcnt vmcnt(8)
	s_barrier
	v_bfe_u32 v0, v171, 4, 2
	v_lshlrev_b32_e32 v1, 4, v0
	v_lshlrev_b32_e32 v2, 6, v171
	s_movk_i32 s4, 0x3c0
	v_lshlrev_b32_e32 v3, 2, v172
	v_and_or_b32 v2, v2, s4, v1
	v_lshl_or_b32 v1, v172, 6, v1
	v_and_b32_e32 v3, 32, v3
	s_waitcnt vmcnt(6)
	s_cmpk_lt_u32 s2, 0x100
	v_bitop3_b32 v1, v1, s20, v3 bitop3:0xde
	v_bitop3_b32 v147, s22, v2, v146 bitop3:0xf6
	s_cselect_b64 s[18:19], -1, 0
	v_mov_b32_e32 v133, 0
	s_add_i32 s50, 0, 0x10000
	s_add_i32 s51, 0, 0x14000
	v_lshl_or_b32 v145, s3, 6, v172
	s_mov_b32 s49, s24
	v_lshl_or_b32 v148, v0, 2, s5
	v_add3_u32 v132, v143, v142, v173
	v_add3_u32 v134, v144, v142, v173
	v_mov_b32_e32 v135, v133
	v_mov_b64_e32 v[136:137], 0x100
	v_mov_b64_e32 v[138:139], 0xff
	v_add_u32_e32 v149, s50, v147
	v_add_u32_e32 v150, s51, v147
	v_add_u32_e32 v151, 0, v1
	s_mov_b32 s20, 0x3f9837f0
	s_mov_b64 s[22:23], 0x80000
	s_mov_b64 s[24:25], 0x90000
	s_mov_b64 s[26:27], 0xa0000
	s_barrier
	s_branch .LBB0_1007

.LBB0_1021:
	v_lshl_add_u32 v156, s54, 8, v145
	v_lshl_or_b32 v158, s55, 8, v148
	v_ashrrev_i32_e32 v157, 31, v156
	v_ashrrev_i32_e32 v159, 31, v158
	v_lshlrev_b64 v[140:141], 10, v[156:157]
	v_lshl_add_u64 v[140:141], v[140:141], 0, v[158:159]
	v_lshlrev_b64 v[140:141], 2, v[140:141]
	v_lshl_add_u64 v[160:161], s[72:73], 0, v[140:141]
	global_load_dwordx4 v[152:155], v[160:161], off
	v_readlane_b32 s66, v246, 34
	v_readlane_b32 s67, v246, 35
	s_and_b64 vcc, exec, s[2:3]
	s_mov_b64 s[2:3], -1
	v_lshl_add_u64 v[162:163], s[66:67], 0, v[140:141]
	s_waitcnt vmcnt(0)
	v_pk_fma_f32 v[126:127], v[154:155], s[20:21], v[126:127] op_sel_hi:[1,0,1]
	v_pk_fma_f32 v[124:125], v[152:153], s[20:21], v[124:125] op_sel_hi:[1,0,1]
	global_store_dwordx4 v[162:163], v[124:127], off
	global_load_dwordx4 v[124:127], v[160:161], off offset:64
	s_waitcnt vmcnt(0)
	v_pk_fma_f32 v[122:123], v[126:127], s[20:21], v[122:123] op_sel_hi:[1,0,1]
	v_pk_fma_f32 v[120:121], v[124:125], s[20:21], v[120:121] op_sel_hi:[1,0,1]
	global_store_dwordx4 v[162:163], v[120:123], off offset:64
	global_load_dwordx4 v[120:123], v[160:161], off offset:512
	s_waitcnt vmcnt(0)
	v_pk_fma_f32 v[118:119], v[122:123], s[20:21], v[118:119] op_sel_hi:[1,0,1]
	v_pk_fma_f32 v[116:117], v[120:121], s[20:21], v[116:117] op_sel_hi:[1,0,1]
	global_store_dwordx4 v[162:163], v[116:119], off offset:512
	global_load_dwordx4 v[116:119], v[160:161], off offset:576
	v_or_b32_e32 v120, 16, v156
	v_ashrrev_i32_e32 v121, 31, v120
	v_lshlrev_b64 v[120:121], 10, v[120:121]
	v_lshl_add_u64 v[120:121], v[120:121], 0, v[158:159]
	v_lshlrev_b64 v[120:121], 2, v[120:121]
	v_lshl_add_u64 v[122:123], s[72:73], 0, v[120:121]
	s_waitcnt vmcnt(0)
	v_pk_fma_f32 v[106:107], v[118:119], s[20:21], v[106:107] op_sel_hi:[1,0,1]
	v_pk_fma_f32 v[104:105], v[116:117], s[20:21], v[104:105] op_sel_hi:[1,0,1]
	global_store_dwordx4 v[162:163], v[104:107], off offset:576
	global_load_dwordx4 v[104:107], v[122:123], off
	v_lshl_add_u64 v[116:117], s[66:67], 0, v[120:121]
	s_waitcnt vmcnt(0)
	v_pk_fma_f32 v[106:107], v[106:107], s[20:21], v[114:115] op_sel_hi:[1,0,1]
	v_pk_fma_f32 v[104:105], v[104:105], s[20:21], v[112:113] op_sel_hi:[1,0,1]
	global_store_dwordx4 v[116:117], v[104:107], off
	global_load_dwordx4 v[104:107], v[122:123], off offset:64
	s_waitcnt vmcnt(0)
	v_pk_fma_f32 v[106:107], v[106:107], s[20:21], v[110:111] op_sel_hi:[1,0,1]
	v_pk_fma_f32 v[104:105], v[104:105], s[20:21], v[108:109] op_sel_hi:[1,0,1]
	global_store_dwordx4 v[116:117], v[104:107], off offset:64
	global_load_dwordx4 v[104:107], v[122:123], off offset:512
	s_waitcnt vmcnt(0)
	v_pk_fma_f32 v[102:103], v[106:107], s[20:21], v[102:103] op_sel_hi:[1,0,1]
	v_pk_fma_f32 v[100:101], v[104:105], s[20:21], v[100:101] op_sel_hi:[1,0,1]
	global_store_dwordx4 v[116:117], v[100:103], off offset:512
	global_load_dwordx4 v[100:103], v[122:123], off offset:576
	v_or_b32_e32 v104, 32, v156
	v_ashrrev_i32_e32 v105, 31, v104
	v_lshlrev_b64 v[104:105], 10, v[104:105]
	v_lshl_add_u64 v[104:105], v[104:105], 0, v[158:159]
	v_lshlrev_b64 v[104:105], 2, v[104:105]
	v_lshl_add_u64 v[106:107], s[72:73], 0, v[104:105]
	s_waitcnt vmcnt(0)
	v_pk_fma_f32 v[90:91], v[102:103], s[20:21], v[90:91] op_sel_hi:[1,0,1]
	v_pk_fma_f32 v[88:89], v[100:101], s[20:21], v[88:89] op_sel_hi:[1,0,1]
	global_store_dwordx4 v[116:117], v[88:91], off offset:576
	global_load_dwordx4 v[88:91], v[106:107], off
	v_lshl_add_u64 v[100:101], s[66:67], 0, v[104:105]
	s_waitcnt vmcnt(0)
	v_pk_fma_f32 v[90:91], v[90:91], s[20:21], v[98:99] op_sel_hi:[1,0,1]
	v_pk_fma_f32 v[88:89], v[88:89], s[20:21], v[96:97] op_sel_hi:[1,0,1]
	global_store_dwordx4 v[100:101], v[88:91], off
	global_load_dwordx4 v[88:91], v[106:107], off offset:64
	s_waitcnt vmcnt(0)
	v_pk_fma_f32 v[90:91], v[90:91], s[20:21], v[94:95] op_sel_hi:[1,0,1]
	v_pk_fma_f32 v[88:89], v[88:89], s[20:21], v[92:93] op_sel_hi:[1,0,1]
	global_store_dwordx4 v[100:101], v[88:91], off offset:64
	global_load_dwordx4 v[88:91], v[106:107], off offset:512
	s_waitcnt vmcnt(0)
	v_pk_fma_f32 v[86:87], v[90:91], s[20:21], v[86:87] op_sel_hi:[1,0,1]
	v_pk_fma_f32 v[84:85], v[88:89], s[20:21], v[84:85] op_sel_hi:[1,0,1]
	global_store_dwordx4 v[100:101], v[84:87], off offset:512
	global_load_dwordx4 v[84:87], v[106:107], off offset:576
	v_or_b32_e32 v88, 48, v156
	v_ashrrev_i32_e32 v89, 31, v88
	v_lshlrev_b64 v[88:89], 10, v[88:89]
	v_lshl_add_u64 v[88:89], v[88:89], 0, v[158:159]
	v_lshlrev_b64 v[88:89], 2, v[88:89]
	v_lshl_add_u64 v[90:91], s[72:73], 0, v[88:89]
	s_waitcnt vmcnt(0)
	v_pk_fma_f32 v[74:75], v[86:87], s[20:21], v[74:75] op_sel_hi:[1,0,1]
	v_pk_fma_f32 v[72:73], v[84:85], s[20:21], v[72:73] op_sel_hi:[1,0,1]
	global_store_dwordx4 v[100:101], v[72:75], off offset:576
	global_load_dwordx4 v[72:75], v[90:91], off
	v_lshl_add_u64 v[84:85], s[66:67], 0, v[88:89]
	s_waitcnt vmcnt(0)
	v_pk_fma_f32 v[74:75], v[74:75], s[20:21], v[82:83] op_sel_hi:[1,0,1]
	v_pk_fma_f32 v[72:73], v[72:73], s[20:21], v[80:81] op_sel_hi:[1,0,1]
	global_store_dwordx4 v[84:85], v[72:75], off
	global_load_dwordx4 v[72:75], v[90:91], off offset:64
	s_waitcnt vmcnt(0)
	v_pk_fma_f32 v[74:75], v[74:75], s[20:21], v[78:79] op_sel_hi:[1,0,1]
	v_pk_fma_f32 v[72:73], v[72:73], s[20:21], v[76:77] op_sel_hi:[1,0,1]
	global_store_dwordx4 v[84:85], v[72:75], off offset:64
	global_load_dwordx4 v[72:75], v[90:91], off offset:512
	s_waitcnt vmcnt(0)
	v_pk_fma_f32 v[70:71], v[74:75], s[20:21], v[70:71] op_sel_hi:[1,0,1]
	v_pk_fma_f32 v[68:69], v[72:73], s[20:21], v[68:69] op_sel_hi:[1,0,1]
	global_store_dwordx4 v[84:85], v[68:71], off offset:512
	global_load_dwordx4 v[68:71], v[90:91], off offset:576
	v_lshl_add_u64 v[72:73], v[140:141], 0, s[22:23]
	v_lshl_add_u64 v[74:75], s[72:73], 0, v[72:73]
	s_waitcnt vmcnt(0)
	v_pk_fma_f32 v[66:67], v[70:71], s[20:21], v[66:67] op_sel_hi:[1,0,1]
	v_pk_fma_f32 v[64:65], v[68:69], s[20:21], v[64:65] op_sel_hi:[1,0,1]
	global_store_dwordx4 v[84:85], v[64:67], off offset:576
	global_load_dwordx4 v[64:67], v[74:75], off
	v_lshl_add_u64 v[68:69], s[66:67], 0, v[72:73]
	s_waitcnt vmcnt(0)
	v_pk_fma_f32 v[62:63], v[66:67], s[20:21], v[62:63] op_sel_hi:[1,0,1]
	v_pk_fma_f32 v[60:61], v[64:65], s[20:21], v[60:61] op_sel_hi:[1,0,1]
	global_store_dwordx4 v[68:69], v[60:63], off
	global_load_dwordx4 v[60:63], v[74:75], off offset:64
	s_waitcnt vmcnt(0)
	v_pk_fma_f32 v[58:59], v[62:63], s[20:21], v[58:59] op_sel_hi:[1,0,1]
	v_pk_fma_f32 v[56:57], v[60:61], s[20:21], v[56:57] op_sel_hi:[1,0,1]
	global_store_dwordx4 v[68:69], v[56:59], off offset:64
	global_load_dwordx4 v[56:59], v[74:75], off offset:512
	s_waitcnt vmcnt(0)
	v_pk_fma_f32 v[54:55], v[58:59], s[20:21], v[54:55] op_sel_hi:[1,0,1]
	v_pk_fma_f32 v[52:53], v[56:57], s[20:21], v[52:53] op_sel_hi:[1,0,1]
	global_store_dwordx4 v[68:69], v[52:55], off offset:512
	global_load_dwordx4 v[52:55], v[74:75], off offset:576
	v_lshl_add_u64 v[56:57], v[140:141], 0, s[24:25]
	v_lshl_add_u64 v[58:59], s[72:73], 0, v[56:57]
	s_waitcnt vmcnt(0)
	v_pk_fma_f32 v[42:43], v[54:55], s[20:21], v[42:43] op_sel_hi:[1,0,1]
	v_pk_fma_f32 v[40:41], v[52:53], s[20:21], v[40:41] op_sel_hi:[1,0,1]
	global_store_dwordx4 v[68:69], v[40:43], off offset:576
	global_load_dwordx4 v[40:43], v[58:59], off
	v_lshl_add_u64 v[52:53], s[66:67], 0, v[56:57]
	s_waitcnt vmcnt(0)
	v_pk_fma_f32 v[42:43], v[42:43], s[20:21], v[50:51] op_sel_hi:[1,0,1]
	v_pk_fma_f32 v[40:41], v[40:41], s[20:21], v[48:49] op_sel_hi:[1,0,1]
	global_store_dwordx4 v[52:53], v[40:43], off
	global_load_dwordx4 v[40:43], v[58:59], off offset:64
	s_waitcnt vmcnt(0)
	v_pk_fma_f32 v[42:43], v[42:43], s[20:21], v[46:47] op_sel_hi:[1,0,1]
	v_pk_fma_f32 v[40:41], v[40:41], s[20:21], v[44:45] op_sel_hi:[1,0,1]
	global_store_dwordx4 v[52:53], v[40:43], off offset:64
	global_load_dwordx4 v[40:43], v[58:59], off offset:512
	s_waitcnt vmcnt(0)
	v_pk_fma_f32 v[38:39], v[42:43], s[20:21], v[38:39] op_sel_hi:[1,0,1]
	v_pk_fma_f32 v[36:37], v[40:41], s[20:21], v[36:37] op_sel_hi:[1,0,1]
	global_store_dwordx4 v[52:53], v[36:39], off offset:512
	global_load_dwordx4 v[36:39], v[58:59], off offset:576
	v_lshl_add_u64 v[40:41], v[140:141], 0, s[26:27]
	v_lshl_add_u64 v[42:43], s[72:73], 0, v[40:41]
	s_waitcnt vmcnt(0)
	v_pk_fma_f32 v[26:27], v[38:39], s[20:21], v[26:27] op_sel_hi:[1,0,1]
	v_pk_fma_f32 v[24:25], v[36:37], s[20:21], v[24:25] op_sel_hi:[1,0,1]
	global_store_dwordx4 v[52:53], v[24:27], off offset:576
	global_load_dwordx4 v[24:27], v[42:43], off
	v_lshl_add_u64 v[36:37], s[66:67], 0, v[40:41]
	s_waitcnt vmcnt(0)
	v_pk_fma_f32 v[26:27], v[26:27], s[20:21], v[34:35] op_sel_hi:[1,0,1]
	v_pk_fma_f32 v[24:25], v[24:25], s[20:21], v[32:33] op_sel_hi:[1,0,1]
	global_store_dwordx4 v[36:37], v[24:27], off
	global_load_dwordx4 v[24:27], v[42:43], off offset:64
	s_waitcnt vmcnt(0)
	v_pk_fma_f32 v[26:27], v[26:27], s[20:21], v[30:31] op_sel_hi:[1,0,1]
	v_pk_fma_f32 v[24:25], v[24:25], s[20:21], v[28:29] op_sel_hi:[1,0,1]
	global_store_dwordx4 v[36:37], v[24:27], off offset:64
	global_load_dwordx4 v[24:27], v[42:43], off offset:512
	s_waitcnt vmcnt(0)
	v_pk_fma_f32 v[22:23], v[26:27], s[20:21], v[22:23] op_sel_hi:[1,0,1]
	v_pk_fma_f32 v[20:21], v[24:25], s[20:21], v[20:21] op_sel_hi:[1,0,1]
	global_store_dwordx4 v[36:37], v[20:23], off offset:512
	global_load_dwordx4 v[20:23], v[42:43], off offset:576
	v_lshl_add_u64 v[24:25], v[140:141], 0, s[14:15]
	v_lshl_add_u64 v[26:27], s[72:73], 0, v[24:25]
	s_waitcnt vmcnt(0)
	v_pk_fma_f32 v[14:15], v[22:23], s[20:21], v[14:15] op_sel_hi:[1,0,1]
	v_pk_fma_f32 v[12:13], v[20:21], s[20:21], v[12:13] op_sel_hi:[1,0,1]
	global_store_dwordx4 v[36:37], v[12:15], off offset:576
	global_load_dwordx4 v[12:15], v[26:27], off
	v_lshl_add_u64 v[20:21], s[66:67], 0, v[24:25]
	s_waitcnt vmcnt(0)
	v_pk_fma_f32 v[14:15], v[14:15], s[20:21], v[18:19] op_sel_hi:[1,0,1]
	v_pk_fma_f32 v[12:13], v[12:13], s[20:21], v[16:17] op_sel_hi:[1,0,1]
	global_store_dwordx4 v[20:21], v[12:15], off
	global_load_dwordx4 v[12:15], v[26:27], off offset:64
	s_waitcnt vmcnt(0)
	v_pk_fma_f32 v[10:11], v[14:15], s[20:21], v[10:11] op_sel_hi:[1,0,1]
	v_pk_fma_f32 v[8:9], v[12:13], s[20:21], v[8:9] op_sel_hi:[1,0,1]
	global_store_dwordx4 v[20:21], v[8:11], off offset:64
	global_load_dwordx4 v[8:11], v[26:27], off offset:512
	s_waitcnt vmcnt(0)
	v_pk_fma_f32 v[6:7], v[10:11], s[20:21], v[6:7] op_sel_hi:[1,0,1]
	v_pk_fma_f32 v[4:5], v[8:9], s[20:21], v[4:5] op_sel_hi:[1,0,1]
	global_store_dwordx4 v[20:21], v[4:7], off offset:512
	global_load_dwordx4 v[4:7], v[26:27], off offset:576
	s_waitcnt vmcnt(0)
	v_pk_fma_f32 v[2:3], v[6:7], s[20:21], v[2:3] op_sel_hi:[1,0,1]
	v_pk_fma_f32 v[0:1], v[4:5], s[20:21], v[0:1] op_sel_hi:[1,0,1]
	global_store_dwordx4 v[20:21], v[0:3], off offset:576
	s_cbranch_vccnz .LBB0_1006
	s_andn2_b64 vcc, exec, s[12:13]
	s_cbranch_vccnz .LBB0_1005
	s_barrier
	s_branch .LBB0_1005

.LBB0_1031:
	s_add_i32 s43, s36, 1
	s_ashr_i32 s0, s43, 31
	v_readlane_b32 s2, v246, 48
	s_mul_i32 s0, s0, s2
	s_mul_hi_u32 s1, s43, s2
	s_add_i32 s1, s1, s0
	s_mul_i32 s0, s43, s2
	s_add_u32 s2, s0, s74
	s_addc_u32 s3, s1, s33
	v_cmp_gt_i64_e64 s[0:1], s[2:3], v[138:139]
	v_cmp_lt_i64_e64 s[4:5], s[2:3], v[136:137]
	s_and_b64 vcc, exec, s[0:1]
	s_cbranch_vccnz .LBB0_1037
	s_ashr_i32 s3, s2, 31
	s_lshr_b32 s3, s3, 29
	s_add_i32 s16, s2, s3
	s_and_b32 s3, s16, -8
	s_sub_i32 s17, s2, s3
	s_cmp_gt_i32 s17, -1
	s_mov_b64 s[2:3], -1
	s_cbranch_scc0 .LBB0_1034
	s_lshl_b32 s20, s17, 5
	s_mov_b64 s[2:3], 0

.LBB0_1090:
	s_or_b64 exec, exec, s[2:3]
	v_readlane_b32 s46, v246, 30
	v_readlane_b32 s47, v246, 31
	v_readlane_b32 s48, v246, 32
	v_readlane_b32 s49, v246, 33
	v_readlane_b32 s50, v246, 34
	v_readlane_b32 s51, v246, 35
	s_mov_b64 s[12:13], s[48:49]
	s_mov_b64 s[10:11], s[46:47]
	s_waitcnt lgkmcnt(0)
	s_barrier
	v_lshl_add_u64 v[128:129], s[10:11], 0, v[160:161]
	v_lshl_add_u64 v[132:133], s[12:13], 0, v[160:161]
	global_load_dwordx4 v[152:155], v[132:133], off
	global_load_dwordx4 v[156:159], v[128:129], off
	global_load_dwordx4 v[144:147], v[128:129], off offset:64
	global_load_dwordx4 v[148:151], v[132:133], off offset:64
	global_load_dwordx4 v[136:139], v[132:133], off offset:512
	global_load_dwordx4 v[140:143], v[128:129], off offset:512
	s_nop 0
	global_load_dwordx4 v[128:131], v[128:129], off offset:576
	s_nop 0
	global_load_dwordx4 v[132:135], v[132:133], off offset:576
	v_lshl_add_u32 v165, v162, 3, 0
	ds_read_b64 v[168:169], v165 offset:8192
	v_add_u32_e32 v162, s20, v162
	v_ashrrev_i32_e32 v163, 31, v162
	s_mov_b64 s[14:15], s[50:51]
	v_lshlrev_b64 v[174:175], 12, v[162:163]
	s_waitcnt lgkmcnt(0)
	v_sub_f32_e32 v125, v125, v168
	v_sub_f32_e32 v124, v124, v168
	v_sub_f32_e32 v127, v127, v168
	v_sub_f32_e32 v126, v126, v168
	v_sub_f32_e32 v121, v121, v168
	v_sub_f32_e32 v120, v120, v168
	v_sub_f32_e32 v123, v123, v168
	v_sub_f32_e32 v122, v122, v168
	v_sub_f32_e32 v113, v113, v168
	v_sub_f32_e32 v112, v112, v168
	v_sub_f32_e32 v115, v115, v168
	v_sub_f32_e32 v114, v114, v168
	v_sub_f32_e32 v109, v109, v168
	v_sub_f32_e32 v108, v108, v168
	v_sub_f32_e32 v111, v111, v168
	v_sub_f32_e32 v110, v110, v168
	v_pk_mul_f32 v[126:127], v[168:169], v[126:127] op_sel:[1,0]
	v_pk_mul_f32 v[124:125], v[168:169], v[124:125] op_sel:[1,0]
	v_mov_b32_e32 v164, 0x7fc00000
	v_lshl_add_u64 v[174:175], s[14:15], 0, v[174:175]
	v_pk_mul_f32 v[122:123], v[168:169], v[122:123] op_sel:[1,0]
	v_pk_mul_f32 v[120:121], v[168:169], v[120:121] op_sel:[1,0]
	v_pk_mul_f32 v[114:115], v[168:169], v[114:115] op_sel:[1,0]
	v_pk_mul_f32 v[112:113], v[168:169], v[112:113] op_sel:[1,0]
	v_pk_mul_f32 v[110:111], v[168:169], v[110:111] op_sel:[1,0]
	v_pk_mul_f32 v[108:109], v[168:169], v[108:109] op_sel:[1,0]
	v_cmp_eq_u32_e32 vcc, 0, v166
	v_lshl_add_u64 v[174:175], v[174:175], 0, v[160:161]
	v_add_u32_e32 v172, 16, v162
	v_ashrrev_i32_e32 v173, 31, v172
	s_waitcnt vmcnt(6)
	v_pk_fma_f32 v[124:125], v[156:157], v[124:125], v[152:153]
	v_pk_fma_f32 v[126:127], v[158:159], v[126:127], v[154:155]
	s_waitcnt vmcnt(4)
	v_pk_fma_f32 v[120:121], v[144:145], v[120:121], v[148:149]
	v_pk_fma_f32 v[122:123], v[146:147], v[122:123], v[150:151]
	s_waitcnt vmcnt(2)
	v_pk_fma_f32 v[168:169], v[140:141], v[112:113], v[136:137]
	v_pk_fma_f32 v[176:177], v[142:143], v[114:115], v[138:139]
	s_waitcnt vmcnt(0)
	v_pk_fma_f32 v[178:179], v[128:129], v[108:109], v[132:133]
	v_pk_fma_f32 v[180:181], v[130:131], v[110:111], v[134:135]
	v_cndmask_b32_e32 v111, v164, v127, vcc
	v_cndmask_b32_e32 v110, v164, v126, vcc
	v_cndmask_b32_e32 v109, v164, v125, vcc
	v_cndmask_b32_e32 v108, v164, v124, vcc
	v_cndmask_b32_e32 v115, v164, v123, vcc
	v_cndmask_b32_e32 v114, v164, v122, vcc
	v_cndmask_b32_e32 v113, v164, v121, vcc
	v_cndmask_b32_e32 v112, v164, v120, vcc
	v_cndmask_b32_e32 v123, v164, v177, vcc
	v_cndmask_b32_e32 v122, v164, v176, vcc
	v_cndmask_b32_e32 v121, v164, v169, vcc
	v_cndmask_b32_e32 v120, v164, v168, vcc
	v_cndmask_b32_e32 v127, v164, v181, vcc
	v_cndmask_b32_e32 v126, v164, v180, vcc
	v_cndmask_b32_e32 v125, v164, v179, vcc
	v_cndmask_b32_e32 v124, v164, v178, vcc
	global_store_dwordx4 v[174:175], v[108:111], off
	global_store_dwordx4 v[174:175], v[112:115], off offset:64
	global_store_dwordx4 v[174:175], v[120:123], off offset:512
	global_store_dwordx4 v[174:175], v[124:127], off offset:576
	ds_read_b64 v[112:113], v165 offset:8320
	v_lshlrev_b64 v[108:109], 12, v[172:173]
	v_lshl_add_u64 v[108:109], s[14:15], 0, v[108:109]
	v_lshl_add_u64 v[114:115], v[108:109], 0, v[160:161]
	s_waitcnt lgkmcnt(0)
	v_sub_f32_e32 v109, v117, v112
	v_sub_f32_e32 v108, v116, v112
	v_sub_f32_e32 v111, v119, v112
	v_sub_f32_e32 v110, v118, v112
	v_sub_f32_e32 v101, v101, v112
	v_sub_f32_e32 v100, v100, v112
	v_sub_f32_e32 v103, v103, v112
	v_sub_f32_e32 v102, v102, v112
	v_sub_f32_e32 v89, v89, v112
	v_sub_f32_e32 v88, v88, v112
	v_sub_f32_e32 v91, v91, v112
	v_sub_f32_e32 v90, v90, v112
	v_sub_f32_e32 v81, v81, v112
	v_sub_f32_e32 v80, v80, v112
	v_sub_f32_e32 v83, v83, v112
	v_sub_f32_e32 v82, v82, v112
	v_pk_mul_f32 v[110:111], v[112:113], v[110:111] op_sel:[1,0]
	v_pk_mul_f32 v[108:109], v[112:113], v[108:109] op_sel:[1,0]
	v_pk_mul_f32 v[102:103], v[112:113], v[102:103] op_sel:[1,0]
	v_pk_mul_f32 v[100:101], v[112:113], v[100:101] op_sel:[1,0]
	v_pk_mul_f32 v[90:91], v[112:113], v[90:91] op_sel:[1,0]
	v_pk_mul_f32 v[88:89], v[112:113], v[88:89] op_sel:[1,0]
	v_pk_mul_f32 v[82:83], v[112:113], v[82:83] op_sel:[1,0]
	v_pk_mul_f32 v[80:81], v[112:113], v[80:81] op_sel:[1,0]
	v_pk_fma_f32 v[108:109], v[156:157], v[108:109], v[152:153]
	v_pk_fma_f32 v[110:111], v[158:159], v[110:111], v[154:155]
	v_pk_fma_f32 v[100:101], v[144:145], v[100:101], v[148:149]
	v_pk_fma_f32 v[102:103], v[146:147], v[102:103], v[150:151]
	v_pk_fma_f32 v[88:89], v[140:141], v[88:89], v[136:137]
	v_pk_fma_f32 v[90:91], v[142:143], v[90:91], v[138:139]
	v_pk_fma_f32 v[80:81], v[128:129], v[80:81], v[132:133]
	v_pk_fma_f32 v[82:83], v[130:131], v[82:83], v[134:135]
	v_cndmask_b32_e32 v111, v164, v111, vcc
	v_cndmask_b32_e32 v110, v164, v110, vcc
	v_cndmask_b32_e32 v109, v164, v109, vcc
	v_cndmask_b32_e32 v108, v164, v108, vcc
	v_cndmask_b32_e32 v103, v164, v103, vcc
	v_cndmask_b32_e32 v102, v164, v102, vcc
	v_cndmask_b32_e32 v101, v164, v101, vcc
	v_cndmask_b32_e32 v100, v164, v100, vcc
	v_cndmask_b32_e32 v91, v164, v91, vcc
	v_cndmask_b32_e32 v90, v164, v90, vcc
	v_cndmask_b32_e32 v89, v164, v89, vcc
	v_cndmask_b32_e32 v88, v164, v88, vcc
	v_cndmask_b32_e32 v83, v164, v83, vcc
	v_cndmask_b32_e32 v82, v164, v82, vcc
	v_cndmask_b32_e32 v81, v164, v81, vcc
	v_cndmask_b32_e32 v80, v164, v80, vcc
	global_store_dwordx4 v[114:115], v[108:111], off
	global_store_dwordx4 v[114:115], v[100:103], off offset:64
	global_store_dwordx4 v[114:115], v[88:91], off offset:512
	global_store_dwordx4 v[114:115], v[80:83], off offset:576
	ds_read_b64 v[88:89], v165 offset:8448
	s_waitcnt lgkmcnt(0)
	v_sub_f32_e32 v73, v73, v88
	v_add_u32_e32 v80, 32, v162
	v_ashrrev_i32_e32 v81, 31, v80
	v_lshlrev_b64 v[90:91], 12, v[80:81]
	v_sub_f32_e32 v81, v105, v88
	v_sub_f32_e32 v80, v104, v88
	v_sub_f32_e32 v83, v107, v88
	v_sub_f32_e32 v82, v106, v88
	v_pk_mul_f32 v[82:83], v[88:89], v[82:83] op_sel:[1,0]
	v_pk_mul_f32 v[80:81], v[88:89], v[80:81] op_sel:[1,0]
	v_pk_fma_f32 v[82:83], v[158:159], v[82:83], v[154:155]
	v_pk_fma_f32 v[80:81], v[156:157], v[80:81], v[152:153]
	v_lshl_add_u64 v[90:91], s[14:15], 0, v[90:91]
	v_cndmask_b32_e32 v83, v164, v83, vcc
	v_cndmask_b32_e32 v82, v164, v82, vcc
	v_cndmask_b32_e32 v81, v164, v81, vcc
	v_cndmask_b32_e32 v80, v164, v80, vcc
	v_lshl_add_u64 v[90:91], v[90:91], 0, v[160:161]
	global_store_dwordx4 v[90:91], v[80:83], off
	v_sub_f32_e32 v72, v72, v88
	v_sub_f32_e32 v75, v75, v88
	v_sub_f32_e32 v81, v93, v88
	v_sub_f32_e32 v80, v92, v88
	v_sub_f32_e32 v83, v95, v88
	v_sub_f32_e32 v82, v94, v88
	v_pk_mul_f32 v[82:83], v[88:89], v[82:83] op_sel:[1,0]
	v_pk_mul_f32 v[80:81], v[88:89], v[80:81] op_sel:[1,0]
	v_pk_fma_f32 v[82:83], v[146:147], v[82:83], v[150:151]
	v_pk_fma_f32 v[80:81], v[144:145], v[80:81], v[148:149]
	v_cndmask_b32_e32 v83, v164, v83, vcc
	v_cndmask_b32_e32 v82, v164, v82, vcc
	v_cndmask_b32_e32 v81, v164, v81, vcc
	v_cndmask_b32_e32 v80, v164, v80, vcc
	global_store_dwordx4 v[90:91], v[80:83], off offset:64
	v_sub_f32_e32 v74, v74, v88
	v_pk_mul_f32 v[74:75], v[88:89], v[74:75] op_sel:[1,0]
	v_sub_f32_e32 v81, v85, v88
	v_sub_f32_e32 v80, v84, v88
	v_sub_f32_e32 v83, v87, v88
	v_sub_f32_e32 v82, v86, v88
	v_pk_mul_f32 v[82:83], v[88:89], v[82:83] op_sel:[1,0]
	v_pk_mul_f32 v[80:81], v[88:89], v[80:81] op_sel:[1,0]
	v_pk_mul_f32 v[72:73], v[88:89], v[72:73] op_sel:[1,0]
	v_pk_fma_f32 v[80:81], v[140:141], v[80:81], v[136:137]
	v_pk_fma_f32 v[82:83], v[142:143], v[82:83], v[138:139]
	v_pk_fma_f32 v[72:73], v[128:129], v[72:73], v[132:133]
	v_pk_fma_f32 v[74:75], v[130:131], v[74:75], v[134:135]
	v_cndmask_b32_e32 v83, v164, v83, vcc
	v_cndmask_b32_e32 v82, v164, v82, vcc
	v_cndmask_b32_e32 v81, v164, v81, vcc
	v_cndmask_b32_e32 v80, v164, v80, vcc
	v_cndmask_b32_e32 v75, v164, v75, vcc
	v_cndmask_b32_e32 v74, v164, v74, vcc
	v_cndmask_b32_e32 v73, v164, v73, vcc
	v_cndmask_b32_e32 v72, v164, v72, vcc
	global_store_dwordx4 v[90:91], v[80:83], off offset:512
	global_store_dwordx4 v[90:91], v[72:75], off offset:576
	ds_read_b64 v[80:81], v165 offset:8576
	s_waitcnt lgkmcnt(0)
	v_sub_f32_e32 v69, v69, v80
	v_add_u32_e32 v72, 48, v162
	v_ashrrev_i32_e32 v73, 31, v72
	v_lshlrev_b64 v[82:83], 12, v[72:73]
	v_sub_f32_e32 v73, v97, v80
	v_sub_f32_e32 v72, v96, v80
	v_sub_f32_e32 v75, v99, v80
	v_sub_f32_e32 v74, v98, v80
	v_pk_mul_f32 v[74:75], v[80:81], v[74:75] op_sel:[1,0]
	v_pk_mul_f32 v[72:73], v[80:81], v[72:73] op_sel:[1,0]
	v_pk_fma_f32 v[74:75], v[158:159], v[74:75], v[154:155]
	v_pk_fma_f32 v[72:73], v[156:157], v[72:73], v[152:153]
	v_lshl_add_u64 v[82:83], s[14:15], 0, v[82:83]
	v_cndmask_b32_e32 v75, v164, v75, vcc
	v_cndmask_b32_e32 v74, v164, v74, vcc
	v_cndmask_b32_e32 v73, v164, v73, vcc
	v_cndmask_b32_e32 v72, v164, v72, vcc
	v_lshl_add_u64 v[82:83], v[82:83], 0, v[160:161]
	global_store_dwordx4 v[82:83], v[72:75], off
	v_sub_f32_e32 v68, v68, v80
	v_sub_f32_e32 v71, v71, v80
	v_sub_f32_e32 v73, v77, v80
	v_sub_f32_e32 v72, v76, v80
	v_sub_f32_e32 v75, v79, v80
	v_sub_f32_e32 v74, v78, v80
	v_sub_f32_e32 v70, v70, v80
	v_sub_f32_e32 v65, v65, v80
	v_sub_f32_e32 v64, v64, v80
	v_sub_f32_e32 v67, v67, v80
	v_sub_f32_e32 v66, v66, v80
	v_pk_mul_f32 v[74:75], v[80:81], v[74:75] op_sel:[1,0]
	v_pk_mul_f32 v[72:73], v[80:81], v[72:73] op_sel:[1,0]
	v_pk_mul_f32 v[70:71], v[80:81], v[70:71] op_sel:[1,0]
	v_pk_mul_f32 v[68:69], v[80:81], v[68:69] op_sel:[1,0]
	v_pk_mul_f32 v[66:67], v[80:81], v[66:67] op_sel:[1,0]
	v_pk_mul_f32 v[64:65], v[80:81], v[64:65] op_sel:[1,0]
	v_pk_fma_f32 v[72:73], v[144:145], v[72:73], v[148:149]
	v_pk_fma_f32 v[74:75], v[146:147], v[74:75], v[150:151]
	v_pk_fma_f32 v[68:69], v[140:141], v[68:69], v[136:137]
	v_pk_fma_f32 v[70:71], v[142:143], v[70:71], v[138:139]
	v_pk_fma_f32 v[64:65], v[128:129], v[64:65], v[132:133]
	v_pk_fma_f32 v[66:67], v[130:131], v[66:67], v[134:135]
	v_cndmask_b32_e32 v75, v164, v75, vcc
	v_cndmask_b32_e32 v74, v164, v74, vcc
	v_cndmask_b32_e32 v73, v164, v73, vcc
	v_cndmask_b32_e32 v72, v164, v72, vcc
	v_cndmask_b32_e32 v71, v164, v71, vcc
	v_cndmask_b32_e32 v70, v164, v70, vcc
	v_cndmask_b32_e32 v69, v164, v69, vcc
	v_cndmask_b32_e32 v68, v164, v68, vcc
	v_cndmask_b32_e32 v67, v164, v67, vcc
	v_cndmask_b32_e32 v66, v164, v66, vcc
	v_cndmask_b32_e32 v65, v164, v65, vcc
	v_cndmask_b32_e32 v64, v164, v64, vcc
	global_store_dwordx4 v[82:83], v[72:75], off offset:64
	global_store_dwordx4 v[82:83], v[68:71], off offset:512
	global_store_dwordx4 v[82:83], v[64:67], off offset:576
	ds_read_b64 v[64:65], v165 offset:9216
	s_waitcnt lgkmcnt(0)
	v_sub_f32_e32 v61, v61, v64
	v_add_u32_e32 v66, 0x80, v162
	v_ashrrev_i32_e32 v67, 31, v66
	v_sub_f32_e32 v60, v60, v64
	v_sub_f32_e32 v63, v63, v64
	v_sub_f32_e32 v62, v62, v64
	v_sub_f32_e32 v57, v57, v64
	v_sub_f32_e32 v56, v56, v64
	v_sub_f32_e32 v59, v59, v64
	v_sub_f32_e32 v58, v58, v64
	v_sub_f32_e32 v53, v53, v64
	v_sub_f32_e32 v52, v52, v64
	v_sub_f32_e32 v55, v55, v64
	v_sub_f32_e32 v54, v54, v64
	v_sub_f32_e32 v49, v49, v64
	v_sub_f32_e32 v48, v48, v64
	v_sub_f32_e32 v51, v51, v64
	v_sub_f32_e32 v50, v50, v64
	v_lshlrev_b64 v[66:67], 12, v[66:67]
	v_pk_mul_f32 v[62:63], v[64:65], v[62:63] op_sel:[1,0]
	v_pk_mul_f32 v[60:61], v[64:65], v[60:61] op_sel:[1,0]
	v_pk_mul_f32 v[58:59], v[64:65], v[58:59] op_sel:[1,0]
	v_pk_mul_f32 v[56:57], v[64:65], v[56:57] op_sel:[1,0]
	v_pk_mul_f32 v[54:55], v[64:65], v[54:55] op_sel:[1,0]
	v_pk_mul_f32 v[52:53], v[64:65], v[52:53] op_sel:[1,0]
	v_pk_mul_f32 v[50:51], v[64:65], v[50:51] op_sel:[1,0]
	v_pk_mul_f32 v[48:49], v[64:65], v[48:49] op_sel:[1,0]
	v_pk_fma_f32 v[60:61], v[156:157], v[60:61], v[152:153]
	v_pk_fma_f32 v[62:63], v[158:159], v[62:63], v[154:155]
	v_lshl_add_u64 v[66:67], s[14:15], 0, v[66:67]
	v_pk_fma_f32 v[56:57], v[144:145], v[56:57], v[148:149]
	v_pk_fma_f32 v[58:59], v[146:147], v[58:59], v[150:151]
	v_pk_fma_f32 v[52:53], v[140:141], v[52:53], v[136:137]
	v_pk_fma_f32 v[54:55], v[142:143], v[54:55], v[138:139]
	v_pk_fma_f32 v[48:49], v[128:129], v[48:49], v[132:133]
	v_pk_fma_f32 v[50:51], v[130:131], v[50:51], v[134:135]
	v_cndmask_b32_e32 v63, v164, v63, vcc
	v_cndmask_b32_e32 v62, v164, v62, vcc
	v_cndmask_b32_e32 v61, v164, v61, vcc
	v_cndmask_b32_e32 v60, v164, v60, vcc
	v_lshl_add_u64 v[66:67], v[66:67], 0, v[160:161]
	v_cndmask_b32_e32 v59, v164, v59, vcc
	v_cndmask_b32_e32 v58, v164, v58, vcc
	v_cndmask_b32_e32 v57, v164, v57, vcc
	v_cndmask_b32_e32 v56, v164, v56, vcc
	v_cndmask_b32_e32 v55, v164, v55, vcc
	v_cndmask_b32_e32 v54, v164, v54, vcc
	v_cndmask_b32_e32 v53, v164, v53, vcc
	v_cndmask_b32_e32 v52, v164, v52, vcc
	v_cndmask_b32_e32 v51, v164, v51, vcc
	v_cndmask_b32_e32 v50, v164, v50, vcc
	v_cndmask_b32_e32 v49, v164, v49, vcc
	v_cndmask_b32_e32 v48, v164, v48, vcc
	global_store_dwordx4 v[66:67], v[60:63], off
	global_store_dwordx4 v[66:67], v[56:59], off offset:64
	global_store_dwordx4 v[66:67], v[52:55], off offset:512
	global_store_dwordx4 v[66:67], v[48:51], off offset:576
	ds_read_b64 v[48:49], v165 offset:9344
	s_waitcnt lgkmcnt(0)
	v_sub_f32_e32 v45, v45, v48
	v_add_u32_e32 v50, 0x90, v162
	v_ashrrev_i32_e32 v51, 31, v50
	v_sub_f32_e32 v44, v44, v48
	v_sub_f32_e32 v47, v47, v48
	v_sub_f32_e32 v46, v46, v48
	v_sub_f32_e32 v41, v41, v48
	v_sub_f32_e32 v40, v40, v48
	v_sub_f32_e32 v43, v43, v48
	v_sub_f32_e32 v42, v42, v48
	v_sub_f32_e32 v37, v37, v48
	v_sub_f32_e32 v36, v36, v48
	v_sub_f32_e32 v39, v39, v48
	v_sub_f32_e32 v38, v38, v48
	v_sub_f32_e32 v33, v33, v48
	v_sub_f32_e32 v32, v32, v48
	v_sub_f32_e32 v35, v35, v48
	v_sub_f32_e32 v34, v34, v48
	v_lshlrev_b64 v[50:51], 12, v[50:51]
	v_pk_mul_f32 v[46:47], v[48:49], v[46:47] op_sel:[1,0]
	v_pk_mul_f32 v[44:45], v[48:49], v[44:45] op_sel:[1,0]
	v_pk_mul_f32 v[42:43], v[48:49], v[42:43] op_sel:[1,0]
	v_pk_mul_f32 v[40:41], v[48:49], v[40:41] op_sel:[1,0]
	v_pk_mul_f32 v[38:39], v[48:49], v[38:39] op_sel:[1,0]
	v_pk_mul_f32 v[36:37], v[48:49], v[36:37] op_sel:[1,0]
	v_pk_mul_f32 v[34:35], v[48:49], v[34:35] op_sel:[1,0]
	v_pk_mul_f32 v[32:33], v[48:49], v[32:33] op_sel:[1,0]
	v_pk_fma_f32 v[44:45], v[156:157], v[44:45], v[152:153]
	v_pk_fma_f32 v[46:47], v[158:159], v[46:47], v[154:155]
	v_lshl_add_u64 v[50:51], s[14:15], 0, v[50:51]
	v_pk_fma_f32 v[40:41], v[144:145], v[40:41], v[148:149]
	v_pk_fma_f32 v[42:43], v[146:147], v[42:43], v[150:151]
	v_pk_fma_f32 v[36:37], v[140:141], v[36:37], v[136:137]
	v_pk_fma_f32 v[38:39], v[142:143], v[38:39], v[138:139]
	v_pk_fma_f32 v[32:33], v[128:129], v[32:33], v[132:133]
	v_pk_fma_f32 v[34:35], v[130:131], v[34:35], v[134:135]
	v_cndmask_b32_e32 v47, v164, v47, vcc
	v_cndmask_b32_e32 v46, v164, v46, vcc
	v_cndmask_b32_e32 v45, v164, v45, vcc
	v_cndmask_b32_e32 v44, v164, v44, vcc
	v_lshl_add_u64 v[50:51], v[50:51], 0, v[160:161]
	v_cndmask_b32_e32 v43, v164, v43, vcc
	v_cndmask_b32_e32 v42, v164, v42, vcc
	v_cndmask_b32_e32 v41, v164, v41, vcc
	v_cndmask_b32_e32 v40, v164, v40, vcc
	v_cndmask_b32_e32 v39, v164, v39, vcc
	v_cndmask_b32_e32 v38, v164, v38, vcc
	v_cndmask_b32_e32 v37, v164, v37, vcc
	v_cndmask_b32_e32 v36, v164, v36, vcc
	v_cndmask_b32_e32 v35, v164, v35, vcc
	v_cndmask_b32_e32 v34, v164, v34, vcc
	v_cndmask_b32_e32 v33, v164, v33, vcc
	v_cndmask_b32_e32 v32, v164, v32, vcc
	global_store_dwordx4 v[50:51], v[44:47], off
	global_store_dwordx4 v[50:51], v[40:43], off offset:64
	global_store_dwordx4 v[50:51], v[36:39], off offset:512
	global_store_dwordx4 v[50:51], v[32:35], off offset:576
	ds_read_b64 v[32:33], v165 offset:9472
	s_waitcnt lgkmcnt(0)
	v_sub_f32_e32 v29, v29, v32
	v_add_u32_e32 v34, 0xa0, v162
	v_ashrrev_i32_e32 v35, 31, v34
	v_sub_f32_e32 v28, v28, v32
	v_sub_f32_e32 v31, v31, v32
	v_sub_f32_e32 v30, v30, v32
	v_sub_f32_e32 v25, v25, v32
	v_sub_f32_e32 v24, v24, v32
	v_sub_f32_e32 v27, v27, v32
	v_sub_f32_e32 v26, v26, v32
	v_sub_f32_e32 v21, v21, v32
	v_sub_f32_e32 v20, v20, v32
	v_sub_f32_e32 v23, v23, v32
	v_sub_f32_e32 v22, v22, v32
	v_sub_f32_e32 v17, v17, v32
	v_sub_f32_e32 v16, v16, v32
	v_sub_f32_e32 v19, v19, v32
	v_sub_f32_e32 v18, v18, v32
	v_lshlrev_b64 v[34:35], 12, v[34:35]
	v_pk_mul_f32 v[30:31], v[32:33], v[30:31] op_sel:[1,0]
	v_pk_mul_f32 v[28:29], v[32:33], v[28:29] op_sel:[1,0]
	v_pk_mul_f32 v[26:27], v[32:33], v[26:27] op_sel:[1,0]
	v_pk_mul_f32 v[24:25], v[32:33], v[24:25] op_sel:[1,0]
	v_pk_mul_f32 v[22:23], v[32:33], v[22:23] op_sel:[1,0]
	v_pk_mul_f32 v[20:21], v[32:33], v[20:21] op_sel:[1,0]
	v_pk_mul_f32 v[18:19], v[32:33], v[18:19] op_sel:[1,0]
	v_pk_mul_f32 v[16:17], v[32:33], v[16:17] op_sel:[1,0]
	v_pk_fma_f32 v[28:29], v[156:157], v[28:29], v[152:153]
	v_pk_fma_f32 v[30:31], v[158:159], v[30:31], v[154:155]
	v_lshl_add_u64 v[34:35], s[14:15], 0, v[34:35]
	v_pk_fma_f32 v[24:25], v[144:145], v[24:25], v[148:149]
	v_pk_fma_f32 v[26:27], v[146:147], v[26:27], v[150:151]
	v_pk_fma_f32 v[20:21], v[140:141], v[20:21], v[136:137]
	v_pk_fma_f32 v[22:23], v[142:143], v[22:23], v[138:139]
	v_pk_fma_f32 v[16:17], v[128:129], v[16:17], v[132:133]
	v_pk_fma_f32 v[18:19], v[130:131], v[18:19], v[134:135]
	v_cndmask_b32_e32 v31, v164, v31, vcc
	v_cndmask_b32_e32 v30, v164, v30, vcc
	v_cndmask_b32_e32 v29, v164, v29, vcc
	v_cndmask_b32_e32 v28, v164, v28, vcc
	v_lshl_add_u64 v[34:35], v[34:35], 0, v[160:161]
	v_cndmask_b32_e32 v27, v164, v27, vcc
	v_cndmask_b32_e32 v26, v164, v26, vcc
	v_cndmask_b32_e32 v25, v164, v25, vcc
	v_cndmask_b32_e32 v24, v164, v24, vcc
	v_cndmask_b32_e32 v23, v164, v23, vcc
	v_cndmask_b32_e32 v22, v164, v22, vcc
	v_cndmask_b32_e32 v21, v164, v21, vcc
	v_cndmask_b32_e32 v20, v164, v20, vcc
	v_cndmask_b32_e32 v19, v164, v19, vcc
	v_cndmask_b32_e32 v18, v164, v18, vcc
	v_cndmask_b32_e32 v17, v164, v17, vcc
	v_cndmask_b32_e32 v16, v164, v16, vcc
	global_store_dwordx4 v[34:35], v[28:31], off
	global_store_dwordx4 v[34:35], v[24:27], off offset:64
	global_store_dwordx4 v[34:35], v[20:23], off offset:512
	global_store_dwordx4 v[34:35], v[16:19], off offset:576
	ds_read_b64 v[16:17], v165 offset:9600
	s_waitcnt lgkmcnt(0)
	v_sub_f32_e32 v13, v13, v16
	v_add_u32_e32 v18, 0xb0, v162
	v_ashrrev_i32_e32 v19, 31, v18
	v_sub_f32_e32 v12, v12, v16
	v_sub_f32_e32 v15, v15, v16
	v_sub_f32_e32 v14, v14, v16
	v_sub_f32_e32 v9, v9, v16
	v_sub_f32_e32 v8, v8, v16
	v_sub_f32_e32 v11, v11, v16
	v_sub_f32_e32 v10, v10, v16
	v_sub_f32_e32 v5, v5, v16
	v_sub_f32_e32 v4, v4, v16
	v_sub_f32_e32 v7, v7, v16
	v_sub_f32_e32 v6, v6, v16
	v_sub_f32_e32 v1, v1, v16
	v_sub_f32_e32 v0, v0, v16
	v_sub_f32_e32 v3, v3, v16
	v_sub_f32_e32 v2, v2, v16
	v_lshlrev_b64 v[18:19], 12, v[18:19]
	v_pk_mul_f32 v[14:15], v[16:17], v[14:15] op_sel:[1,0]
	v_pk_mul_f32 v[12:13], v[16:17], v[12:13] op_sel:[1,0]
	v_pk_mul_f32 v[10:11], v[16:17], v[10:11] op_sel:[1,0]
	v_pk_mul_f32 v[8:9], v[16:17], v[8:9] op_sel:[1,0]
	v_pk_mul_f32 v[6:7], v[16:17], v[6:7] op_sel:[1,0]
	v_pk_mul_f32 v[4:5], v[16:17], v[4:5] op_sel:[1,0]
	v_pk_mul_f32 v[2:3], v[16:17], v[2:3] op_sel:[1,0]
	v_pk_mul_f32 v[0:1], v[16:17], v[0:1] op_sel:[1,0]
	v_pk_fma_f32 v[12:13], v[156:157], v[12:13], v[152:153]
	v_pk_fma_f32 v[14:15], v[158:159], v[14:15], v[154:155]
	v_lshl_add_u64 v[18:19], s[14:15], 0, v[18:19]
	v_pk_fma_f32 v[8:9], v[144:145], v[8:9], v[148:149]
	v_pk_fma_f32 v[10:11], v[146:147], v[10:11], v[150:151]
	v_pk_fma_f32 v[4:5], v[140:141], v[4:5], v[136:137]
	v_pk_fma_f32 v[6:7], v[142:143], v[6:7], v[138:139]
	v_pk_fma_f32 v[0:1], v[128:129], v[0:1], v[132:133]
	v_pk_fma_f32 v[2:3], v[130:131], v[2:3], v[134:135]
	v_cndmask_b32_e32 v15, v164, v15, vcc
	v_cndmask_b32_e32 v14, v164, v14, vcc
	v_cndmask_b32_e32 v13, v164, v13, vcc
	v_cndmask_b32_e32 v12, v164, v12, vcc
	v_lshl_add_u64 v[18:19], v[18:19], 0, v[160:161]
	v_cndmask_b32_e32 v11, v164, v11, vcc
	v_cndmask_b32_e32 v10, v164, v10, vcc
	v_cndmask_b32_e32 v9, v164, v9, vcc
	v_cndmask_b32_e32 v8, v164, v8, vcc
	v_cndmask_b32_e32 v7, v164, v7, vcc
	v_cndmask_b32_e32 v6, v164, v6, vcc
	v_cndmask_b32_e32 v5, v164, v5, vcc
	v_cndmask_b32_e32 v4, v164, v4, vcc
	v_cndmask_b32_e32 v3, v164, v3, vcc
	v_cndmask_b32_e32 v2, v164, v2, vcc
	v_cndmask_b32_e32 v1, v164, v1, vcc
	v_cndmask_b32_e32 v0, v164, v0, vcc
	global_store_dwordx4 v[18:19], v[12:15], off
	global_store_dwordx4 v[18:19], v[8:11], off offset:64
	global_store_dwordx4 v[18:19], v[4:7], off offset:512
	global_store_dwordx4 v[18:19], v[0:3], off offset:576

.LBB0_1141:
	s_cmp_gt_i32 s78, 12
	s_cselect_b64 s[0:1], -1, 0
	s_cmp_lt_i32 s79, 13
	s_cselect_b64 s[2:3], -1, 0
	s_or_b64 s[0:1], s[0:1], s[2:3]
	s_or_b64 s[0:1], s[0:1], s[92:93]
	s_and_b64 vcc, exec, s[0:1]
	s_cbranch_vccnz .LBB0_1145
	s_cmpk_gt_i32 s84, 0x3fff
	s_cbranch_scc1 .LBB0_1145
	v_mbcnt_lo_u32_b32 v6, -1, 0
	v_mbcnt_hi_u32_b32 v11, -1, v6
	v_and_b32_e32 v6, 64, v11
	v_add_u32_e32 v12, 64, v6
	v_xor_b32_e32 v6, 1, v11
	v_cmp_lt_i32_e32 vcc, v6, v12
	v_xor_b32_e32 v7, 2, v11
	s_nop 0
	v_cndmask_b32_e32 v6, v11, v6, vcc
	v_cmp_lt_i32_e32 vcc, v7, v12
	v_xor_b32_e32 v8, 4, v11
	s_nop 0
	v_cndmask_b32_e32 v7, v11, v7, vcc
	v_cmp_lt_i32_e32 vcc, v8, v12
	v_xor_b32_e32 v9, 8, v11
	s_ashr_i32 s85, s84, 31
	v_readlane_b32 s14, v246, 34
	v_cndmask_b32_e32 v8, v11, v8, vcc
	v_cmp_lt_i32_e32 vcc, v9, v12
	v_xor_b32_e32 v10, 16, v11
	s_lshl_b64 s[0:1], s[84:85], 12
	v_readlane_b32 s15, v246, 35
	v_cndmask_b32_e32 v9, v11, v9, vcc
	v_cmp_lt_i32_e32 vcc, v10, v12
	v_xor_b32_e32 v13, 32, v11
	s_add_u32 s0, s14, s0
	v_lshlrev_b32_e32 v4, 4, v170
	v_mov_b32_e32 v5, 0
	v_readlane_b32 s10, v246, 30
	v_readlane_b32 s11, v246, 31
	v_readlane_b32 s12, v246, 32
	v_readlane_b32 s13, v246, 33
	v_cndmask_b32_e32 v10, v11, v10, vcc
	v_cmp_lt_i32_e32 vcc, v13, v12
	s_addc_u32 s1, s15, s1
	v_lshl_add_u64 v[0:1], s[10:11], 0, v[4:5]
	v_lshl_add_u64 v[2:3], s[12:13], 0, v[4:5]
	v_cndmask_b32_e32 v11, v11, v13, vcc
	v_lshl_add_u64 v[4:5], s[0:1], 0, v[4:5]
	s_mov_b64 s[0:1], 0x800
	s_ashr_i32 s87, s86, 31
	v_lshlrev_b32_e32 v6, 2, v6
	v_lshlrev_b32_e32 v7, 2, v7
	v_lshlrev_b32_e32 v8, 2, v8
	v_lshlrev_b32_e32 v9, 2, v9
	v_lshlrev_b32_e32 v10, 2, v10
	v_lshlrev_b32_e32 v11, 2, v11
	v_lshl_add_u64 v[4:5], v[4:5], 0, s[0:1]
	s_lshl_b64 s[0:1], s[86:87], 12
	v_mov_b32_e32 v12, 0x3727c5ac
